# prep S3: batched raw-row prefetch + software-pipelined forward substitution (same math order)
# speedup vs baseline: 1.0170x; 1.0170x over previous
.LBB0_167:
	s_waitcnt lgkmcnt(0)
	s_barrier
	v_mov_b32_e32 v49, v166
	s_movk_i32 s0, 0xff
	s_nop 0
	v_cmp_lt_i32_e32 vcc, s0, v49
	s_and_saveexec_b64 s[0:1], vcc
	s_xor_b64 s[20:21], exec, s[0:1]
	s_cbranch_execz .LBB0_191
	v_readfirstlane_b32 s26, v46
	s_add_i32 s26, s26, s63
	s_cmpk_lt_i32 s26, 0x1000
	s_cbranch_scc0 .Lrl_early_done
	s_and_b32 s27, s26, 63
	s_bfe_u32 s28, s26, 0x30006
	s_lshl_b32 s28, s28, 8
	s_lshr_b32 s29, s26, 9
	s_lshl_b32 s30, s29, 12
	s_lshl_b32 s31, s27, 6
	s_add_i32 s30, s30, s31
	s_add_i32 s30, s30, -3
	s_lshl_b32 s34, s30, 13
	s_ashr_i32 s35, s30, 31
	s_add_u32 s34, s34, s74
	s_addc_u32 s35, s35, s75
	s_add_u32 s34, s34, s28
	s_addc_u32 s35, s35, 0
	s_lshl_b32 s29, s29, 6
	s_add_i32 s29, s29, s27
	s_mul_i32 s29, s29, 0x4800
	s_add_i32 s29, s29, s28
	s_add_u32 s30, s82, s29
	s_addc_u32 s31, s83, 0
	s_mov_b32 s26, 0xaaaaaaab
	v_add_u32_e32 v202, 0xffffff00, v49
	v_mul_hi_u32 v204, v202, s26
	v_lshrrev_b32_e32 v204, 5, v204
	v_mul_u32_u24_e32 v220, 48, v204
	v_sub_u32_e32 v220, v202, v220
	v_lshrrev_b32_e32 v221, 4, v220
	v_mul_u32_u24_e32 v221, 0x700, v221
	v_lshl_add_u32 v221, v220, 4, v221
	v_mov_b32_e32 v190, 0
	v_mov_b32_e32 v191, 0
	v_mov_b32_e32 v192, 0
	v_mov_b32_e32 v193, 0
	s_mov_b64 s[28:29], exec
	v_cmp_gt_u32_e32 vcc, 3, v204
	s_and_b64 exec, s[28:29], vcc
	s_cbranch_execz .Lrl_e_nohalo
	s_cmp_eq_u32 s27, 0
	s_cbranch_scc1 .Lrl_e_nohalo
	v_mul_u32_u24_e32 v226, 0x1800, v204
	v_add_u32_e32 v226, v226, v221
	global_load_dwordx4 v[190:193], v226, s[30:31]
.Lrl_e_nohalo:
	s_andn2_b64 exec, s[28:29], vcc
	s_cbranch_execz .Lrl_e_noproj
	v_lshl_add_u32 v226, v204, 13, v221
	global_load_dwordx4 v[190:193], v226, s[34:35]
.Lrl_e_noproj:
	s_mov_b64 exec, s[28:29]
	v_add_u32_e32 v203, 256, v202
	v_mul_hi_u32 v204, v203, s26
	v_lshrrev_b32_e32 v204, 5, v204
	v_mul_u32_u24_e32 v220, 48, v204
	v_sub_u32_e32 v220, v203, v220
	v_lshrrev_b32_e32 v221, 4, v220
	v_mul_u32_u24_e32 v221, 0x700, v221
	v_lshl_add_u32 v221, v220, 4, v221
	v_lshl_add_u32 v221, v204, 13, v221
	global_load_dwordx4 v[194:197], v221, s[34:35]
	v_add_u32_e32 v203, 512, v202
	v_mul_hi_u32 v204, v203, s26
	v_lshrrev_b32_e32 v204, 5, v204
	v_mul_u32_u24_e32 v220, 48, v204
	v_sub_u32_e32 v220, v203, v220
	v_lshrrev_b32_e32 v221, 4, v220
	v_mul_u32_u24_e32 v221, 0x700, v221
	v_lshl_add_u32 v221, v220, 4, v221
	v_lshl_add_u32 v221, v204, 13, v221
	global_load_dwordx4 v[198:201], v221, s[34:35]
	v_add_u32_e32 v203, 768, v202
	v_mul_hi_u32 v204, v203, s26
	v_lshrrev_b32_e32 v204, 5, v204
	v_mul_u32_u24_e32 v220, 48, v204
	v_sub_u32_e32 v220, v203, v220
	v_lshrrev_b32_e32 v221, 4, v220
	v_mul_u32_u24_e32 v221, 0x700, v221
	v_lshl_add_u32 v221, v220, 4, v221
	v_lshl_add_u32 v221, v204, 13, v221
	global_load_dwordx4 v[206:209], v221, s[34:35]
	v_add_u32_e32 v203, 1024, v202
	v_mul_hi_u32 v204, v203, s26
	v_lshrrev_b32_e32 v204, 5, v204
	v_mul_u32_u24_e32 v220, 48, v204
	v_sub_u32_e32 v220, v203, v220
	v_lshrrev_b32_e32 v221, 4, v220
	v_mul_u32_u24_e32 v221, 0x700, v221
	v_lshl_add_u32 v221, v220, 4, v221
	v_lshl_add_u32 v221, v204, 13, v221
	global_load_dwordx4 v[210:213], v221, s[34:35]
	v_add_u32_e32 v203, 1280, v202
	v_mul_hi_u32 v204, v203, s26
	v_lshrrev_b32_e32 v204, 5, v204
	v_mul_u32_u24_e32 v220, 48, v204
	v_sub_u32_e32 v220, v203, v220
	v_lshrrev_b32_e32 v221, 4, v220
	v_mul_u32_u24_e32 v221, 0x700, v221
	v_lshl_add_u32 v221, v220, 4, v221
	v_lshl_add_u32 v221, v204, 13, v221
	global_load_dwordx4 v[214:217], v221, s[34:35]
	v_add_u32_e32 v203, 1536, v202
	v_mul_hi_u32 v204, v203, s26
	v_lshrrev_b32_e32 v204, 5, v204
	v_mul_u32_u24_e32 v220, 48, v204
	v_sub_u32_e32 v220, v203, v220
	v_lshrrev_b32_e32 v221, 4, v220
	v_mul_u32_u24_e32 v221, 0x700, v221
	v_lshl_add_u32 v221, v220, 4, v221
	v_lshl_add_u32 v221, v204, 13, v221
	global_load_dwordx4 v[238:241], v221, s[34:35]
	v_add_u32_e32 v203, 1792, v202
	v_mul_hi_u32 v204, v203, s26
	v_lshrrev_b32_e32 v204, 5, v204
	v_mul_u32_u24_e32 v220, 48, v204
	v_sub_u32_e32 v220, v203, v220
	v_lshrrev_b32_e32 v221, 4, v220
	v_mul_u32_u24_e32 v221, 0x700, v221
	v_lshl_add_u32 v221, v220, 4, v221
	v_lshl_add_u32 v221, v204, 13, v221
	global_load_dwordx4 v[242:245], v221, s[34:35]
	v_add_u32_e32 v203, 2048, v202
	v_mul_hi_u32 v204, v203, s26
	v_lshrrev_b32_e32 v204, 5, v204
	v_mul_u32_u24_e32 v220, 48, v204
	v_sub_u32_e32 v220, v203, v220
	v_lshrrev_b32_e32 v221, 4, v220
	v_mul_u32_u24_e32 v221, 0x700, v221
	v_lshl_add_u32 v221, v220, 4, v221
	v_lshl_add_u32 v221, v204, 13, v221
	global_load_dwordx4 v[246:249], v221, s[34:35]
.Lrl_early_done:
	s_movk_i32 s0, 0x180
	v_cmp_gt_u32_e32 vcc, s0, v49
	v_add_u32_e32 v6, 0xffffff00, v49
	s_and_saveexec_b64 s[0:1], vcc
	s_cbranch_execz .LBB0_172
	v_readlane_b32 s18, v253, 38
	v_lshlrev_b64 v[2:3], 14, v[46:47]
	v_cmp_eq_u32_e32 vcc, 0, v6
	v_mov_b32_e32 v0, s18
	v_readlane_b32 s18, v254, 21
	v_readlane_b32 s19, v254, 22
	ds_read_b32 v7, v0
	s_nop 0
	v_lshl_add_u64 v[2:3], s[18:19], 0, v[2:3]
	v_readlane_b32 s18, v253, 31
	s_nop 1
	v_mov_b32_e32 v4, s18
	ds_read_b128 v[8:11], v4
	v_lshlrev_b32_e32 v0, 7, v6
	v_lshl_add_u64 v[2:3], v[2:3], 0, v[0:1]
	v_lshl_add_u32 v0, v6, 1, 0
	v_add_u32_e32 v0, 0x10d00, v0
	s_waitcnt lgkmcnt(0)
	v_sub_f32_e32 v4, v7, v8
	v_sub_f32_e32 v5, v7, v9
	ds_read_u16 v8, v0
	ds_read_u16 v9, v0 offset:272
	v_mul_f32_e32 v4, 0x3fb8aa3b, v4
	v_mul_f32_e32 v5, 0x3fb8aa3b, v5
	v_exp_f32_e32 v4, v4
	v_exp_f32_e32 v5, v5
	s_waitcnt lgkmcnt(0)
	v_lshlrev_b32_e32 v9, 16, v9
	v_lshlrev_b32_e32 v8, 16, v8
	v_readlane_b32 s18, v253, 39
	v_pk_mul_f32 v[4:5], v[4:5], v[8:9]
	v_sub_f32_e32 v8, v7, v10
	v_sub_f32_e32 v9, v7, v11
	ds_read_u16 v10, v0 offset:544
	ds_read_u16 v11, v0 offset:816
	v_mul_f32_e32 v8, 0x3fb8aa3b, v8
	v_mul_f32_e32 v9, 0x3fb8aa3b, v9
	v_exp_f32_e32 v8, v8
	v_exp_f32_e32 v9, v9
	s_waitcnt lgkmcnt(0)
	v_lshlrev_b32_e32 v11, 16, v11
	v_lshlrev_b32_e32 v10, 16, v10
	v_pk_mul_f32 v[12:13], v[8:9], v[10:11]
	v_mov_b32_e32 v8, s18
	ds_read_b128 v[8:11], v8
	ds_read_u16 v14, v0 offset:1088
	ds_read_u16 v15, v0 offset:1360
	v_readlane_b32 s18, v253, 40
	s_waitcnt lgkmcnt(0)
	v_sub_f32_e32 v8, v7, v8
	v_sub_f32_e32 v9, v7, v9
	v_mul_f32_e32 v8, 0x3fb8aa3b, v8
	v_mul_f32_e32 v9, 0x3fb8aa3b, v9
	v_exp_f32_e32 v8, v8
	v_exp_f32_e32 v9, v9
	v_lshlrev_b32_e32 v15, 16, v15
	v_lshlrev_b32_e32 v14, 16, v14
	v_pk_mul_f32 v[14:15], v[8:9], v[14:15]
	v_sub_f32_e32 v8, v7, v10
	v_sub_f32_e32 v9, v7, v11
	ds_read_u16 v10, v0 offset:1632
	ds_read_u16 v11, v0 offset:1904
	v_mul_f32_e32 v8, 0x3fb8aa3b, v8
	v_mul_f32_e32 v9, 0x3fb8aa3b, v9
	v_exp_f32_e32 v8, v8
	v_exp_f32_e32 v9, v9
	s_waitcnt lgkmcnt(0)
	v_lshlrev_b32_e32 v11, 16, v11
	v_lshlrev_b32_e32 v10, 16, v10
	v_pk_mul_f32 v[16:17], v[8:9], v[10:11]
	v_cvt_pk_bf16_f32 v8, v4, v5
	v_cvt_pk_bf16_f32 v9, v12, v13
	v_cvt_pk_bf16_f32 v10, v14, v15
	v_cvt_pk_bf16_f32 v11, v16, v17
	flat_store_dwordx4 v[2:3], v[8:11]
	v_mov_b32_e32 v4, s18
	ds_read_b128 v[8:11], v4
	v_readlane_b32 s18, v253, 41
	s_waitcnt lgkmcnt(0)
	v_sub_f32_e32 v4, v7, v8
	v_sub_f32_e32 v5, v7, v9
	ds_read_u16 v8, v0 offset:2176
	ds_read_u16 v9, v0 offset:2448
	v_mul_f32_e32 v4, 0x3fb8aa3b, v4
	v_mul_f32_e32 v5, 0x3fb8aa3b, v5
	v_exp_f32_e32 v4, v4
	v_exp_f32_e32 v5, v5
	s_waitcnt lgkmcnt(0)
	v_lshlrev_b32_e32 v9, 16, v9
	v_lshlrev_b32_e32 v8, 16, v8
	v_pk_mul_f32 v[4:5], v[4:5], v[8:9]
	v_sub_f32_e32 v8, v7, v10
	v_sub_f32_e32 v9, v7, v11
	ds_read_u16 v10, v0 offset:2720
	ds_read_u16 v11, v0 offset:2992
	v_mul_f32_e32 v8, 0x3fb8aa3b, v8
	v_mul_f32_e32 v9, 0x3fb8aa3b, v9
	v_exp_f32_e32 v8, v8
	v_exp_f32_e32 v9, v9
	s_waitcnt lgkmcnt(0)
	v_lshlrev_b32_e32 v11, 16, v11
	v_lshlrev_b32_e32 v10, 16, v10
	v_pk_mul_f32 v[8:9], v[8:9], v[10:11]
	v_mov_b32_e32 v10, s18
	ds_read_b128 v[10:13], v10
	ds_read_u16 v14, v0 offset:3264
	ds_read_u16 v15, v0 offset:3536
	v_readlane_b32 s18, v253, 42
	s_waitcnt lgkmcnt(0)
	v_sub_f32_e32 v10, v7, v10
	v_sub_f32_e32 v11, v7, v11
	v_mul_f32_e32 v10, 0x3fb8aa3b, v10
	v_mul_f32_e32 v11, 0x3fb8aa3b, v11
	v_exp_f32_e32 v10, v10
	v_exp_f32_e32 v11, v11
	v_lshlrev_b32_e32 v15, 16, v15
	v_lshlrev_b32_e32 v14, 16, v14
	v_pk_mul_f32 v[14:15], v[10:11], v[14:15]
	v_sub_f32_e32 v10, v7, v12
	v_sub_f32_e32 v11, v7, v13
	ds_read_u16 v12, v0 offset:3808
	ds_read_u16 v13, v0 offset:4080
	v_mul_f32_e32 v10, 0x3fb8aa3b, v10
	v_mul_f32_e32 v11, 0x3fb8aa3b, v11
	v_exp_f32_e32 v10, v10
	v_exp_f32_e32 v11, v11
	s_waitcnt lgkmcnt(0)
	v_lshlrev_b32_e32 v13, 16, v13
	v_lshlrev_b32_e32 v12, 16, v12
	v_pk_mul_f32 v[16:17], v[10:11], v[12:13]
	v_cvt_pk_bf16_f32 v10, v4, v5
	v_cvt_pk_bf16_f32 v11, v8, v9
	v_cvt_pk_bf16_f32 v12, v14, v15
	v_cvt_pk_bf16_f32 v13, v16, v17
	flat_store_dwordx4 v[2:3], v[10:13] offset:16
	v_mov_b32_e32 v4, s18
	ds_read_b128 v[8:11], v4
	v_readlane_b32 s18, v253, 43
	s_waitcnt lgkmcnt(0)
	v_sub_f32_e32 v4, v7, v8
	v_sub_f32_e32 v5, v7, v9
	ds_read_u16 v8, v0 offset:4352
	ds_read_u16 v9, v0 offset:4624
	v_mul_f32_e32 v4, 0x3fb8aa3b, v4
	v_mul_f32_e32 v5, 0x3fb8aa3b, v5
	v_exp_f32_e32 v4, v4
	v_exp_f32_e32 v5, v5
	s_waitcnt lgkmcnt(0)
	v_lshlrev_b32_e32 v9, 16, v9
	v_lshlrev_b32_e32 v8, 16, v8
	v_pk_mul_f32 v[4:5], v[4:5], v[8:9]
	v_sub_f32_e32 v8, v7, v10
	v_sub_f32_e32 v9, v7, v11
	ds_read_u16 v10, v0 offset:4896
	ds_read_u16 v11, v0 offset:5168
	v_mul_f32_e32 v8, 0x3fb8aa3b, v8
	v_mul_f32_e32 v9, 0x3fb8aa3b, v9
	v_exp_f32_e32 v8, v8
	v_exp_f32_e32 v9, v9
	s_waitcnt lgkmcnt(0)
	v_lshlrev_b32_e32 v11, 16, v11
	v_lshlrev_b32_e32 v10, 16, v10
	v_pk_mul_f32 v[8:9], v[8:9], v[10:11]
	v_mov_b32_e32 v10, s18
	ds_read_b128 v[10:13], v10
	ds_read_u16 v14, v0 offset:5440
	ds_read_u16 v15, v0 offset:5712
	v_readlane_b32 s18, v253, 44
	s_waitcnt lgkmcnt(0)
	v_sub_f32_e32 v10, v7, v10
	v_sub_f32_e32 v11, v7, v11
	v_mul_f32_e32 v10, 0x3fb8aa3b, v10
	v_mul_f32_e32 v11, 0x3fb8aa3b, v11
	v_exp_f32_e32 v10, v10
	v_exp_f32_e32 v11, v11
	v_lshlrev_b32_e32 v15, 16, v15
	v_lshlrev_b32_e32 v14, 16, v14
	v_pk_mul_f32 v[14:15], v[10:11], v[14:15]
	v_sub_f32_e32 v10, v7, v12
	v_sub_f32_e32 v11, v7, v13
	ds_read_u16 v12, v0 offset:5984
	ds_read_u16 v13, v0 offset:6256
	v_mul_f32_e32 v10, 0x3fb8aa3b, v10
	v_mul_f32_e32 v11, 0x3fb8aa3b, v11
	v_exp_f32_e32 v10, v10
	v_exp_f32_e32 v11, v11
	s_waitcnt lgkmcnt(0)
	v_lshlrev_b32_e32 v13, 16, v13
	v_lshlrev_b32_e32 v12, 16, v12
	v_pk_mul_f32 v[16:17], v[10:11], v[12:13]
	v_cvt_pk_bf16_f32 v10, v4, v5
	v_cvt_pk_bf16_f32 v11, v8, v9
	v_cvt_pk_bf16_f32 v12, v14, v15
	v_cvt_pk_bf16_f32 v13, v16, v17
	flat_store_dwordx4 v[2:3], v[10:13] offset:32
	v_mov_b32_e32 v4, s18
	ds_read_b128 v[8:11], v4
	v_readlane_b32 s18, v253, 45
	s_waitcnt lgkmcnt(0)
	v_sub_f32_e32 v4, v7, v8
	v_sub_f32_e32 v5, v7, v9
	ds_read_u16 v8, v0 offset:6528
	ds_read_u16 v9, v0 offset:6800
	v_mul_f32_e32 v4, 0x3fb8aa3b, v4
	v_mul_f32_e32 v5, 0x3fb8aa3b, v5
	v_exp_f32_e32 v4, v4
	v_exp_f32_e32 v5, v5
	s_waitcnt lgkmcnt(0)
	v_lshlrev_b32_e32 v9, 16, v9
	v_lshlrev_b32_e32 v8, 16, v8
	v_pk_mul_f32 v[4:5], v[4:5], v[8:9]
	v_sub_f32_e32 v8, v7, v10
	v_sub_f32_e32 v9, v7, v11
	ds_read_u16 v10, v0 offset:7072
	ds_read_u16 v11, v0 offset:7344
	v_mul_f32_e32 v8, 0x3fb8aa3b, v8
	v_mul_f32_e32 v9, 0x3fb8aa3b, v9
	v_exp_f32_e32 v8, v8
	v_exp_f32_e32 v9, v9
	s_waitcnt lgkmcnt(0)
	v_lshlrev_b32_e32 v11, 16, v11
	v_lshlrev_b32_e32 v10, 16, v10
	v_pk_mul_f32 v[8:9], v[8:9], v[10:11]
	v_mov_b32_e32 v10, s18
	ds_read_b128 v[10:13], v10
	ds_read_u16 v14, v0 offset:7616
	ds_read_u16 v15, v0 offset:7888
	v_readlane_b32 s18, v253, 46
	s_waitcnt lgkmcnt(0)
	v_sub_f32_e32 v10, v7, v10
	v_sub_f32_e32 v11, v7, v11
	v_mul_f32_e32 v10, 0x3fb8aa3b, v10
	v_mul_f32_e32 v11, 0x3fb8aa3b, v11
	v_exp_f32_e32 v10, v10
	v_exp_f32_e32 v11, v11
	v_lshlrev_b32_e32 v15, 16, v15
	v_lshlrev_b32_e32 v14, 16, v14
	v_pk_mul_f32 v[14:15], v[10:11], v[14:15]
	v_sub_f32_e32 v10, v7, v12
	v_sub_f32_e32 v11, v7, v13
	ds_read_u16 v12, v0 offset:8160
	ds_read_u16 v13, v0 offset:8432
	v_mul_f32_e32 v10, 0x3fb8aa3b, v10
	v_mul_f32_e32 v11, 0x3fb8aa3b, v11
	v_exp_f32_e32 v10, v10
	v_exp_f32_e32 v11, v11
	s_waitcnt lgkmcnt(0)
	v_lshlrev_b32_e32 v13, 16, v13
	v_lshlrev_b32_e32 v12, 16, v12
	v_pk_mul_f32 v[16:17], v[10:11], v[12:13]
	v_cvt_pk_bf16_f32 v10, v4, v5
	v_cvt_pk_bf16_f32 v11, v8, v9
	v_cvt_pk_bf16_f32 v12, v14, v15
	v_cvt_pk_bf16_f32 v13, v16, v17
	flat_store_dwordx4 v[2:3], v[10:13] offset:48
	v_mov_b32_e32 v4, s18
	ds_read_b128 v[8:11], v4
	v_readlane_b32 s18, v253, 47
	s_waitcnt lgkmcnt(0)
	v_sub_f32_e32 v4, v7, v8
	v_sub_f32_e32 v5, v7, v9
	ds_read_u16 v8, v0 offset:8704
	ds_read_u16 v9, v0 offset:8976
	v_mul_f32_e32 v4, 0x3fb8aa3b, v4
	v_mul_f32_e32 v5, 0x3fb8aa3b, v5
	v_exp_f32_e32 v4, v4
	v_exp_f32_e32 v5, v5
	s_waitcnt lgkmcnt(0)
	v_lshlrev_b32_e32 v9, 16, v9
	v_lshlrev_b32_e32 v8, 16, v8
	v_pk_mul_f32 v[4:5], v[4:5], v[8:9]
	v_sub_f32_e32 v8, v7, v10
	v_sub_f32_e32 v9, v7, v11
	ds_read_u16 v10, v0 offset:9248
	ds_read_u16 v11, v0 offset:9520
	v_mul_f32_e32 v8, 0x3fb8aa3b, v8
	v_mul_f32_e32 v9, 0x3fb8aa3b, v9
	v_exp_f32_e32 v8, v8
	v_exp_f32_e32 v9, v9
	s_waitcnt lgkmcnt(0)
	v_lshlrev_b32_e32 v11, 16, v11
	v_lshlrev_b32_e32 v10, 16, v10
	v_pk_mul_f32 v[8:9], v[8:9], v[10:11]
	v_mov_b32_e32 v10, s18
	ds_read_b128 v[10:13], v10
	ds_read_u16 v14, v0 offset:9792
	ds_read_u16 v15, v0 offset:10064
	v_readlane_b32 s18, v253, 48
	s_waitcnt lgkmcnt(0)
	v_sub_f32_e32 v10, v7, v10
	v_sub_f32_e32 v11, v7, v11
	v_mul_f32_e32 v10, 0x3fb8aa3b, v10
	v_mul_f32_e32 v11, 0x3fb8aa3b, v11
	v_exp_f32_e32 v10, v10
	v_exp_f32_e32 v11, v11
	v_lshlrev_b32_e32 v15, 16, v15
	v_lshlrev_b32_e32 v14, 16, v14
	v_pk_mul_f32 v[14:15], v[10:11], v[14:15]
	v_sub_f32_e32 v10, v7, v12
	v_sub_f32_e32 v11, v7, v13
	ds_read_u16 v12, v0 offset:10336
	ds_read_u16 v13, v0 offset:10608
	v_mul_f32_e32 v10, 0x3fb8aa3b, v10
	v_mul_f32_e32 v11, 0x3fb8aa3b, v11
	v_exp_f32_e32 v10, v10
	v_exp_f32_e32 v11, v11
	s_waitcnt lgkmcnt(0)
	v_lshlrev_b32_e32 v13, 16, v13
	v_lshlrev_b32_e32 v12, 16, v12
	v_pk_mul_f32 v[16:17], v[10:11], v[12:13]
	v_cvt_pk_bf16_f32 v10, v4, v5
	v_cvt_pk_bf16_f32 v11, v8, v9
	v_cvt_pk_bf16_f32 v12, v14, v15
	v_cvt_pk_bf16_f32 v13, v16, v17
	flat_store_dwordx4 v[2:3], v[10:13] offset:64
	v_mov_b32_e32 v4, s18
	ds_read_b128 v[8:11], v4
	v_readlane_b32 s18, v253, 49
	s_waitcnt lgkmcnt(0)
	v_sub_f32_e32 v4, v7, v8
	v_sub_f32_e32 v5, v7, v9
	ds_read_u16 v8, v0 offset:10880
	ds_read_u16 v9, v0 offset:11152
	v_mul_f32_e32 v4, 0x3fb8aa3b, v4
	v_mul_f32_e32 v5, 0x3fb8aa3b, v5
	v_exp_f32_e32 v4, v4
	v_exp_f32_e32 v5, v5
	s_waitcnt lgkmcnt(0)
	v_lshlrev_b32_e32 v9, 16, v9
	v_lshlrev_b32_e32 v8, 16, v8
	v_pk_mul_f32 v[4:5], v[4:5], v[8:9]
	v_sub_f32_e32 v8, v7, v10
	v_sub_f32_e32 v9, v7, v11
	ds_read_u16 v10, v0 offset:11424
	ds_read_u16 v11, v0 offset:11696
	v_mul_f32_e32 v8, 0x3fb8aa3b, v8
	v_mul_f32_e32 v9, 0x3fb8aa3b, v9
	v_exp_f32_e32 v8, v8
	v_exp_f32_e32 v9, v9
	s_waitcnt lgkmcnt(0)
	v_lshlrev_b32_e32 v11, 16, v11
	v_lshlrev_b32_e32 v10, 16, v10
	v_pk_mul_f32 v[8:9], v[8:9], v[10:11]
	v_mov_b32_e32 v10, s18
	ds_read_b128 v[10:13], v10
	ds_read_u16 v14, v0 offset:11968
	ds_read_u16 v15, v0 offset:12240
	v_readlane_b32 s18, v253, 50
	s_waitcnt lgkmcnt(0)
	v_sub_f32_e32 v10, v7, v10
	v_sub_f32_e32 v11, v7, v11
	v_mul_f32_e32 v10, 0x3fb8aa3b, v10
	v_mul_f32_e32 v11, 0x3fb8aa3b, v11
	v_exp_f32_e32 v10, v10
	v_exp_f32_e32 v11, v11
	v_lshlrev_b32_e32 v15, 16, v15
	v_lshlrev_b32_e32 v14, 16, v14
	v_pk_mul_f32 v[14:15], v[10:11], v[14:15]
	v_sub_f32_e32 v10, v7, v12
	v_sub_f32_e32 v11, v7, v13
	ds_read_u16 v12, v0 offset:12512
	ds_read_u16 v13, v0 offset:12784
	v_mul_f32_e32 v10, 0x3fb8aa3b, v10
	v_mul_f32_e32 v11, 0x3fb8aa3b, v11
	v_exp_f32_e32 v10, v10
	v_exp_f32_e32 v11, v11
	s_waitcnt lgkmcnt(0)
	v_lshlrev_b32_e32 v13, 16, v13
	v_lshlrev_b32_e32 v12, 16, v12
	v_pk_mul_f32 v[16:17], v[10:11], v[12:13]
	v_cvt_pk_bf16_f32 v10, v4, v5
	v_cvt_pk_bf16_f32 v11, v8, v9
	v_cvt_pk_bf16_f32 v12, v14, v15
	v_cvt_pk_bf16_f32 v13, v16, v17
	flat_store_dwordx4 v[2:3], v[10:13] offset:80
	v_mov_b32_e32 v4, s18
	ds_read_b128 v[8:11], v4
	v_readlane_b32 s18, v253, 51
	s_waitcnt lgkmcnt(0)
	v_sub_f32_e32 v4, v7, v8
	v_sub_f32_e32 v5, v7, v9
	ds_read_u16 v8, v0 offset:13056
	ds_read_u16 v9, v0 offset:13328
	v_mul_f32_e32 v4, 0x3fb8aa3b, v4
	v_mul_f32_e32 v5, 0x3fb8aa3b, v5
	v_exp_f32_e32 v4, v4
	v_exp_f32_e32 v5, v5
	s_waitcnt lgkmcnt(0)
	v_lshlrev_b32_e32 v9, 16, v9
	v_lshlrev_b32_e32 v8, 16, v8
	v_pk_mul_f32 v[4:5], v[4:5], v[8:9]
	v_sub_f32_e32 v8, v7, v10
	v_sub_f32_e32 v9, v7, v11
	ds_read_u16 v10, v0 offset:13600
	ds_read_u16 v11, v0 offset:13872
	v_mul_f32_e32 v8, 0x3fb8aa3b, v8
	v_mul_f32_e32 v9, 0x3fb8aa3b, v9
	v_exp_f32_e32 v8, v8
	v_exp_f32_e32 v9, v9
	s_waitcnt lgkmcnt(0)
	v_lshlrev_b32_e32 v11, 16, v11
	v_lshlrev_b32_e32 v10, 16, v10
	v_pk_mul_f32 v[8:9], v[8:9], v[10:11]
	v_mov_b32_e32 v10, s18
	ds_read_b128 v[10:13], v10
	ds_read_u16 v14, v0 offset:14144
	ds_read_u16 v15, v0 offset:14416
	v_readlane_b32 s18, v253, 52
	s_waitcnt lgkmcnt(0)
	v_sub_f32_e32 v10, v7, v10
	v_sub_f32_e32 v11, v7, v11
	v_mul_f32_e32 v10, 0x3fb8aa3b, v10
	v_mul_f32_e32 v11, 0x3fb8aa3b, v11
	v_exp_f32_e32 v10, v10
	v_exp_f32_e32 v11, v11
	v_lshlrev_b32_e32 v15, 16, v15
	v_lshlrev_b32_e32 v14, 16, v14
	v_pk_mul_f32 v[14:15], v[10:11], v[14:15]
	v_sub_f32_e32 v10, v7, v12
	v_sub_f32_e32 v11, v7, v13
	ds_read_u16 v12, v0 offset:14688
	ds_read_u16 v13, v0 offset:14960
	v_mul_f32_e32 v10, 0x3fb8aa3b, v10
	v_mul_f32_e32 v11, 0x3fb8aa3b, v11
	v_exp_f32_e32 v10, v10
	v_exp_f32_e32 v11, v11
	s_waitcnt lgkmcnt(0)
	v_lshlrev_b32_e32 v13, 16, v13
	v_lshlrev_b32_e32 v12, 16, v12
	v_pk_mul_f32 v[16:17], v[10:11], v[12:13]
	v_cvt_pk_bf16_f32 v10, v4, v5
	v_cvt_pk_bf16_f32 v11, v8, v9
	v_cvt_pk_bf16_f32 v12, v14, v15
	v_cvt_pk_bf16_f32 v13, v16, v17
	flat_store_dwordx4 v[2:3], v[10:13] offset:96
	v_mov_b32_e32 v4, s18
	ds_read_b128 v[8:11], v4
	v_readlane_b32 s18, v253, 53
	s_waitcnt lgkmcnt(0)
	v_sub_f32_e32 v4, v7, v8
	v_sub_f32_e32 v5, v7, v9
	ds_read_u16 v8, v0 offset:15232
	ds_read_u16 v9, v0 offset:15504
	v_mul_f32_e32 v4, 0x3fb8aa3b, v4
	v_mul_f32_e32 v5, 0x3fb8aa3b, v5
	v_exp_f32_e32 v4, v4
	v_exp_f32_e32 v5, v5
	s_waitcnt lgkmcnt(0)
	v_lshlrev_b32_e32 v9, 16, v9
	v_lshlrev_b32_e32 v8, 16, v8
	v_pk_mul_f32 v[4:5], v[4:5], v[8:9]
	v_sub_f32_e32 v8, v7, v10
	v_sub_f32_e32 v9, v7, v11
	ds_read_u16 v10, v0 offset:15776
	ds_read_u16 v11, v0 offset:16048
	v_mul_f32_e32 v8, 0x3fb8aa3b, v8
	v_mul_f32_e32 v9, 0x3fb8aa3b, v9
	v_exp_f32_e32 v8, v8
	v_exp_f32_e32 v9, v9
	s_waitcnt lgkmcnt(0)
	v_lshlrev_b32_e32 v11, 16, v11
	v_lshlrev_b32_e32 v10, 16, v10
	v_pk_mul_f32 v[8:9], v[8:9], v[10:11]
	v_mov_b32_e32 v10, s18
	ds_read_b128 v[10:13], v10
	ds_read_u16 v14, v0 offset:16320
	ds_read_u16 v15, v0 offset:16592
	s_waitcnt lgkmcnt(0)
	v_sub_f32_e32 v10, v7, v10
	v_sub_f32_e32 v11, v7, v11
	v_mul_f32_e32 v10, 0x3fb8aa3b, v10
	v_mul_f32_e32 v11, 0x3fb8aa3b, v11
	v_exp_f32_e32 v10, v10
	v_exp_f32_e32 v11, v11
	v_lshlrev_b32_e32 v15, 16, v15
	v_lshlrev_b32_e32 v14, 16, v14
	v_pk_mul_f32 v[14:15], v[10:11], v[14:15]
	v_sub_f32_e32 v10, v7, v12
	v_sub_f32_e32 v11, v7, v13
	ds_read_u16 v12, v0 offset:16864
	ds_read_u16 v0, v0 offset:17136
	v_mul_f32_e32 v10, 0x3fb8aa3b, v10
	v_mul_f32_e32 v11, 0x3fb8aa3b, v11
	v_exp_f32_e32 v10, v10
	v_exp_f32_e32 v11, v11
	s_waitcnt lgkmcnt(0)
	v_lshlrev_b32_e32 v13, 16, v0
	v_lshlrev_b32_e32 v12, 16, v12
	v_pk_mul_f32 v[16:17], v[10:11], v[12:13]
	v_cvt_pk_bf16_f32 v10, v4, v5
	v_cvt_pk_bf16_f32 v11, v8, v9
	v_cvt_pk_bf16_f32 v12, v14, v15
	v_cvt_pk_bf16_f32 v13, v16, v17
	flat_store_dwordx4 v[2:3], v[10:13] offset:112
	s_and_saveexec_b64 s[24:25], vcc
	s_cbranch_execz .LBB0_171
	v_mul_f32_e32 v0, 0x3fb8aa3b, v7
	v_exp_f32_e32 v0, v0
	v_lshl_add_u64 v[2:3], v[46:47], 2, s[40:41]
	v_mov_b32_e32 v6, 0
	flat_store_dword v[2:3], v0

.LBB0_172:
	s_or_b64 exec, exec, s[0:1]
	v_lshlrev_b32_e32 v0, 4, v49
	v_and_b32_e32 v2, 0xf0, v0
	v_lshlrev_b32_e32 v0, 1, v84
	v_add_u32_e32 v4, 0, v2
	v_lshl_add_u64 v[8:9], s[74:75], 0, v[0:1]
	v_mov_b32_e32 v3, v1
	v_lshrrev_b32_e32 v0, 4, v6
	s_movk_i32 s19, 0x110
	v_readlane_b32 s18, v253, 31
	v_lshl_add_u64 v[2:3], v[8:9], 0, v[2:3]
	v_mad_u64_u32 v[8:9], s[0:1], v0, s19, v[4:5]
	v_lshl_add_u32 v5, v0, 2, s18
	ds_read_b128 v[8:11], v8 offset:51456
	ds_read_b32 v5, v5
	v_add_u32_e32 v46, s63, v46
	s_waitcnt lgkmcnt(0)
	v_lshlrev_b32_e32 v14, 16, v8
	v_mul_f32_e32 v5, 0x3fb8aa3b, v5
	v_exp_f32_e32 v12, v5
	v_and_b32_e32 v15, 0xffff0000, v8
	v_pk_mul_f32 v[14:15], v[12:13], v[14:15] op_sel_hi:[0,1]
	v_cvt_pk_bf16_f32 v8, v14, v15
	v_lshlrev_b32_e32 v14, 16, v9
	v_and_b32_e32 v15, 0xffff0000, v9
	v_pk_mul_f32 v[14:15], v[12:13], v[14:15] op_sel_hi:[0,1]
	v_cvt_pk_bf16_f32 v9, v14, v15
	v_lshlrev_b32_e32 v14, 16, v10
	v_and_b32_e32 v15, 0xffff0000, v10
	v_pk_mul_f32 v[14:15], v[12:13], v[14:15] op_sel_hi:[0,1]
	v_cvt_pk_bf16_f32 v10, v14, v15
	v_lshlrev_b32_e32 v14, 16, v11
	v_and_b32_e32 v15, 0xffff0000, v11
	v_pk_mul_f32 v[12:13], v[12:13], v[14:15] op_sel_hi:[0,1]
	v_cvt_pk_bf16_f32 v11, v12, v13
	v_lshl_add_u64 v[12:13], v[82:83], 0, v[0:1]
	v_lshlrev_b64 v[12:13], 13, v[12:13]
	v_lshl_add_u64 v[12:13], v[2:3], 0, v[12:13]
	v_lshrrev_b32_e32 v0, 4, v49
	flat_store_dwordx4 v[12:13], v[8:11]
	s_nop 1
	v_mad_u64_u32 v[8:9], s[0:1], v0, s19, v[4:5]
	v_lshl_add_u32 v5, v0, 2, s18
	ds_read_b128 v[8:11], v8 offset:51456
	ds_read_b32 v5, v5
	s_waitcnt lgkmcnt(0)
	v_lshlrev_b32_e32 v14, 16, v8
	v_mul_f32_e32 v5, 0x3fb8aa3b, v5
	v_exp_f32_e32 v12, v5
	v_and_b32_e32 v15, 0xffff0000, v8
	v_pk_mul_f32 v[14:15], v[12:13], v[14:15] op_sel_hi:[0,1]
	v_cvt_pk_bf16_f32 v8, v14, v15
	v_lshlrev_b32_e32 v14, 16, v9
	v_and_b32_e32 v15, 0xffff0000, v9
	v_pk_mul_f32 v[14:15], v[12:13], v[14:15] op_sel_hi:[0,1]
	v_cvt_pk_bf16_f32 v9, v14, v15
	v_lshlrev_b32_e32 v14, 16, v10
	v_and_b32_e32 v15, 0xffff0000, v10
	v_pk_mul_f32 v[14:15], v[12:13], v[14:15] op_sel_hi:[0,1]
	v_cvt_pk_bf16_f32 v10, v14, v15
	v_lshlrev_b32_e32 v14, 16, v11
	v_and_b32_e32 v15, 0xffff0000, v11
	v_pk_mul_f32 v[12:13], v[12:13], v[14:15] op_sel_hi:[0,1]
	v_cvt_pk_bf16_f32 v11, v12, v13
	v_lshl_add_u64 v[12:13], v[82:83], 0, v[0:1]
	v_lshlrev_b64 v[12:13], 13, v[12:13]
	v_add_u32_e32 v0, 0x100, v49
	v_lshl_add_u64 v[12:13], v[2:3], 0, v[12:13]
	v_lshrrev_b32_e32 v0, 4, v0
	flat_store_dwordx4 v[12:13], v[8:11]
	s_nop 1
	v_mad_u64_u32 v[8:9], s[0:1], v0, s19, v[4:5]
	v_lshl_add_u32 v5, v0, 2, s18
	ds_read_b128 v[8:11], v8 offset:51456
	ds_read_b32 v5, v5
	s_waitcnt lgkmcnt(0)
	v_lshlrev_b32_e32 v14, 16, v8
	v_mul_f32_e32 v5, 0x3fb8aa3b, v5
	v_exp_f32_e32 v12, v5
	v_and_b32_e32 v15, 0xffff0000, v8
	v_pk_mul_f32 v[14:15], v[12:13], v[14:15] op_sel_hi:[0,1]
	v_cvt_pk_bf16_f32 v8, v14, v15
	v_lshlrev_b32_e32 v14, 16, v9
	v_and_b32_e32 v15, 0xffff0000, v9
	v_pk_mul_f32 v[14:15], v[12:13], v[14:15] op_sel_hi:[0,1]
	v_cvt_pk_bf16_f32 v9, v14, v15
	v_lshlrev_b32_e32 v14, 16, v10
	v_and_b32_e32 v15, 0xffff0000, v10
	v_pk_mul_f32 v[14:15], v[12:13], v[14:15] op_sel_hi:[0,1]
	v_cvt_pk_bf16_f32 v10, v14, v15
	v_lshlrev_b32_e32 v14, 16, v11
	v_and_b32_e32 v15, 0xffff0000, v11
	v_pk_mul_f32 v[12:13], v[12:13], v[14:15] op_sel_hi:[0,1]
	v_cvt_pk_bf16_f32 v11, v12, v13
	v_lshl_add_u64 v[12:13], v[82:83], 0, v[0:1]
	v_lshlrev_b64 v[12:13], 13, v[12:13]
	v_add_u32_e32 v0, 0x200, v49
	v_lshl_add_u64 v[12:13], v[2:3], 0, v[12:13]
	v_lshrrev_b32_e32 v0, 4, v0
	flat_store_dwordx4 v[12:13], v[8:11]
	v_mad_u64_u32 v[4:5], s[0:1], v0, s19, v[4:5]
	ds_read_b128 v[8:11], v4 offset:51456
	v_lshl_add_u32 v4, v0, 2, s18
	ds_read_b32 v4, v4
	s_movk_i32 s0, 0x1000
	v_cmp_gt_i32_e32 vcc, s0, v46
	s_waitcnt lgkmcnt(0)
	v_lshlrev_b32_e32 v12, 16, v8
	v_and_b32_e32 v13, 0xffff0000, v8
	v_mul_f32_e32 v4, 0x3fb8aa3b, v4
	v_exp_f32_e32 v4, v4
	s_nop 0
	v_pk_mul_f32 v[12:13], v[4:5], v[12:13] op_sel_hi:[0,1]
	v_cvt_pk_bf16_f32 v8, v12, v13
	v_lshlrev_b32_e32 v12, 16, v9
	v_and_b32_e32 v13, 0xffff0000, v9
	v_pk_mul_f32 v[12:13], v[4:5], v[12:13] op_sel_hi:[0,1]
	v_cvt_pk_bf16_f32 v9, v12, v13
	v_lshlrev_b32_e32 v12, 16, v10
	v_and_b32_e32 v13, 0xffff0000, v10
	v_pk_mul_f32 v[12:13], v[4:5], v[12:13] op_sel_hi:[0,1]
	v_cvt_pk_bf16_f32 v10, v12, v13
	v_lshlrev_b32_e32 v12, 16, v11
	v_and_b32_e32 v13, 0xffff0000, v11
	v_pk_mul_f32 v[4:5], v[4:5], v[12:13] op_sel_hi:[0,1]
	v_cvt_pk_bf16_f32 v11, v4, v5
	v_lshl_add_u64 v[4:5], v[82:83], 0, v[0:1]
	v_lshlrev_b64 v[4:5], 13, v[4:5]
	v_lshl_add_u64 v[2:3], v[2:3], 0, v[4:5]
	flat_store_dwordx4 v[2:3], v[8:11]
	s_and_saveexec_b64 s[24:25], vcc
	s_cbranch_execz .LBB0_190
	v_readfirstlane_b32 s26, v46
	s_and_b32 s27, s26, 63
	s_bfe_u32 s28, s26, 0x30006
	s_lshl_b32 s28, s28, 8
	s_lshr_b32 s29, s26, 9
	s_lshl_b32 s30, s29, 12
	s_lshl_b32 s31, s27, 6
	s_add_i32 s30, s30, s31
	s_add_i32 s30, s30, -3
	s_lshl_b32 s34, s30, 13
	s_ashr_i32 s35, s30, 31
	s_add_u32 s34, s34, s74
	s_addc_u32 s35, s35, s75
	s_add_u32 s34, s34, s28
	s_addc_u32 s35, s35, 0
	s_mov_b32 s26, 0xaaaaaaab
	v_add_u32_e32 v202, 0xffffff00, v49
	v_lshlrev_b32_e32 v227, 4, v202
	v_add_u32_e32 v203, 2304, v202
	v_mul_hi_u32 v204, v203, s26
	v_lshrrev_b32_e32 v204, 5, v204
	v_mul_u32_u24_e32 v220, 48, v204
	v_sub_u32_e32 v220, v203, v220
	v_lshrrev_b32_e32 v221, 4, v220
	v_mul_u32_u24_e32 v221, 0x700, v221
	v_lshl_add_u32 v221, v220, 4, v221
	v_lshl_add_u32 v221, v204, 13, v221
	global_load_dwordx4 v[2:5], v221, s[34:35]
	v_add_u32_e32 v203, 2560, v202
	v_mul_hi_u32 v204, v203, s26
	v_lshrrev_b32_e32 v204, 5, v204
	v_mul_u32_u24_e32 v220, 48, v204
	v_sub_u32_e32 v220, v203, v220
	v_lshrrev_b32_e32 v221, 4, v220
	v_mul_u32_u24_e32 v221, 0x700, v221
	v_lshl_add_u32 v221, v220, 4, v221
	v_lshl_add_u32 v221, v204, 13, v221
	global_load_dwordx4 v[6:9], v221, s[34:35]
	v_add_u32_e32 v203, 2816, v202
	v_mul_hi_u32 v204, v203, s26
	v_lshrrev_b32_e32 v204, 5, v204
	v_mul_u32_u24_e32 v220, 48, v204
	v_sub_u32_e32 v220, v203, v220
	v_lshrrev_b32_e32 v221, 4, v220
	v_mul_u32_u24_e32 v221, 0x700, v221
	v_lshl_add_u32 v221, v220, 4, v221
	v_lshl_add_u32 v221, v204, 13, v221
	global_load_dwordx4 v[10:13], v221, s[34:35]
	s_mov_b64 s[28:29], exec
	v_cmp_gt_u32_e32 vcc, 0x90, v202
	s_and_b64 exec, s[28:29], vcc
	s_cbranch_execz .Lrl_l_no12
	v_add_u32_e32 v203, 3072, v202
	v_mul_hi_u32 v204, v203, s26
	v_lshrrev_b32_e32 v204, 5, v204
	v_mul_u32_u24_e32 v220, 48, v204
	v_sub_u32_e32 v220, v203, v220
	v_lshrrev_b32_e32 v221, 4, v220
	v_mul_u32_u24_e32 v221, 0x700, v221
	v_lshl_add_u32 v221, v220, 4, v221
	v_lshl_add_u32 v221, v204, 13, v221
	global_load_dwordx4 v[14:17], v221, s[34:35]
.Lrl_l_no12:
	s_mov_b64 exec, s[28:29]
	s_waitcnt vmcnt(3)
	ds_write_b128 v227, v[190:193]
	ds_write_b128 v227, v[194:197] offset:4096
	ds_write_b128 v227, v[198:201] offset:8192
	ds_write_b128 v227, v[206:209] offset:12288
	ds_write_b128 v227, v[210:213] offset:16384
	ds_write_b128 v227, v[214:217] offset:20480
	ds_write_b128 v227, v[238:241] offset:24576
	ds_write_b128 v227, v[242:245] offset:28672
	ds_write_b128 v227, v[246:249] offset:32768
	s_waitcnt vmcnt(0)
	ds_write_b128 v227, v[2:5] offset:36864
	ds_write_b128 v227, v[6:9] offset:40960
	ds_write_b128 v227, v[10:13] offset:45056
	s_and_b64 exec, s[28:29], vcc
	s_cbranch_execz .Lrl_l_now12
	ds_write_b128 v227, v[14:17] offset:49152
.Lrl_l_now12:
	s_mov_b64 exec, s[28:29]

.LBB0_191:
	s_andn2_saveexec_b64 s[20:21], s[20:21]
	s_cbranch_execz .LBB0_43
	s_movk_i32 s0, 0x7f
	v_cmp_lt_u32_e32 vcc, s0, v49
	s_movk_i32 s0, 0x80
	v_lshlrev_b32_e32 v0, 1, v49
	v_cmp_gt_u32_e64 s[0:1], s0, v49
	v_and_b32_e32 v47, 0x7f, v49
	v_and_b32_e32 v0, 0xffffff00, v0
	v_cndmask_b32_e64 v2, v232, v223, s[0:1]
	v_add_u32_e32 v0, 0x1d700, v0
	v_lshl_or_b32 v2, v47, 1, v2
	v_mov_b32_e32 v3, 0x19100
	v_cndmask_b32_e64 v55, v228, v229, s[0:1]
	v_add_u32_e32 v53, 0, v0
	v_add_u32_e32 v51, 0, v2
	v_add_u32_e32 v57, 0, v3
	v_mov_b32_e32 v85, v1
	v_mov_b32_e32 v0, 0
	v_mov_b32_e32 v2, 0
	v_mov_b32_e32 v3, 0
	v_mov_b32_e32 v4, 0
	v_mov_b32_e32 v5, 0
	v_mov_b32_e32 v6, 0
	v_mov_b32_e32 v7, 0
	v_mov_b32_e32 v8, 0
	v_mov_b32_e32 v9, 0
	v_mov_b32_e32 v10, 0
	v_mov_b32_e32 v11, 0
	v_mov_b32_e32 v12, 0
	v_mov_b32_e32 v13, 0
	v_mov_b32_e32 v14, 0
	v_mov_b32_e32 v15, 0
	v_mov_b32_e32 v16, 0
	v_mov_b32_e32 v17, 0
	v_mov_b32_e32 v18, 0
	v_mov_b32_e32 v19, 0
	v_mov_b32_e32 v20, 0
	v_mov_b32_e32 v21, 0
	v_mov_b32_e32 v22, 0
	v_mov_b32_e32 v23, 0
	v_mov_b32_e32 v24, 0
	v_mov_b32_e32 v25, 0
	v_mov_b32_e32 v26, 0
	v_mov_b32_e32 v27, 0
	v_mov_b32_e32 v28, 0
	v_mov_b32_e32 v29, 0
	v_mov_b32_e32 v30, 0
	v_mov_b32_e32 v31, 0
	v_mov_b32_e32 v32, 0
	v_mov_b32_e32 v33, 0
	v_mov_b32_e32 v34, 0
	v_mov_b32_e32 v35, 0
	v_mov_b32_e32 v36, 0
	v_mov_b32_e32 v37, 0
	v_mov_b32_e32 v86, 0
	v_mov_b32_e32 v87, 0
	v_mov_b32_e32 v88, 0
	v_mov_b32_e32 v89, 0
	v_mov_b32_e32 v90, 0
	v_mov_b32_e32 v91, 0
	v_mov_b32_e32 v92, 0
	v_mov_b32_e32 v93, 0
	v_mov_b32_e32 v94, 0
	v_mov_b32_e32 v95, 0
	v_mov_b32_e32 v96, 0
	v_mov_b32_e32 v97, 0
	v_mov_b32_e32 v98, 0
	v_mov_b32_e32 v99, 0
	v_mov_b32_e32 v100, 0
	v_mov_b32_e32 v101, 0
	v_mov_b32_e32 v102, 0
	v_mov_b32_e32 v103, 0
	v_mov_b32_e32 v104, 0
	v_mov_b32_e32 v105, 0
	v_mov_b32_e32 v106, 0
	v_mov_b32_e32 v107, 0
	v_mov_b32_e32 v108, 0
	v_mov_b32_e32 v109, 0
	v_mov_b32_e32 v110, 0
	v_mov_b32_e32 v111, 0
	v_mov_b32_e32 v112, 0
	v_mov_b32_e32 v113, 0
	ds_read_u16 v221, v51
	ds_read_b32 v220, v53
	ds_read_b128 v[174:177], v57 offset:272
	v_mad_u32_u24 v61, v55, 1, v51
	ds_read_u16 v227, v61
	ds_read_b32 v226, v53 offset:4
	ds_read_b128 v[178:181], v57 offset:544
	v_mad_u32_u24 v61, v55, 2, v51
	ds_read_u16 v59, v61
	ds_read_b32 v204, v53 offset:8
	ds_read_b128 v[182:185], v57 offset:816
	s_waitcnt lgkmcnt(7)
	v_lshlrev_b32_e32 v221, 16, v221
	v_mul_f32_e32 v0, v220, v221
	v_mov_b32_e32 v2, v0
	v_mad_u32_u24 v61, v55, 3, v51
	ds_read_u16 v221, v61
	ds_read_b32 v220, v53 offset:12
	ds_read_b128 v[186:189], v57 offset:1088
	s_waitcnt lgkmcnt(9)
	v_pk_fma_f32 v[250:251], v[174:175], v[2:3], 0 op_sel_hi:[1,1,0]
	v_pk_fma_f32 v[202:203], v[176:177], v[4:5], 0 op_sel_hi:[1,1,0]
	v_add_f32_e32 v250, v250, v251
	v_add_f32_e32 v202, v202, v203
	s_waitcnt lgkmcnt(7)
	v_lshlrev_b32_e32 v227, 16, v227
	v_add_f32_e32 v250, v250, v202
	v_fma_f32 v3, v226, v227, -v250
	v_mad_u32_u24 v61, v55, 4, v51
	ds_read_u16 v227, v61
	ds_read_b32 v226, v53 offset:16
	ds_read_b128 v[190:193], v57 offset:1360
	ds_read_b128 v[194:197], v57 offset:1376
	s_waitcnt lgkmcnt(10)
	v_pk_fma_f32 v[246:247], v[178:179], v[2:3], 0 op_sel_hi:[1,1,0]
	v_pk_fma_f32 v[248:249], v[180:181], v[4:5], 0 op_sel_hi:[1,1,0]
	v_add_f32_e32 v246, v246, v247
	v_add_f32_e32 v248, v248, v249
	s_waitcnt lgkmcnt(8)
	v_lshlrev_b32_e32 v59, 16, v59
	v_add_f32_e32 v246, v246, v248
	v_fma_f32 v4, v204, v59, -v246
	v_mad_u32_u24 v61, v55, 5, v51
	ds_read_u16 v59, v61
	ds_read_b32 v204, v53 offset:20
	ds_read_b128 v[198:201], v57 offset:1632
	ds_read_b128 v[206:209], v57 offset:1648
	s_waitcnt lgkmcnt(11)
	v_pk_fma_f32 v[250:251], v[182:183], v[2:3], 0 op_sel_hi:[1,1,0]
	v_pk_fma_f32 v[202:203], v[184:185], v[4:5], 0 op_sel_hi:[1,1,0]
	v_add_f32_e32 v250, v250, v251
	v_add_f32_e32 v202, v202, v203
	s_waitcnt lgkmcnt(9)
	v_lshlrev_b32_e32 v221, 16, v221
	v_add_f32_e32 v250, v250, v202
	v_fma_f32 v5, v220, v221, -v250
	v_mad_u32_u24 v61, v55, 6, v51
	ds_read_u16 v221, v61
	ds_read_b32 v220, v53 offset:24
	ds_read_b128 v[210:213], v57 offset:1904
	ds_read_b128 v[214:217], v57 offset:1920
	s_waitcnt lgkmcnt(12)
	v_pk_fma_f32 v[246:247], v[186:187], v[2:3], 0 op_sel_hi:[1,1,0]
	v_pk_fma_f32 v[248:249], v[188:189], v[4:5], 0 op_sel_hi:[1,1,0]
	s_waitcnt lgkmcnt(9)
	v_pk_fma_f32 v[250:251], v[190:191], v[2:3], 0 op_sel_hi:[1,1,0]
	v_pk_fma_f32 v[202:203], v[192:193], v[4:5], 0 op_sel_hi:[1,1,0]
	v_add_f32_e32 v246, v246, v247
	v_add_f32_e32 v248, v248, v249
	v_lshlrev_b32_e32 v227, 16, v227
	v_add_f32_e32 v246, v246, v248
	v_fma_f32 v6, v226, v227, -v246
	v_mad_u32_u24 v61, v55, 7, v51
	ds_read_u16 v227, v61
	ds_read_b32 v226, v53 offset:28
	ds_read_b128 v[238:241], v57 offset:2176
	ds_read_b128 v[242:245], v57 offset:2192
	s_waitcnt lgkmcnt(12)
	v_pk_fma_f32 v[250:251], v[194:195], v[6:7], v[250:251]
	v_pk_fma_f32 v[202:203], v[196:197], v[8:9], v[202:203]
	s_waitcnt lgkmcnt(9)
	v_pk_fma_f32 v[246:247], v[198:199], v[2:3], 0 op_sel_hi:[1,1,0]
	v_pk_fma_f32 v[248:249], v[200:201], v[4:5], 0 op_sel_hi:[1,1,0]
	v_add_f32_e32 v250, v250, v251
	v_add_f32_e32 v202, v202, v203
	v_lshlrev_b32_e32 v59, 16, v59
	v_add_f32_e32 v250, v250, v202
	v_fma_f32 v7, v204, v59, -v250
	v_mad_u32_u24 v61, v55, 8, v51
	ds_read_u16 v59, v61
	ds_read_b32 v204, v53 offset:32
	ds_read_b128 v[174:177], v57 offset:2448
	ds_read_b128 v[178:181], v57 offset:2464
	s_waitcnt lgkmcnt(12)
	v_pk_fma_f32 v[246:247], v[206:207], v[6:7], v[246:247]
	v_pk_fma_f32 v[248:249], v[208:209], v[8:9], v[248:249]
	ds_read_b128 v[182:185], v57 offset:2480
	s_waitcnt lgkmcnt(10)
	v_pk_fma_f32 v[250:251], v[210:211], v[2:3], 0 op_sel_hi:[1,1,0]
	v_pk_fma_f32 v[202:203], v[212:213], v[4:5], 0 op_sel_hi:[1,1,0]
	v_add_f32_e32 v246, v246, v247
	v_add_f32_e32 v248, v248, v249
	v_lshlrev_b32_e32 v221, 16, v221
	v_add_f32_e32 v246, v246, v248
	v_fma_f32 v8, v220, v221, -v246
	v_mad_u32_u24 v61, v55, 9, v51
	ds_read_u16 v221, v61
	ds_read_b32 v220, v53 offset:36
	ds_read_b128 v[186:189], v57 offset:2720
	s_waitcnt lgkmcnt(12)
	v_pk_fma_f32 v[250:251], v[214:215], v[6:7], v[250:251]
	v_pk_fma_f32 v[202:203], v[216:217], v[8:9], v[202:203]
	ds_read_b128 v[190:193], v57 offset:2736
	s_waitcnt lgkmcnt(10)
	v_pk_fma_f32 v[246:247], v[238:239], v[2:3], 0 op_sel_hi:[1,1,0]
	v_pk_fma_f32 v[248:249], v[240:241], v[4:5], 0 op_sel_hi:[1,1,0]
	ds_read_b128 v[194:197], v57 offset:2752
	v_add_f32_e32 v250, v250, v251
	v_add_f32_e32 v202, v202, v203
	v_lshlrev_b32_e32 v227, 16, v227
	v_add_f32_e32 v250, v250, v202
	v_fma_f32 v9, v226, v227, -v250
	v_mad_u32_u24 v61, v55, 10, v51
	ds_read_u16 v227, v61
	ds_read_b32 v226, v53 offset:40
	s_waitcnt lgkmcnt(12)
	v_pk_fma_f32 v[246:247], v[242:243], v[6:7], v[246:247]
	v_pk_fma_f32 v[248:249], v[244:245], v[8:9], v[248:249]
	ds_read_b128 v[198:201], v57 offset:2992
	s_waitcnt lgkmcnt(10)
	v_pk_fma_f32 v[250:251], v[174:175], v[2:3], 0 op_sel_hi:[1,1,0]
	v_pk_fma_f32 v[202:203], v[176:177], v[4:5], 0 op_sel_hi:[1,1,0]
	ds_read_b128 v[206:209], v57 offset:3008
	ds_read_b128 v[210:213], v57 offset:3024
	v_add_f32_e32 v246, v246, v247
	s_waitcnt lgkmcnt(11)
	v_pk_fma_f32 v[250:251], v[178:179], v[6:7], v[250:251]
	v_pk_fma_f32 v[202:203], v[180:181], v[8:9], v[202:203]
	v_add_f32_e32 v248, v248, v249
	v_lshlrev_b32_e32 v59, 16, v59
	v_add_f32_e32 v246, v246, v248
	v_fma_f32 v10, v204, v59, -v246
	v_mad_u32_u24 v61, v55, 11, v51
	ds_read_u16 v59, v61
	ds_read_b32 v204, v53 offset:44
	s_waitcnt lgkmcnt(12)
	v_pk_fma_f32 v[250:251], v[182:183], v[10:11], v[250:251]
	v_pk_fma_f32 v[202:203], v[184:185], v[12:13], v[202:203]
	ds_read_b128 v[214:217], v57 offset:3264
	s_waitcnt lgkmcnt(10)
	v_pk_fma_f32 v[246:247], v[186:187], v[2:3], 0 op_sel_hi:[1,1,0]
	v_pk_fma_f32 v[248:249], v[188:189], v[4:5], 0 op_sel_hi:[1,1,0]
	ds_read_b128 v[238:241], v57 offset:3280
	ds_read_b128 v[242:245], v57 offset:3296
	v_add_f32_e32 v250, v250, v251
	s_waitcnt lgkmcnt(11)
	v_pk_fma_f32 v[246:247], v[190:191], v[6:7], v[246:247]
	v_pk_fma_f32 v[248:249], v[192:193], v[8:9], v[248:249]
	v_add_f32_e32 v202, v202, v203
	v_lshlrev_b32_e32 v221, 16, v221
	v_add_f32_e32 v250, v250, v202
	v_fma_f32 v11, v220, v221, -v250
	v_mad_u32_u24 v61, v55, 12, v51
	ds_read_u16 v221, v61
	ds_read_b32 v220, v53 offset:48
	s_waitcnt lgkmcnt(12)
	v_pk_fma_f32 v[246:247], v[194:195], v[10:11], v[246:247]
	v_pk_fma_f32 v[248:249], v[196:197], v[12:13], v[248:249]
	ds_read_b128 v[174:177], v57 offset:3536
	s_waitcnt lgkmcnt(10)
	v_pk_fma_f32 v[250:251], v[198:199], v[2:3], 0 op_sel_hi:[1,1,0]
	v_pk_fma_f32 v[202:203], v[200:201], v[4:5], 0 op_sel_hi:[1,1,0]
	ds_read_b128 v[178:181], v57 offset:3552
	ds_read_b128 v[182:185], v57 offset:3568
	ds_read_b128 v[186:189], v57 offset:3584
	v_add_f32_e32 v246, v246, v247
	s_waitcnt lgkmcnt(12)
	v_pk_fma_f32 v[250:251], v[206:207], v[6:7], v[250:251]
	v_pk_fma_f32 v[202:203], v[208:209], v[8:9], v[202:203]
	v_add_f32_e32 v248, v248, v249
	v_lshlrev_b32_e32 v227, 16, v227
	v_add_f32_e32 v246, v246, v248
	v_fma_f32 v12, v226, v227, -v246
	s_waitcnt lgkmcnt(11)
	v_pk_fma_f32 v[250:251], v[210:211], v[10:11], v[250:251]
	v_pk_fma_f32 v[202:203], v[212:213], v[12:13], v[202:203]
	v_mad_u32_u24 v61, v55, 13, v51
	ds_read_u16 v227, v61
	ds_read_b32 v226, v53 offset:52
	s_waitcnt lgkmcnt(10)
	v_pk_fma_f32 v[246:247], v[214:215], v[2:3], 0 op_sel_hi:[1,1,0]
	v_pk_fma_f32 v[248:249], v[216:217], v[4:5], 0 op_sel_hi:[1,1,0]
	ds_read_b128 v[190:193], v57 offset:3808
	ds_read_b128 v[194:197], v57 offset:3824
	ds_read_b128 v[198:201], v57 offset:3840
	v_add_f32_e32 v250, v250, v251
	s_waitcnt lgkmcnt(12)
	v_pk_fma_f32 v[246:247], v[238:239], v[6:7], v[246:247]
	v_pk_fma_f32 v[248:249], v[240:241], v[8:9], v[248:249]
	ds_read_b128 v[206:209], v57 offset:3856
	v_add_f32_e32 v202, v202, v203
	v_lshlrev_b32_e32 v59, 16, v59
	v_add_f32_e32 v250, v250, v202
	v_fma_f32 v13, v204, v59, -v250
	s_waitcnt lgkmcnt(12)
	v_pk_fma_f32 v[246:247], v[242:243], v[10:11], v[246:247]
	v_pk_fma_f32 v[248:249], v[244:245], v[12:13], v[248:249]
	s_waitcnt lgkmcnt(9)
	v_pk_fma_f32 v[250:251], v[174:175], v[2:3], 0 op_sel_hi:[1,1,0]
	v_pk_fma_f32 v[202:203], v[176:177], v[4:5], 0 op_sel_hi:[1,1,0]
	v_mad_u32_u24 v61, v55, 14, v51
	ds_read_u16 v59, v61
	ds_read_b32 v204, v53 offset:56
	ds_read_b128 v[210:213], v57 offset:4080
	ds_read_b128 v[214:217], v57 offset:4096
	v_add_f32_e32 v246, v246, v247
	s_waitcnt lgkmcnt(12)
	v_pk_fma_f32 v[250:251], v[178:179], v[6:7], v[250:251]
	v_pk_fma_f32 v[202:203], v[180:181], v[8:9], v[202:203]
	ds_read_b128 v[238:241], v57 offset:4112
	v_add_f32_e32 v248, v248, v249
	s_waitcnt lgkmcnt(12)
	v_pk_fma_f32 v[250:251], v[182:183], v[10:11], v[250:251]
	v_pk_fma_f32 v[202:203], v[184:185], v[12:13], v[202:203]
	ds_read_b128 v[242:245], v57 offset:4128
	v_lshlrev_b32_e32 v221, 16, v221
	v_add_f32_e32 v246, v246, v248
	v_fma_f32 v14, v220, v221, -v246
	s_waitcnt lgkmcnt(12)
	v_pk_fma_f32 v[250:251], v[186:187], v[14:15], v[250:251]
	v_pk_fma_f32 v[202:203], v[188:189], v[16:17], v[202:203]
	s_waitcnt lgkmcnt(9)
	v_pk_fma_f32 v[246:247], v[190:191], v[2:3], 0 op_sel_hi:[1,1,0]
	v_pk_fma_f32 v[248:249], v[192:193], v[4:5], 0 op_sel_hi:[1,1,0]
	v_mad_u32_u24 v61, v55, 15, v51
	ds_read_u16 v221, v61
	ds_read_b32 v220, v53 offset:60
	ds_read_b128 v[174:177], v57 offset:4352
	ds_read_b128 v[178:181], v57 offset:4368
	v_add_f32_e32 v250, v250, v251
	s_waitcnt lgkmcnt(12)
	v_pk_fma_f32 v[246:247], v[194:195], v[6:7], v[246:247]
	v_pk_fma_f32 v[248:249], v[196:197], v[8:9], v[248:249]
	ds_read_b128 v[182:185], v57 offset:4384
	v_add_f32_e32 v202, v202, v203
	s_waitcnt lgkmcnt(12)
	v_pk_fma_f32 v[246:247], v[198:199], v[10:11], v[246:247]
	v_pk_fma_f32 v[248:249], v[200:201], v[12:13], v[248:249]
	ds_read_b128 v[186:189], v57 offset:4400
	v_lshlrev_b32_e32 v227, 16, v227
	v_add_f32_e32 v250, v250, v202
	v_fma_f32 v15, v226, v227, -v250
	s_waitcnt lgkmcnt(12)
	v_pk_fma_f32 v[246:247], v[206:207], v[14:15], v[246:247]
	v_pk_fma_f32 v[248:249], v[208:209], v[16:17], v[248:249]
	s_waitcnt lgkmcnt(9)
	v_pk_fma_f32 v[250:251], v[210:211], v[2:3], 0 op_sel_hi:[1,1,0]
	v_pk_fma_f32 v[202:203], v[212:213], v[4:5], 0 op_sel_hi:[1,1,0]
	v_mad_u32_u24 v61, v55, 16, v51
	ds_read_u16 v227, v61
	ds_read_b32 v226, v53 offset:64
	ds_read_b128 v[190:193], v57 offset:4624
	ds_read_b128 v[194:197], v57 offset:4640
	v_add_f32_e32 v246, v246, v247
	s_waitcnt lgkmcnt(12)
	v_pk_fma_f32 v[250:251], v[214:215], v[6:7], v[250:251]
	v_pk_fma_f32 v[202:203], v[216:217], v[8:9], v[202:203]
	ds_read_b128 v[198:201], v57 offset:4656
	v_add_f32_e32 v248, v248, v249
	s_waitcnt lgkmcnt(12)
	v_pk_fma_f32 v[250:251], v[238:239], v[10:11], v[250:251]
	v_pk_fma_f32 v[202:203], v[240:241], v[12:13], v[202:203]
	ds_read_b128 v[206:209], v57 offset:4672
	v_lshlrev_b32_e32 v59, 16, v59
	v_add_f32_e32 v246, v246, v248
	v_fma_f32 v16, v204, v59, -v246
	s_waitcnt lgkmcnt(12)
	v_pk_fma_f32 v[250:251], v[242:243], v[14:15], v[250:251]
	v_pk_fma_f32 v[202:203], v[244:245], v[16:17], v[202:203]
	ds_read_b128 v[210:213], v57 offset:4688
	s_waitcnt lgkmcnt(10)
	v_pk_fma_f32 v[246:247], v[174:175], v[2:3], 0 op_sel_hi:[1,1,0]
	v_pk_fma_f32 v[248:249], v[176:177], v[4:5], 0 op_sel_hi:[1,1,0]
	v_mad_u32_u24 v61, v55, 17, v51
	ds_read_u16 v59, v61
	ds_read_b32 v204, v53 offset:68
	ds_read_b128 v[214:217], v57 offset:4896
	v_add_f32_e32 v250, v250, v251
	s_waitcnt lgkmcnt(12)
	v_pk_fma_f32 v[246:247], v[178:179], v[6:7], v[246:247]
	v_pk_fma_f32 v[248:249], v[180:181], v[8:9], v[248:249]
	ds_read_b128 v[238:241], v57 offset:4912
	v_add_f32_e32 v202, v202, v203
	s_waitcnt lgkmcnt(12)
	v_pk_fma_f32 v[246:247], v[182:183], v[10:11], v[246:247]
	v_pk_fma_f32 v[248:249], v[184:185], v[12:13], v[248:249]
	ds_read_b128 v[242:245], v57 offset:4928
	v_lshlrev_b32_e32 v221, 16, v221
	v_add_f32_e32 v250, v250, v202
	v_fma_f32 v17, v220, v221, -v250
	s_waitcnt lgkmcnt(12)
	v_pk_fma_f32 v[246:247], v[186:187], v[14:15], v[246:247]
	v_pk_fma_f32 v[248:249], v[188:189], v[16:17], v[248:249]
	ds_read_b128 v[174:177], v57 offset:4944
	s_waitcnt lgkmcnt(10)
	v_pk_fma_f32 v[250:251], v[190:191], v[2:3], 0 op_sel_hi:[1,1,0]
	v_pk_fma_f32 v[202:203], v[192:193], v[4:5], 0 op_sel_hi:[1,1,0]
	ds_read_b128 v[178:181], v57 offset:4960
	v_mad_u32_u24 v61, v55, 18, v51
	ds_read_u16 v221, v61
	ds_read_b32 v220, v53 offset:72
	v_add_f32_e32 v246, v246, v247
	s_waitcnt lgkmcnt(12)
	v_pk_fma_f32 v[250:251], v[194:195], v[6:7], v[250:251]
	v_pk_fma_f32 v[202:203], v[196:197], v[8:9], v[202:203]
	ds_read_b128 v[182:185], v57 offset:5168
	v_add_f32_e32 v248, v248, v249
	s_waitcnt lgkmcnt(12)
	v_pk_fma_f32 v[250:251], v[198:199], v[10:11], v[250:251]
	v_pk_fma_f32 v[202:203], v[200:201], v[12:13], v[202:203]
	ds_read_b128 v[186:189], v57 offset:5184
	v_lshlrev_b32_e32 v227, 16, v227
	s_waitcnt lgkmcnt(12)
	v_pk_fma_f32 v[250:251], v[206:207], v[14:15], v[250:251]
	v_pk_fma_f32 v[202:203], v[208:209], v[16:17], v[202:203]
	ds_read_b128 v[190:193], v57 offset:5200
	v_add_f32_e32 v246, v246, v248
	v_fma_f32 v18, v226, v227, -v246
	s_waitcnt lgkmcnt(12)
	v_pk_fma_f32 v[250:251], v[210:211], v[18:19], v[250:251]
	v_pk_fma_f32 v[202:203], v[212:213], v[20:21], v[202:203]
	ds_read_b128 v[194:197], v57 offset:5216
	s_waitcnt lgkmcnt(10)
	v_pk_fma_f32 v[246:247], v[214:215], v[2:3], 0 op_sel_hi:[1,1,0]
	v_pk_fma_f32 v[248:249], v[216:217], v[4:5], 0 op_sel_hi:[1,1,0]
	ds_read_b128 v[198:201], v57 offset:5232
	v_mad_u32_u24 v61, v55, 19, v51
	ds_read_u16 v227, v61
	ds_read_b32 v226, v53 offset:76
	v_add_f32_e32 v250, v250, v251
	s_waitcnt lgkmcnt(12)
	v_pk_fma_f32 v[246:247], v[238:239], v[6:7], v[246:247]
	v_pk_fma_f32 v[248:249], v[240:241], v[8:9], v[248:249]
	ds_read_b128 v[206:209], v57 offset:5440
	v_add_f32_e32 v202, v202, v203
	s_waitcnt lgkmcnt(12)
	v_pk_fma_f32 v[246:247], v[242:243], v[10:11], v[246:247]
	v_pk_fma_f32 v[248:249], v[244:245], v[12:13], v[248:249]
	ds_read_b128 v[210:213], v57 offset:5456
	v_lshlrev_b32_e32 v59, 16, v59
	s_waitcnt lgkmcnt(12)
	v_pk_fma_f32 v[246:247], v[174:175], v[14:15], v[246:247]
	v_pk_fma_f32 v[248:249], v[176:177], v[16:17], v[248:249]
	ds_read_b128 v[214:217], v57 offset:5472
	v_add_f32_e32 v250, v250, v202
	v_fma_f32 v19, v204, v59, -v250
	s_waitcnt lgkmcnt(12)
	v_pk_fma_f32 v[246:247], v[178:179], v[18:19], v[246:247]
	v_pk_fma_f32 v[248:249], v[180:181], v[20:21], v[248:249]
	ds_read_b128 v[238:241], v57 offset:5488
	s_waitcnt lgkmcnt(10)
	v_pk_fma_f32 v[250:251], v[182:183], v[2:3], 0 op_sel_hi:[1,1,0]
	v_pk_fma_f32 v[202:203], v[184:185], v[4:5], 0 op_sel_hi:[1,1,0]
	ds_read_b128 v[242:245], v57 offset:5504
	v_mad_u32_u24 v61, v55, 20, v51
	ds_read_u16 v59, v61
	ds_read_b32 v204, v53 offset:80
	v_add_f32_e32 v246, v246, v247
	s_waitcnt lgkmcnt(12)
	v_pk_fma_f32 v[250:251], v[186:187], v[6:7], v[250:251]
	v_pk_fma_f32 v[202:203], v[188:189], v[8:9], v[202:203]
	ds_read_b128 v[174:177], v57 offset:5712
	v_add_f32_e32 v248, v248, v249
	s_waitcnt lgkmcnt(12)
	v_pk_fma_f32 v[250:251], v[190:191], v[10:11], v[250:251]
	v_pk_fma_f32 v[202:203], v[192:193], v[12:13], v[202:203]
	ds_read_b128 v[178:181], v57 offset:5728
	v_lshlrev_b32_e32 v221, 16, v221
	s_waitcnt lgkmcnt(12)
	v_pk_fma_f32 v[250:251], v[194:195], v[14:15], v[250:251]
	v_pk_fma_f32 v[202:203], v[196:197], v[16:17], v[202:203]
	ds_read_b128 v[182:185], v57 offset:5744
	v_add_f32_e32 v246, v246, v248
	v_fma_f32 v20, v220, v221, -v246
	s_waitcnt lgkmcnt(12)
	v_pk_fma_f32 v[250:251], v[198:199], v[18:19], v[250:251]
	v_pk_fma_f32 v[202:203], v[200:201], v[20:21], v[202:203]
	ds_read_b128 v[186:189], v57 offset:5760
	s_waitcnt lgkmcnt(10)
	v_pk_fma_f32 v[246:247], v[206:207], v[2:3], 0 op_sel_hi:[1,1,0]
	v_pk_fma_f32 v[248:249], v[208:209], v[4:5], 0 op_sel_hi:[1,1,0]
	ds_read_b128 v[190:193], v57 offset:5776
	ds_read_b128 v[194:197], v57 offset:5792
	v_add_f32_e32 v250, v250, v251
	s_waitcnt lgkmcnt(11)
	v_pk_fma_f32 v[246:247], v[210:211], v[6:7], v[246:247]
	v_pk_fma_f32 v[248:249], v[212:213], v[8:9], v[248:249]
	v_mad_u32_u24 v61, v55, 21, v51
	ds_read_u16 v221, v61
	ds_read_b32 v220, v53 offset:84
	v_add_f32_e32 v202, v202, v203
	s_waitcnt lgkmcnt(12)
	v_pk_fma_f32 v[246:247], v[214:215], v[10:11], v[246:247]
	v_pk_fma_f32 v[248:249], v[216:217], v[12:13], v[248:249]
	ds_read_b128 v[198:201], v57 offset:5984
	v_lshlrev_b32_e32 v227, 16, v227
	s_waitcnt lgkmcnt(12)
	v_pk_fma_f32 v[246:247], v[238:239], v[14:15], v[246:247]
	v_pk_fma_f32 v[248:249], v[240:241], v[16:17], v[248:249]
	ds_read_b128 v[206:209], v57 offset:6000
	v_add_f32_e32 v250, v250, v202
	v_fma_f32 v21, v226, v227, -v250
	s_waitcnt lgkmcnt(12)
	v_pk_fma_f32 v[246:247], v[242:243], v[18:19], v[246:247]
	v_pk_fma_f32 v[248:249], v[244:245], v[20:21], v[248:249]
	ds_read_b128 v[210:213], v57 offset:6016
	s_waitcnt lgkmcnt(10)
	v_pk_fma_f32 v[250:251], v[174:175], v[2:3], 0 op_sel_hi:[1,1,0]
	v_pk_fma_f32 v[202:203], v[176:177], v[4:5], 0 op_sel_hi:[1,1,0]
	ds_read_b128 v[214:217], v57 offset:6032
	ds_read_b128 v[238:241], v57 offset:6048
	ds_read_b128 v[242:245], v57 offset:6064
	v_add_f32_e32 v246, v246, v247
	s_waitcnt lgkmcnt(12)
	v_pk_fma_f32 v[250:251], v[178:179], v[6:7], v[250:251]
	v_pk_fma_f32 v[202:203], v[180:181], v[8:9], v[202:203]
	v_add_f32_e32 v248, v248, v249
	s_waitcnt lgkmcnt(11)
	v_pk_fma_f32 v[250:251], v[182:183], v[10:11], v[250:251]
	v_pk_fma_f32 v[202:203], v[184:185], v[12:13], v[202:203]
	v_mad_u32_u24 v61, v55, 22, v51
	ds_read_u16 v227, v61
	ds_read_b32 v226, v53 offset:88
	v_lshlrev_b32_e32 v59, 16, v59
	s_waitcnt lgkmcnt(12)
	v_pk_fma_f32 v[250:251], v[186:187], v[14:15], v[250:251]
	v_pk_fma_f32 v[202:203], v[188:189], v[16:17], v[202:203]
	ds_read_b128 v[174:177], v57 offset:6256
	v_add_f32_e32 v246, v246, v248
	s_waitcnt lgkmcnt(12)
	v_pk_fma_f32 v[250:251], v[190:191], v[18:19], v[250:251]
	v_pk_fma_f32 v[202:203], v[192:193], v[20:21], v[202:203]
	ds_read_b128 v[178:181], v57 offset:6272
	v_fma_f32 v22, v204, v59, -v246
	s_waitcnt lgkmcnt(12)
	v_pk_fma_f32 v[250:251], v[194:195], v[22:23], v[250:251]
	v_pk_fma_f32 v[202:203], v[196:197], v[24:25], v[202:203]
	ds_read_b128 v[182:185], v57 offset:6288
	s_waitcnt lgkmcnt(10)
	v_pk_fma_f32 v[246:247], v[198:199], v[2:3], 0 op_sel_hi:[1,1,0]
	v_pk_fma_f32 v[248:249], v[200:201], v[4:5], 0 op_sel_hi:[1,1,0]
	ds_read_b128 v[186:189], v57 offset:6304
	ds_read_b128 v[190:193], v57 offset:6320
	ds_read_b128 v[194:197], v57 offset:6336
	v_add_f32_e32 v250, v250, v251
	s_waitcnt lgkmcnt(12)
	v_pk_fma_f32 v[246:247], v[206:207], v[6:7], v[246:247]
	v_pk_fma_f32 v[248:249], v[208:209], v[8:9], v[248:249]
	v_add_f32_e32 v202, v202, v203
	s_waitcnt lgkmcnt(11)
	v_pk_fma_f32 v[246:247], v[210:211], v[10:11], v[246:247]
	v_pk_fma_f32 v[248:249], v[212:213], v[12:13], v[248:249]
	v_mad_u32_u24 v61, v55, 23, v51
	ds_read_u16 v59, v61
	ds_read_b32 v204, v53 offset:92
	v_lshlrev_b32_e32 v221, 16, v221
	s_waitcnt lgkmcnt(12)
	v_pk_fma_f32 v[246:247], v[214:215], v[14:15], v[246:247]
	v_pk_fma_f32 v[248:249], v[216:217], v[16:17], v[248:249]
	ds_read_b128 v[198:201], v57 offset:6528
	v_add_f32_e32 v250, v250, v202
	s_waitcnt lgkmcnt(12)
	v_pk_fma_f32 v[246:247], v[238:239], v[18:19], v[246:247]
	v_pk_fma_f32 v[248:249], v[240:241], v[20:21], v[248:249]
	ds_read_b128 v[206:209], v57 offset:6544
	v_fma_f32 v23, v220, v221, -v250
	s_waitcnt lgkmcnt(12)
	v_pk_fma_f32 v[246:247], v[242:243], v[22:23], v[246:247]
	v_pk_fma_f32 v[248:249], v[244:245], v[24:25], v[248:249]
	ds_read_b128 v[210:213], v57 offset:6560
	s_waitcnt lgkmcnt(10)
	v_pk_fma_f32 v[250:251], v[174:175], v[2:3], 0 op_sel_hi:[1,1,0]
	v_pk_fma_f32 v[202:203], v[176:177], v[4:5], 0 op_sel_hi:[1,1,0]
	ds_read_b128 v[214:217], v57 offset:6576
	ds_read_b128 v[238:241], v57 offset:6592
	ds_read_b128 v[242:245], v57 offset:6608
	v_add_f32_e32 v246, v246, v247
	s_waitcnt lgkmcnt(12)
	v_pk_fma_f32 v[250:251], v[178:179], v[6:7], v[250:251]
	v_pk_fma_f32 v[202:203], v[180:181], v[8:9], v[202:203]
	v_add_f32_e32 v248, v248, v249
	s_waitcnt lgkmcnt(11)
	v_pk_fma_f32 v[250:251], v[182:183], v[10:11], v[250:251]
	v_pk_fma_f32 v[202:203], v[184:185], v[12:13], v[202:203]
	v_mad_u32_u24 v61, v55, 24, v51
	ds_read_u16 v221, v61
	ds_read_b32 v220, v53 offset:96
	v_lshlrev_b32_e32 v227, 16, v227
	s_waitcnt lgkmcnt(12)
	v_pk_fma_f32 v[250:251], v[186:187], v[14:15], v[250:251]
	v_pk_fma_f32 v[202:203], v[188:189], v[16:17], v[202:203]
	ds_read_b128 v[174:177], v57 offset:6800
	v_add_f32_e32 v246, v246, v248
	s_waitcnt lgkmcnt(12)
	v_pk_fma_f32 v[250:251], v[190:191], v[18:19], v[250:251]
	v_pk_fma_f32 v[202:203], v[192:193], v[20:21], v[202:203]
	ds_read_b128 v[178:181], v57 offset:6816
	v_fma_f32 v24, v226, v227, -v246
	s_waitcnt lgkmcnt(12)
	v_pk_fma_f32 v[250:251], v[194:195], v[22:23], v[250:251]
	v_pk_fma_f32 v[202:203], v[196:197], v[24:25], v[202:203]
	ds_read_b128 v[182:185], v57 offset:6832
	s_waitcnt lgkmcnt(10)
	v_pk_fma_f32 v[246:247], v[198:199], v[2:3], 0 op_sel_hi:[1,1,0]
	v_pk_fma_f32 v[248:249], v[200:201], v[4:5], 0 op_sel_hi:[1,1,0]
	ds_read_b128 v[186:189], v57 offset:6848
	ds_read_b128 v[190:193], v57 offset:6864
	ds_read_b128 v[194:197], v57 offset:6880
	v_add_f32_e32 v250, v250, v251
	s_waitcnt lgkmcnt(12)
	v_pk_fma_f32 v[246:247], v[206:207], v[6:7], v[246:247]
	v_pk_fma_f32 v[248:249], v[208:209], v[8:9], v[248:249]
	ds_read_b128 v[198:201], v57 offset:6896
	v_add_f32_e32 v202, v202, v203
	s_waitcnt lgkmcnt(12)
	v_pk_fma_f32 v[246:247], v[210:211], v[10:11], v[246:247]
	v_pk_fma_f32 v[248:249], v[212:213], v[12:13], v[248:249]
	v_lshlrev_b32_e32 v59, 16, v59
	s_waitcnt lgkmcnt(11)
	v_pk_fma_f32 v[246:247], v[214:215], v[14:15], v[246:247]
	v_pk_fma_f32 v[248:249], v[216:217], v[16:17], v[248:249]
	v_mad_u32_u24 v61, v55, 25, v51
	ds_read_u16 v227, v61
	ds_read_b32 v226, v53 offset:100
	v_add_f32_e32 v250, v250, v202
	s_waitcnt lgkmcnt(12)
	v_pk_fma_f32 v[246:247], v[238:239], v[18:19], v[246:247]
	v_pk_fma_f32 v[248:249], v[240:241], v[20:21], v[248:249]
	ds_read_b128 v[206:209], v57 offset:7072
	v_fma_f32 v25, v204, v59, -v250
	s_waitcnt lgkmcnt(12)
	v_pk_fma_f32 v[246:247], v[242:243], v[22:23], v[246:247]
	v_pk_fma_f32 v[248:249], v[244:245], v[24:25], v[248:249]
	ds_read_b128 v[210:213], v57 offset:7088
	s_waitcnt lgkmcnt(10)
	v_pk_fma_f32 v[250:251], v[174:175], v[2:3], 0 op_sel_hi:[1,1,0]
	v_pk_fma_f32 v[202:203], v[176:177], v[4:5], 0 op_sel_hi:[1,1,0]
	ds_read_b128 v[214:217], v57 offset:7104
	ds_read_b128 v[238:241], v57 offset:7120
	ds_read_b128 v[242:245], v57 offset:7136
	v_add_f32_e32 v246, v246, v247
	s_waitcnt lgkmcnt(12)
	v_pk_fma_f32 v[250:251], v[178:179], v[6:7], v[250:251]
	v_pk_fma_f32 v[202:203], v[180:181], v[8:9], v[202:203]
	ds_read_b128 v[174:177], v57 offset:7152
	v_add_f32_e32 v248, v248, v249
	s_waitcnt lgkmcnt(12)
	v_pk_fma_f32 v[250:251], v[182:183], v[10:11], v[250:251]
	v_pk_fma_f32 v[202:203], v[184:185], v[12:13], v[202:203]
	ds_read_b128 v[178:181], v57 offset:7168
	v_lshlrev_b32_e32 v221, 16, v221
	s_waitcnt lgkmcnt(12)
	v_pk_fma_f32 v[250:251], v[186:187], v[14:15], v[250:251]
	v_pk_fma_f32 v[202:203], v[188:189], v[16:17], v[202:203]
	v_add_f32_e32 v246, v246, v248
	s_waitcnt lgkmcnt(11)
	v_pk_fma_f32 v[250:251], v[190:191], v[18:19], v[250:251]
	v_pk_fma_f32 v[202:203], v[192:193], v[20:21], v[202:203]
	v_mad_u32_u24 v61, v55, 26, v51
	ds_read_u16 v59, v61
	ds_read_b32 v204, v53 offset:104
	v_fma_f32 v26, v220, v221, -v246
	s_waitcnt lgkmcnt(12)
	v_pk_fma_f32 v[250:251], v[194:195], v[22:23], v[250:251]
	v_pk_fma_f32 v[202:203], v[196:197], v[24:25], v[202:203]
	ds_read_b128 v[182:185], v57 offset:7344
	s_waitcnt lgkmcnt(12)
	v_pk_fma_f32 v[250:251], v[198:199], v[26:27], v[250:251]
	v_pk_fma_f32 v[202:203], v[200:201], v[28:29], v[202:203]
	ds_read_b128 v[186:189], v57 offset:7360
	s_waitcnt lgkmcnt(10)
	v_pk_fma_f32 v[246:247], v[206:207], v[2:3], 0 op_sel_hi:[1,1,0]
	v_pk_fma_f32 v[248:249], v[208:209], v[4:5], 0 op_sel_hi:[1,1,0]
	ds_read_b128 v[190:193], v57 offset:7376
	ds_read_b128 v[194:197], v57 offset:7392
	ds_read_b128 v[198:201], v57 offset:7408
	v_add_f32_e32 v250, v250, v251
	s_waitcnt lgkmcnt(12)
	v_pk_fma_f32 v[246:247], v[210:211], v[6:7], v[246:247]
	v_pk_fma_f32 v[248:249], v[212:213], v[8:9], v[248:249]
	ds_read_b128 v[206:209], v57 offset:7424
	v_add_f32_e32 v202, v202, v203
	s_waitcnt lgkmcnt(12)
	v_pk_fma_f32 v[246:247], v[214:215], v[10:11], v[246:247]
	v_pk_fma_f32 v[248:249], v[216:217], v[12:13], v[248:249]
	ds_read_b128 v[210:213], v57 offset:7440
	v_lshlrev_b32_e32 v227, 16, v227
	s_waitcnt lgkmcnt(12)
	v_pk_fma_f32 v[246:247], v[238:239], v[14:15], v[246:247]
	v_pk_fma_f32 v[248:249], v[240:241], v[16:17], v[248:249]
	v_add_f32_e32 v250, v250, v202
	s_waitcnt lgkmcnt(11)
	v_pk_fma_f32 v[246:247], v[242:243], v[18:19], v[246:247]
	v_pk_fma_f32 v[248:249], v[244:245], v[20:21], v[248:249]
	v_mad_u32_u24 v61, v55, 27, v51
	ds_read_u16 v221, v61
	ds_read_b32 v220, v53 offset:108
	v_fma_f32 v27, v226, v227, -v250
	s_waitcnt lgkmcnt(12)
	v_pk_fma_f32 v[246:247], v[174:175], v[22:23], v[246:247]
	v_pk_fma_f32 v[248:249], v[176:177], v[24:25], v[248:249]
	ds_read_b128 v[214:217], v57 offset:7616
	s_waitcnt lgkmcnt(12)
	v_pk_fma_f32 v[246:247], v[178:179], v[26:27], v[246:247]
	v_pk_fma_f32 v[248:249], v[180:181], v[28:29], v[248:249]
	ds_read_b128 v[238:241], v57 offset:7632
	s_waitcnt lgkmcnt(10)
	v_pk_fma_f32 v[250:251], v[182:183], v[2:3], 0 op_sel_hi:[1,1,0]
	v_pk_fma_f32 v[202:203], v[184:185], v[4:5], 0 op_sel_hi:[1,1,0]
	ds_read_b128 v[242:245], v57 offset:7648
	ds_read_b128 v[174:177], v57 offset:7664
	ds_read_b128 v[178:181], v57 offset:7680
	v_add_f32_e32 v246, v246, v247
	s_waitcnt lgkmcnt(12)
	v_pk_fma_f32 v[250:251], v[186:187], v[6:7], v[250:251]
	v_pk_fma_f32 v[202:203], v[188:189], v[8:9], v[202:203]
	ds_read_b128 v[182:185], v57 offset:7696
	v_add_f32_e32 v248, v248, v249
	s_waitcnt lgkmcnt(12)
	v_pk_fma_f32 v[250:251], v[190:191], v[10:11], v[250:251]
	v_pk_fma_f32 v[202:203], v[192:193], v[12:13], v[202:203]
	ds_read_b128 v[186:189], v57 offset:7712
	v_lshlrev_b32_e32 v59, 16, v59
	s_waitcnt lgkmcnt(12)
	v_pk_fma_f32 v[250:251], v[194:195], v[14:15], v[250:251]
	v_pk_fma_f32 v[202:203], v[196:197], v[16:17], v[202:203]
	v_add_f32_e32 v246, v246, v248
	s_waitcnt lgkmcnt(11)
	v_pk_fma_f32 v[250:251], v[198:199], v[18:19], v[250:251]
	v_pk_fma_f32 v[202:203], v[200:201], v[20:21], v[202:203]
	v_mad_u32_u24 v61, v55, 28, v51
	ds_read_u16 v227, v61
	ds_read_b32 v226, v53 offset:112
	v_fma_f32 v28, v204, v59, -v246
	s_waitcnt lgkmcnt(12)
	v_pk_fma_f32 v[250:251], v[206:207], v[22:23], v[250:251]
	v_pk_fma_f32 v[202:203], v[208:209], v[24:25], v[202:203]
	ds_read_b128 v[190:193], v57 offset:7888
	s_waitcnt lgkmcnt(12)
	v_pk_fma_f32 v[250:251], v[210:211], v[26:27], v[250:251]
	v_pk_fma_f32 v[202:203], v[212:213], v[28:29], v[202:203]
	ds_read_b128 v[194:197], v57 offset:7904
	s_waitcnt lgkmcnt(10)
	v_pk_fma_f32 v[246:247], v[214:215], v[2:3], 0 op_sel_hi:[1,1,0]
	v_pk_fma_f32 v[248:249], v[216:217], v[4:5], 0 op_sel_hi:[1,1,0]
	ds_read_b128 v[198:201], v57 offset:7920
	ds_read_b128 v[206:209], v57 offset:7936
	ds_read_b128 v[210:213], v57 offset:7952
	v_add_f32_e32 v250, v250, v251
	s_waitcnt lgkmcnt(12)
	v_pk_fma_f32 v[246:247], v[238:239], v[6:7], v[246:247]
	v_pk_fma_f32 v[248:249], v[240:241], v[8:9], v[248:249]
	ds_read_b128 v[214:217], v57 offset:7968
	v_add_f32_e32 v202, v202, v203
	s_waitcnt lgkmcnt(12)
	v_pk_fma_f32 v[246:247], v[242:243], v[10:11], v[246:247]
	v_pk_fma_f32 v[248:249], v[244:245], v[12:13], v[248:249]
	ds_read_b128 v[238:241], v57 offset:7984
	v_lshlrev_b32_e32 v221, 16, v221
	s_waitcnt lgkmcnt(12)
	v_pk_fma_f32 v[246:247], v[174:175], v[14:15], v[246:247]
	v_pk_fma_f32 v[248:249], v[176:177], v[16:17], v[248:249]
	ds_read_b128 v[242:245], v57 offset:8000
	v_add_f32_e32 v250, v250, v202
	s_waitcnt lgkmcnt(12)
	v_pk_fma_f32 v[246:247], v[178:179], v[18:19], v[246:247]
	v_pk_fma_f32 v[248:249], v[180:181], v[20:21], v[248:249]
	v_fma_f32 v29, v220, v221, -v250
	s_waitcnt lgkmcnt(11)
	v_pk_fma_f32 v[246:247], v[182:183], v[22:23], v[246:247]
	v_pk_fma_f32 v[248:249], v[184:185], v[24:25], v[248:249]
	v_mad_u32_u24 v61, v55, 29, v51
	ds_read_u16 v59, v61
	ds_read_b32 v204, v53 offset:116
	s_waitcnt lgkmcnt(12)
	v_pk_fma_f32 v[246:247], v[186:187], v[26:27], v[246:247]
	v_pk_fma_f32 v[248:249], v[188:189], v[28:29], v[248:249]
	ds_read_b128 v[174:177], v57 offset:8160
	s_waitcnt lgkmcnt(10)
	v_pk_fma_f32 v[250:251], v[190:191], v[2:3], 0 op_sel_hi:[1,1,0]
	v_pk_fma_f32 v[202:203], v[192:193], v[4:5], 0 op_sel_hi:[1,1,0]
	ds_read_b128 v[178:181], v57 offset:8176
	ds_read_b128 v[182:185], v57 offset:8192
	ds_read_b128 v[186:189], v57 offset:8208
	v_add_f32_e32 v246, v246, v247
	s_waitcnt lgkmcnt(12)
	v_pk_fma_f32 v[250:251], v[194:195], v[6:7], v[250:251]
	v_pk_fma_f32 v[202:203], v[196:197], v[8:9], v[202:203]
	ds_read_b128 v[190:193], v57 offset:8224
	v_add_f32_e32 v248, v248, v249
	s_waitcnt lgkmcnt(12)
	v_pk_fma_f32 v[250:251], v[198:199], v[10:11], v[250:251]
	v_pk_fma_f32 v[202:203], v[200:201], v[12:13], v[202:203]
	ds_read_b128 v[194:197], v57 offset:8240
	v_lshlrev_b32_e32 v227, 16, v227
	s_waitcnt lgkmcnt(12)
	v_pk_fma_f32 v[250:251], v[206:207], v[14:15], v[250:251]
	v_pk_fma_f32 v[202:203], v[208:209], v[16:17], v[202:203]
	ds_read_b128 v[198:201], v57 offset:8256
	v_add_f32_e32 v246, v246, v248
	s_waitcnt lgkmcnt(12)
	v_pk_fma_f32 v[250:251], v[210:211], v[18:19], v[250:251]
	v_pk_fma_f32 v[202:203], v[212:213], v[20:21], v[202:203]
	ds_read_b128 v[206:209], v57 offset:8272
	v_fma_f32 v30, v226, v227, -v246
	s_waitcnt lgkmcnt(12)
	v_pk_fma_f32 v[250:251], v[214:215], v[22:23], v[250:251]
	v_pk_fma_f32 v[202:203], v[216:217], v[24:25], v[202:203]
	s_waitcnt lgkmcnt(11)
	v_pk_fma_f32 v[250:251], v[238:239], v[26:27], v[250:251]
	v_pk_fma_f32 v[202:203], v[240:241], v[28:29], v[202:203]
	v_mad_u32_u24 v61, v55, 30, v51
	ds_read_u16 v221, v61
	ds_read_b32 v220, v53 offset:120
	s_waitcnt lgkmcnt(12)
	v_pk_fma_f32 v[250:251], v[242:243], v[30:31], v[250:251]
	v_pk_fma_f32 v[202:203], v[244:245], v[32:33], v[202:203]
	ds_read_b128 v[210:213], v57 offset:8432
	s_waitcnt lgkmcnt(10)
	v_pk_fma_f32 v[246:247], v[174:175], v[2:3], 0 op_sel_hi:[1,1,0]
	v_pk_fma_f32 v[248:249], v[176:177], v[4:5], 0 op_sel_hi:[1,1,0]
	ds_read_b128 v[214:217], v57 offset:8448
	ds_read_b128 v[238:241], v57 offset:8464
	ds_read_b128 v[242:245], v57 offset:8480
	v_add_f32_e32 v250, v250, v251
	s_waitcnt lgkmcnt(12)
	v_pk_fma_f32 v[246:247], v[178:179], v[6:7], v[246:247]
	v_pk_fma_f32 v[248:249], v[180:181], v[8:9], v[248:249]
	ds_read_b128 v[174:177], v57 offset:8496
	v_add_f32_e32 v202, v202, v203
	s_waitcnt lgkmcnt(12)
	v_pk_fma_f32 v[246:247], v[182:183], v[10:11], v[246:247]
	v_pk_fma_f32 v[248:249], v[184:185], v[12:13], v[248:249]
	ds_read_b128 v[178:181], v57 offset:8512
	v_lshlrev_b32_e32 v59, 16, v59
	s_waitcnt lgkmcnt(12)
	v_pk_fma_f32 v[246:247], v[186:187], v[14:15], v[246:247]
	v_pk_fma_f32 v[248:249], v[188:189], v[16:17], v[248:249]
	ds_read_b128 v[182:185], v57 offset:8528
	v_add_f32_e32 v250, v250, v202
	s_waitcnt lgkmcnt(12)
	v_pk_fma_f32 v[246:247], v[190:191], v[18:19], v[246:247]
	v_pk_fma_f32 v[248:249], v[192:193], v[20:21], v[248:249]
	ds_read_b128 v[186:189], v57 offset:8544
	v_fma_f32 v31, v204, v59, -v250
	s_waitcnt lgkmcnt(12)
	v_pk_fma_f32 v[246:247], v[194:195], v[22:23], v[246:247]
	v_pk_fma_f32 v[248:249], v[196:197], v[24:25], v[248:249]
	s_waitcnt lgkmcnt(11)
	v_pk_fma_f32 v[246:247], v[198:199], v[26:27], v[246:247]
	v_pk_fma_f32 v[248:249], v[200:201], v[28:29], v[248:249]
	v_mad_u32_u24 v61, v55, 31, v51
	ds_read_u16 v227, v61
	ds_read_b32 v226, v53 offset:124
	s_waitcnt lgkmcnt(12)
	v_pk_fma_f32 v[246:247], v[206:207], v[30:31], v[246:247]
	v_pk_fma_f32 v[248:249], v[208:209], v[32:33], v[248:249]
	ds_read_b128 v[190:193], v57 offset:8704
	s_waitcnt lgkmcnt(10)
	v_pk_fma_f32 v[250:251], v[210:211], v[2:3], 0 op_sel_hi:[1,1,0]
	v_pk_fma_f32 v[202:203], v[212:213], v[4:5], 0 op_sel_hi:[1,1,0]
	ds_read_b128 v[194:197], v57 offset:8720
	ds_read_b128 v[198:201], v57 offset:8736
	ds_read_b128 v[206:209], v57 offset:8752
	v_add_f32_e32 v246, v246, v247
	s_waitcnt lgkmcnt(12)
	v_pk_fma_f32 v[250:251], v[214:215], v[6:7], v[250:251]
	v_pk_fma_f32 v[202:203], v[216:217], v[8:9], v[202:203]
	ds_read_b128 v[210:213], v57 offset:8768
	v_add_f32_e32 v248, v248, v249
	s_waitcnt lgkmcnt(12)
	v_pk_fma_f32 v[250:251], v[238:239], v[10:11], v[250:251]
	v_pk_fma_f32 v[202:203], v[240:241], v[12:13], v[202:203]
	ds_read_b128 v[214:217], v57 offset:8784
	v_lshlrev_b32_e32 v221, 16, v221
	s_waitcnt lgkmcnt(12)
	v_pk_fma_f32 v[250:251], v[242:243], v[14:15], v[250:251]
	v_pk_fma_f32 v[202:203], v[244:245], v[16:17], v[202:203]
	ds_read_b128 v[238:241], v57 offset:8800
	v_add_f32_e32 v246, v246, v248
	s_waitcnt lgkmcnt(12)
	v_pk_fma_f32 v[250:251], v[174:175], v[18:19], v[250:251]
	v_pk_fma_f32 v[202:203], v[176:177], v[20:21], v[202:203]
	ds_read_b128 v[242:245], v57 offset:8816
	v_fma_f32 v32, v220, v221, -v246
	s_waitcnt lgkmcnt(12)
	v_pk_fma_f32 v[250:251], v[178:179], v[22:23], v[250:251]
	v_pk_fma_f32 v[202:203], v[180:181], v[24:25], v[202:203]
	s_waitcnt lgkmcnt(11)
	v_pk_fma_f32 v[250:251], v[182:183], v[26:27], v[250:251]
	v_pk_fma_f32 v[202:203], v[184:185], v[28:29], v[202:203]
	v_mad_u32_u24 v61, v55, 32, v51
	ds_read_u16 v59, v61
	ds_read_b32 v204, v53 offset:128
	s_waitcnt lgkmcnt(12)
	v_pk_fma_f32 v[250:251], v[186:187], v[30:31], v[250:251]
	v_pk_fma_f32 v[202:203], v[188:189], v[32:33], v[202:203]
	ds_read_b128 v[174:177], v57 offset:8976
	s_waitcnt lgkmcnt(10)
	v_pk_fma_f32 v[246:247], v[190:191], v[2:3], 0 op_sel_hi:[1,1,0]
	v_pk_fma_f32 v[248:249], v[192:193], v[4:5], 0 op_sel_hi:[1,1,0]
	ds_read_b128 v[178:181], v57 offset:8992
	ds_read_b128 v[182:185], v57 offset:9008
	ds_read_b128 v[186:189], v57 offset:9024
	v_add_f32_e32 v250, v250, v251
	s_waitcnt lgkmcnt(12)
	v_pk_fma_f32 v[246:247], v[194:195], v[6:7], v[246:247]
	v_pk_fma_f32 v[248:249], v[196:197], v[8:9], v[248:249]
	ds_read_b128 v[190:193], v57 offset:9040
	v_add_f32_e32 v202, v202, v203
	s_waitcnt lgkmcnt(12)
	v_pk_fma_f32 v[246:247], v[198:199], v[10:11], v[246:247]
	v_pk_fma_f32 v[248:249], v[200:201], v[12:13], v[248:249]
	ds_read_b128 v[194:197], v57 offset:9056
	v_lshlrev_b32_e32 v227, 16, v227
	s_waitcnt lgkmcnt(12)
	v_pk_fma_f32 v[246:247], v[206:207], v[14:15], v[246:247]
	v_pk_fma_f32 v[248:249], v[208:209], v[16:17], v[248:249]
	ds_read_b128 v[198:201], v57 offset:9072
	v_add_f32_e32 v250, v250, v202
	s_waitcnt lgkmcnt(12)
	v_pk_fma_f32 v[246:247], v[210:211], v[18:19], v[246:247]
	v_pk_fma_f32 v[248:249], v[212:213], v[20:21], v[248:249]
	ds_read_b128 v[206:209], v57 offset:9088
	v_fma_f32 v33, v226, v227, -v250
	s_waitcnt lgkmcnt(12)
	v_pk_fma_f32 v[246:247], v[214:215], v[22:23], v[246:247]
	v_pk_fma_f32 v[248:249], v[216:217], v[24:25], v[248:249]
	ds_read_b128 v[210:213], v57 offset:9104
	s_waitcnt lgkmcnt(12)
	v_pk_fma_f32 v[246:247], v[238:239], v[26:27], v[246:247]
	v_pk_fma_f32 v[248:249], v[240:241], v[28:29], v[248:249]
	s_waitcnt lgkmcnt(11)
	v_pk_fma_f32 v[246:247], v[242:243], v[30:31], v[246:247]
	v_pk_fma_f32 v[248:249], v[244:245], v[32:33], v[248:249]
	v_mad_u32_u24 v61, v55, 33, v51
	ds_read_u16 v221, v61
	ds_read_b32 v220, v53 offset:132
	s_waitcnt lgkmcnt(10)
	v_pk_fma_f32 v[250:251], v[174:175], v[2:3], 0 op_sel_hi:[1,1,0]
	v_pk_fma_f32 v[202:203], v[176:177], v[4:5], 0 op_sel_hi:[1,1,0]
	ds_read_b128 v[214:217], v57 offset:9248
	ds_read_b128 v[238:241], v57 offset:9264
	ds_read_b128 v[242:245], v57 offset:9280
	v_add_f32_e32 v246, v246, v247
	s_waitcnt lgkmcnt(12)
	v_pk_fma_f32 v[250:251], v[178:179], v[6:7], v[250:251]
	v_pk_fma_f32 v[202:203], v[180:181], v[8:9], v[202:203]
	ds_read_b128 v[174:177], v57 offset:9296
	v_add_f32_e32 v248, v248, v249
	s_waitcnt lgkmcnt(12)
	v_pk_fma_f32 v[250:251], v[182:183], v[10:11], v[250:251]
	v_pk_fma_f32 v[202:203], v[184:185], v[12:13], v[202:203]
	ds_read_b128 v[178:181], v57 offset:9312
	v_lshlrev_b32_e32 v59, 16, v59
	s_waitcnt lgkmcnt(12)
	v_pk_fma_f32 v[250:251], v[186:187], v[14:15], v[250:251]
	v_pk_fma_f32 v[202:203], v[188:189], v[16:17], v[202:203]
	ds_read_b128 v[182:185], v57 offset:9328
	v_add_f32_e32 v246, v246, v248
	s_waitcnt lgkmcnt(12)
	v_pk_fma_f32 v[250:251], v[190:191], v[18:19], v[250:251]
	v_pk_fma_f32 v[202:203], v[192:193], v[20:21], v[202:203]
	ds_read_b128 v[186:189], v57 offset:9344
	v_fma_f32 v34, v204, v59, -v246
	s_waitcnt lgkmcnt(12)
	v_pk_fma_f32 v[250:251], v[194:195], v[22:23], v[250:251]
	v_pk_fma_f32 v[202:203], v[196:197], v[24:25], v[202:203]
	ds_read_b128 v[190:193], v57 offset:9360
	s_waitcnt lgkmcnt(12)
	v_pk_fma_f32 v[250:251], v[198:199], v[26:27], v[250:251]
	v_pk_fma_f32 v[202:203], v[200:201], v[28:29], v[202:203]
	ds_read_b128 v[194:197], v57 offset:9376
	s_waitcnt lgkmcnt(12)
	v_pk_fma_f32 v[250:251], v[206:207], v[30:31], v[250:251]
	v_pk_fma_f32 v[202:203], v[208:209], v[32:33], v[202:203]
	s_waitcnt lgkmcnt(11)
	v_pk_fma_f32 v[250:251], v[210:211], v[34:35], v[250:251]
	v_pk_fma_f32 v[202:203], v[212:213], v[36:37], v[202:203]
	v_mad_u32_u24 v61, v55, 34, v51
	ds_read_u16 v227, v61
	ds_read_b32 v226, v53 offset:136
	s_waitcnt lgkmcnt(10)
	v_pk_fma_f32 v[246:247], v[214:215], v[2:3], 0 op_sel_hi:[1,1,0]
	v_pk_fma_f32 v[248:249], v[216:217], v[4:5], 0 op_sel_hi:[1,1,0]
	ds_read_b128 v[198:201], v57 offset:9520
	ds_read_b128 v[206:209], v57 offset:9536
	ds_read_b128 v[210:213], v57 offset:9552
	v_add_f32_e32 v250, v250, v251
	s_waitcnt lgkmcnt(12)
	v_pk_fma_f32 v[246:247], v[238:239], v[6:7], v[246:247]
	v_pk_fma_f32 v[248:249], v[240:241], v[8:9], v[248:249]
	ds_read_b128 v[214:217], v57 offset:9568
	v_add_f32_e32 v202, v202, v203
	s_waitcnt lgkmcnt(12)
	v_pk_fma_f32 v[246:247], v[242:243], v[10:11], v[246:247]
	v_pk_fma_f32 v[248:249], v[244:245], v[12:13], v[248:249]
	ds_read_b128 v[238:241], v57 offset:9584
	v_lshlrev_b32_e32 v221, 16, v221
	s_waitcnt lgkmcnt(12)
	v_pk_fma_f32 v[246:247], v[174:175], v[14:15], v[246:247]
	v_pk_fma_f32 v[248:249], v[176:177], v[16:17], v[248:249]
	ds_read_b128 v[242:245], v57 offset:9600
	v_add_f32_e32 v250, v250, v202
	s_waitcnt lgkmcnt(12)
	v_pk_fma_f32 v[246:247], v[178:179], v[18:19], v[246:247]
	v_pk_fma_f32 v[248:249], v[180:181], v[20:21], v[248:249]
	ds_read_b128 v[174:177], v57 offset:9616
	v_fma_f32 v35, v220, v221, -v250
	s_waitcnt lgkmcnt(12)
	v_pk_fma_f32 v[246:247], v[182:183], v[22:23], v[246:247]
	v_pk_fma_f32 v[248:249], v[184:185], v[24:25], v[248:249]
	ds_read_b128 v[178:181], v57 offset:9632
	s_waitcnt lgkmcnt(12)
	v_pk_fma_f32 v[246:247], v[186:187], v[26:27], v[246:247]
	v_pk_fma_f32 v[248:249], v[188:189], v[28:29], v[248:249]
	ds_read_b128 v[182:185], v57 offset:9648
	s_waitcnt lgkmcnt(12)
	v_pk_fma_f32 v[246:247], v[190:191], v[30:31], v[246:247]
	v_pk_fma_f32 v[248:249], v[192:193], v[32:33], v[248:249]
	s_waitcnt lgkmcnt(11)
	v_pk_fma_f32 v[246:247], v[194:195], v[34:35], v[246:247]
	v_pk_fma_f32 v[248:249], v[196:197], v[36:37], v[248:249]
	v_mad_u32_u24 v61, v55, 35, v51
	ds_read_u16 v59, v61
	ds_read_b32 v204, v53 offset:140
	s_waitcnt lgkmcnt(10)
	v_pk_fma_f32 v[250:251], v[198:199], v[2:3], 0 op_sel_hi:[1,1,0]
	v_pk_fma_f32 v[202:203], v[200:201], v[4:5], 0 op_sel_hi:[1,1,0]
	ds_read_b128 v[186:189], v57 offset:9792
	ds_read_b128 v[190:193], v57 offset:9808
	ds_read_b128 v[194:197], v57 offset:9824
	v_add_f32_e32 v246, v246, v247
	s_waitcnt lgkmcnt(12)
	v_pk_fma_f32 v[250:251], v[206:207], v[6:7], v[250:251]
	v_pk_fma_f32 v[202:203], v[208:209], v[8:9], v[202:203]
	ds_read_b128 v[198:201], v57 offset:9840
	v_add_f32_e32 v248, v248, v249
	s_waitcnt lgkmcnt(12)
	v_pk_fma_f32 v[250:251], v[210:211], v[10:11], v[250:251]
	v_pk_fma_f32 v[202:203], v[212:213], v[12:13], v[202:203]
	ds_read_b128 v[206:209], v57 offset:9856
	v_lshlrev_b32_e32 v227, 16, v227
	s_waitcnt lgkmcnt(12)
	v_pk_fma_f32 v[250:251], v[214:215], v[14:15], v[250:251]
	v_pk_fma_f32 v[202:203], v[216:217], v[16:17], v[202:203]
	ds_read_b128 v[210:213], v57 offset:9872
	v_add_f32_e32 v246, v246, v248
	s_waitcnt lgkmcnt(12)
	v_pk_fma_f32 v[250:251], v[238:239], v[18:19], v[250:251]
	v_pk_fma_f32 v[202:203], v[240:241], v[20:21], v[202:203]
	ds_read_b128 v[214:217], v57 offset:9888
	v_fma_f32 v36, v226, v227, -v246
	s_waitcnt lgkmcnt(12)
	v_pk_fma_f32 v[250:251], v[242:243], v[22:23], v[250:251]
	v_pk_fma_f32 v[202:203], v[244:245], v[24:25], v[202:203]
	ds_read_b128 v[238:241], v57 offset:9904
	s_waitcnt lgkmcnt(12)
	v_pk_fma_f32 v[250:251], v[174:175], v[26:27], v[250:251]
	v_pk_fma_f32 v[202:203], v[176:177], v[28:29], v[202:203]
	ds_read_b128 v[242:245], v57 offset:9920
	s_waitcnt lgkmcnt(12)
	v_pk_fma_f32 v[250:251], v[178:179], v[30:31], v[250:251]
	v_pk_fma_f32 v[202:203], v[180:181], v[32:33], v[202:203]
	s_waitcnt lgkmcnt(11)
	v_pk_fma_f32 v[250:251], v[182:183], v[34:35], v[250:251]
	v_pk_fma_f32 v[202:203], v[184:185], v[36:37], v[202:203]
	v_mad_u32_u24 v61, v55, 36, v51
	ds_read_u16 v221, v61
	ds_read_b32 v220, v53 offset:144
	s_waitcnt lgkmcnt(10)
	v_pk_fma_f32 v[246:247], v[186:187], v[2:3], 0 op_sel_hi:[1,1,0]
	v_pk_fma_f32 v[248:249], v[188:189], v[4:5], 0 op_sel_hi:[1,1,0]
	ds_read_b128 v[174:177], v57 offset:10064
	ds_read_b128 v[178:181], v57 offset:10080
	ds_read_b128 v[182:185], v57 offset:10096
	v_add_f32_e32 v250, v250, v251
	s_waitcnt lgkmcnt(12)
	v_pk_fma_f32 v[246:247], v[190:191], v[6:7], v[246:247]
	v_pk_fma_f32 v[248:249], v[192:193], v[8:9], v[248:249]
	ds_read_b128 v[186:189], v57 offset:10112
	v_add_f32_e32 v202, v202, v203
	s_waitcnt lgkmcnt(12)
	v_pk_fma_f32 v[246:247], v[194:195], v[10:11], v[246:247]
	v_pk_fma_f32 v[248:249], v[196:197], v[12:13], v[248:249]
	ds_read_b128 v[190:193], v57 offset:10128
	v_lshlrev_b32_e32 v59, 16, v59
	s_waitcnt lgkmcnt(12)
	v_pk_fma_f32 v[246:247], v[198:199], v[14:15], v[246:247]
	v_pk_fma_f32 v[248:249], v[200:201], v[16:17], v[248:249]
	ds_read_b128 v[194:197], v57 offset:10144
	v_add_f32_e32 v250, v250, v202
	s_waitcnt lgkmcnt(12)
	v_pk_fma_f32 v[246:247], v[206:207], v[18:19], v[246:247]
	v_pk_fma_f32 v[248:249], v[208:209], v[20:21], v[248:249]
	ds_read_b128 v[198:201], v57 offset:10160
	v_fma_f32 v37, v204, v59, -v250
	s_waitcnt lgkmcnt(12)
	v_pk_fma_f32 v[246:247], v[210:211], v[22:23], v[246:247]
	v_pk_fma_f32 v[248:249], v[212:213], v[24:25], v[248:249]
	ds_read_b128 v[206:209], v57 offset:10176
	s_waitcnt lgkmcnt(12)
	v_pk_fma_f32 v[246:247], v[214:215], v[26:27], v[246:247]
	v_pk_fma_f32 v[248:249], v[216:217], v[28:29], v[248:249]
	ds_read_b128 v[210:213], v57 offset:10192
	s_waitcnt lgkmcnt(12)
	v_pk_fma_f32 v[246:247], v[238:239], v[30:31], v[246:247]
	v_pk_fma_f32 v[248:249], v[240:241], v[32:33], v[248:249]
	ds_read_b128 v[214:217], v57 offset:10208
	s_waitcnt lgkmcnt(12)
	v_pk_fma_f32 v[246:247], v[242:243], v[34:35], v[246:247]
	v_pk_fma_f32 v[248:249], v[244:245], v[36:37], v[248:249]
	s_waitcnt lgkmcnt(9)
	v_pk_fma_f32 v[250:251], v[174:175], v[2:3], 0 op_sel_hi:[1,1,0]
	v_pk_fma_f32 v[202:203], v[176:177], v[4:5], 0 op_sel_hi:[1,1,0]
	v_mad_u32_u24 v61, v55, 37, v51
	ds_read_u16 v227, v61
	ds_read_b32 v226, v53 offset:148
	ds_read_b128 v[238:241], v57 offset:10336
	ds_read_b128 v[242:245], v57 offset:10352
	v_add_f32_e32 v246, v246, v247
	s_waitcnt lgkmcnt(12)
	v_pk_fma_f32 v[250:251], v[178:179], v[6:7], v[250:251]
	v_pk_fma_f32 v[202:203], v[180:181], v[8:9], v[202:203]
	ds_read_b128 v[174:177], v57 offset:10368
	v_add_f32_e32 v248, v248, v249
	s_waitcnt lgkmcnt(12)
	v_pk_fma_f32 v[250:251], v[182:183], v[10:11], v[250:251]
	v_pk_fma_f32 v[202:203], v[184:185], v[12:13], v[202:203]
	ds_read_b128 v[178:181], v57 offset:10384
	v_lshlrev_b32_e32 v221, 16, v221
	s_waitcnt lgkmcnt(12)
	v_pk_fma_f32 v[250:251], v[186:187], v[14:15], v[250:251]
	v_pk_fma_f32 v[202:203], v[188:189], v[16:17], v[202:203]
	ds_read_b128 v[182:185], v57 offset:10400
	v_add_f32_e32 v246, v246, v248
	s_waitcnt lgkmcnt(12)
	v_pk_fma_f32 v[250:251], v[190:191], v[18:19], v[250:251]
	v_pk_fma_f32 v[202:203], v[192:193], v[20:21], v[202:203]
	ds_read_b128 v[186:189], v57 offset:10416
	v_fma_f32 v86, v220, v221, -v246
	s_waitcnt lgkmcnt(12)
	v_pk_fma_f32 v[250:251], v[194:195], v[22:23], v[250:251]
	v_pk_fma_f32 v[202:203], v[196:197], v[24:25], v[202:203]
	ds_read_b128 v[190:193], v57 offset:10432
	s_waitcnt lgkmcnt(12)
	v_pk_fma_f32 v[250:251], v[198:199], v[26:27], v[250:251]
	v_pk_fma_f32 v[202:203], v[200:201], v[28:29], v[202:203]
	ds_read_b128 v[194:197], v57 offset:10448
	s_waitcnt lgkmcnt(12)
	v_pk_fma_f32 v[250:251], v[206:207], v[30:31], v[250:251]
	v_pk_fma_f32 v[202:203], v[208:209], v[32:33], v[202:203]
	ds_read_b128 v[198:201], v57 offset:10464
	s_waitcnt lgkmcnt(12)
	v_pk_fma_f32 v[250:251], v[210:211], v[34:35], v[250:251]
	v_pk_fma_f32 v[202:203], v[212:213], v[36:37], v[202:203]
	ds_read_b128 v[206:209], v57 offset:10480
	s_waitcnt lgkmcnt(12)
	v_pk_fma_f32 v[250:251], v[214:215], v[86:87], v[250:251]
	v_pk_fma_f32 v[202:203], v[216:217], v[88:89], v[202:203]
	s_waitcnt lgkmcnt(9)
	v_pk_fma_f32 v[246:247], v[238:239], v[2:3], 0 op_sel_hi:[1,1,0]
	v_pk_fma_f32 v[248:249], v[240:241], v[4:5], 0 op_sel_hi:[1,1,0]
	v_mad_u32_u24 v61, v55, 38, v51
	ds_read_u16 v59, v61
	ds_read_b32 v204, v53 offset:152
	ds_read_b128 v[210:213], v57 offset:10608
	ds_read_b128 v[214:217], v57 offset:10624
	v_add_f32_e32 v250, v250, v251
	s_waitcnt lgkmcnt(12)
	v_pk_fma_f32 v[246:247], v[242:243], v[6:7], v[246:247]
	v_pk_fma_f32 v[248:249], v[244:245], v[8:9], v[248:249]
	ds_read_b128 v[238:241], v57 offset:10640
	v_add_f32_e32 v202, v202, v203
	s_waitcnt lgkmcnt(12)
	v_pk_fma_f32 v[246:247], v[174:175], v[10:11], v[246:247]
	v_pk_fma_f32 v[248:249], v[176:177], v[12:13], v[248:249]
	ds_read_b128 v[242:245], v57 offset:10656
	v_lshlrev_b32_e32 v227, 16, v227
	s_waitcnt lgkmcnt(12)
	v_pk_fma_f32 v[246:247], v[178:179], v[14:15], v[246:247]
	v_pk_fma_f32 v[248:249], v[180:181], v[16:17], v[248:249]
	ds_read_b128 v[174:177], v57 offset:10672
	v_add_f32_e32 v250, v250, v202
	s_waitcnt lgkmcnt(12)
	v_pk_fma_f32 v[246:247], v[182:183], v[18:19], v[246:247]
	v_pk_fma_f32 v[248:249], v[184:185], v[20:21], v[248:249]
	ds_read_b128 v[178:181], v57 offset:10688
	v_fma_f32 v87, v226, v227, -v250
	s_waitcnt lgkmcnt(12)
	v_pk_fma_f32 v[246:247], v[186:187], v[22:23], v[246:247]
	v_pk_fma_f32 v[248:249], v[188:189], v[24:25], v[248:249]
	ds_read_b128 v[182:185], v57 offset:10704
	s_waitcnt lgkmcnt(12)
	v_pk_fma_f32 v[246:247], v[190:191], v[26:27], v[246:247]
	v_pk_fma_f32 v[248:249], v[192:193], v[28:29], v[248:249]
	ds_read_b128 v[186:189], v57 offset:10720
	s_waitcnt lgkmcnt(12)
	v_pk_fma_f32 v[246:247], v[194:195], v[30:31], v[246:247]
	v_pk_fma_f32 v[248:249], v[196:197], v[32:33], v[248:249]
	ds_read_b128 v[190:193], v57 offset:10736
	s_waitcnt lgkmcnt(12)
	v_pk_fma_f32 v[246:247], v[198:199], v[34:35], v[246:247]
	v_pk_fma_f32 v[248:249], v[200:201], v[36:37], v[248:249]
	ds_read_b128 v[194:197], v57 offset:10752
	s_waitcnt lgkmcnt(12)
	v_pk_fma_f32 v[246:247], v[206:207], v[86:87], v[246:247]
	v_pk_fma_f32 v[248:249], v[208:209], v[88:89], v[248:249]
	s_waitcnt lgkmcnt(9)
	v_pk_fma_f32 v[250:251], v[210:211], v[2:3], 0 op_sel_hi:[1,1,0]
	v_pk_fma_f32 v[202:203], v[212:213], v[4:5], 0 op_sel_hi:[1,1,0]
	v_mad_u32_u24 v61, v55, 39, v51
	ds_read_u16 v221, v61
	ds_read_b32 v220, v53 offset:156
	ds_read_b128 v[198:201], v57 offset:10880
	ds_read_b128 v[206:209], v57 offset:10896
	v_add_f32_e32 v246, v246, v247
	s_waitcnt lgkmcnt(12)
	v_pk_fma_f32 v[250:251], v[214:215], v[6:7], v[250:251]
	v_pk_fma_f32 v[202:203], v[216:217], v[8:9], v[202:203]
	ds_read_b128 v[210:213], v57 offset:10912
	v_add_f32_e32 v248, v248, v249
	s_waitcnt lgkmcnt(12)
	v_pk_fma_f32 v[250:251], v[238:239], v[10:11], v[250:251]
	v_pk_fma_f32 v[202:203], v[240:241], v[12:13], v[202:203]
	ds_read_b128 v[214:217], v57 offset:10928
	v_lshlrev_b32_e32 v59, 16, v59
	s_waitcnt lgkmcnt(12)
	v_pk_fma_f32 v[250:251], v[242:243], v[14:15], v[250:251]
	v_pk_fma_f32 v[202:203], v[244:245], v[16:17], v[202:203]
	ds_read_b128 v[238:241], v57 offset:10944
	v_add_f32_e32 v246, v246, v248
	s_waitcnt lgkmcnt(12)
	v_pk_fma_f32 v[250:251], v[174:175], v[18:19], v[250:251]
	v_pk_fma_f32 v[202:203], v[176:177], v[20:21], v[202:203]
	ds_read_b128 v[242:245], v57 offset:10960
	v_fma_f32 v88, v204, v59, -v246
	s_waitcnt lgkmcnt(12)
	v_pk_fma_f32 v[250:251], v[178:179], v[22:23], v[250:251]
	v_pk_fma_f32 v[202:203], v[180:181], v[24:25], v[202:203]
	ds_read_b128 v[174:177], v57 offset:10976
	s_waitcnt lgkmcnt(12)
	v_pk_fma_f32 v[250:251], v[182:183], v[26:27], v[250:251]
	v_pk_fma_f32 v[202:203], v[184:185], v[28:29], v[202:203]
	ds_read_b128 v[178:181], v57 offset:10992
	s_waitcnt lgkmcnt(12)
	v_pk_fma_f32 v[250:251], v[186:187], v[30:31], v[250:251]
	v_pk_fma_f32 v[202:203], v[188:189], v[32:33], v[202:203]
	ds_read_b128 v[182:185], v57 offset:11008
	s_waitcnt lgkmcnt(12)
	v_pk_fma_f32 v[250:251], v[190:191], v[34:35], v[250:251]
	v_pk_fma_f32 v[202:203], v[192:193], v[36:37], v[202:203]
	ds_read_b128 v[186:189], v57 offset:11024
	s_waitcnt lgkmcnt(12)
	v_pk_fma_f32 v[250:251], v[194:195], v[86:87], v[250:251]
	v_pk_fma_f32 v[202:203], v[196:197], v[88:89], v[202:203]
	s_waitcnt lgkmcnt(9)
	v_pk_fma_f32 v[246:247], v[198:199], v[2:3], 0 op_sel_hi:[1,1,0]
	v_pk_fma_f32 v[248:249], v[200:201], v[4:5], 0 op_sel_hi:[1,1,0]
	v_mad_u32_u24 v61, v55, 40, v51
	ds_read_u16 v227, v61
	ds_read_b32 v226, v53 offset:160
	ds_read_b128 v[190:193], v57 offset:11152
	ds_read_b128 v[194:197], v57 offset:11168
	v_add_f32_e32 v250, v250, v251
	s_waitcnt lgkmcnt(12)
	v_pk_fma_f32 v[246:247], v[206:207], v[6:7], v[246:247]
	v_pk_fma_f32 v[248:249], v[208:209], v[8:9], v[248:249]
	ds_read_b128 v[198:201], v57 offset:11184
	v_add_f32_e32 v202, v202, v203
	s_waitcnt lgkmcnt(12)
	v_pk_fma_f32 v[246:247], v[210:211], v[10:11], v[246:247]
	v_pk_fma_f32 v[248:249], v[212:213], v[12:13], v[248:249]
	ds_read_b128 v[206:209], v57 offset:11200
	v_lshlrev_b32_e32 v221, 16, v221
	s_waitcnt lgkmcnt(12)
	v_pk_fma_f32 v[246:247], v[214:215], v[14:15], v[246:247]
	v_pk_fma_f32 v[248:249], v[216:217], v[16:17], v[248:249]
	ds_read_b128 v[210:213], v57 offset:11216
	v_add_f32_e32 v250, v250, v202
	s_waitcnt lgkmcnt(12)
	v_pk_fma_f32 v[246:247], v[238:239], v[18:19], v[246:247]
	v_pk_fma_f32 v[248:249], v[240:241], v[20:21], v[248:249]
	ds_read_b128 v[214:217], v57 offset:11232
	v_fma_f32 v89, v220, v221, -v250
	s_waitcnt lgkmcnt(12)
	v_pk_fma_f32 v[246:247], v[242:243], v[22:23], v[246:247]
	v_pk_fma_f32 v[248:249], v[244:245], v[24:25], v[248:249]
	ds_read_b128 v[238:241], v57 offset:11248
	s_waitcnt lgkmcnt(12)
	v_pk_fma_f32 v[246:247], v[174:175], v[26:27], v[246:247]
	v_pk_fma_f32 v[248:249], v[176:177], v[28:29], v[248:249]
	ds_read_b128 v[242:245], v57 offset:11264
	s_waitcnt lgkmcnt(12)
	v_pk_fma_f32 v[246:247], v[178:179], v[30:31], v[246:247]
	v_pk_fma_f32 v[248:249], v[180:181], v[32:33], v[248:249]
	ds_read_b128 v[174:177], v57 offset:11280
	s_waitcnt lgkmcnt(12)
	v_pk_fma_f32 v[246:247], v[182:183], v[34:35], v[246:247]
	v_pk_fma_f32 v[248:249], v[184:185], v[36:37], v[248:249]
	ds_read_b128 v[178:181], v57 offset:11296
	s_waitcnt lgkmcnt(12)
	v_pk_fma_f32 v[246:247], v[186:187], v[86:87], v[246:247]
	v_pk_fma_f32 v[248:249], v[188:189], v[88:89], v[248:249]
	ds_read_b128 v[182:185], v57 offset:11312
	s_waitcnt lgkmcnt(10)
	v_pk_fma_f32 v[250:251], v[190:191], v[2:3], 0 op_sel_hi:[1,1,0]
	v_pk_fma_f32 v[202:203], v[192:193], v[4:5], 0 op_sel_hi:[1,1,0]
	v_mad_u32_u24 v61, v55, 41, v51
	ds_read_u16 v59, v61
	ds_read_b32 v204, v53 offset:164
	ds_read_b128 v[186:189], v57 offset:11424
	v_add_f32_e32 v246, v246, v247
	s_waitcnt lgkmcnt(12)
	v_pk_fma_f32 v[250:251], v[194:195], v[6:7], v[250:251]
	v_pk_fma_f32 v[202:203], v[196:197], v[8:9], v[202:203]
	ds_read_b128 v[190:193], v57 offset:11440
	v_add_f32_e32 v248, v248, v249
	s_waitcnt lgkmcnt(12)
	v_pk_fma_f32 v[250:251], v[198:199], v[10:11], v[250:251]
	v_pk_fma_f32 v[202:203], v[200:201], v[12:13], v[202:203]
	ds_read_b128 v[194:197], v57 offset:11456
	v_lshlrev_b32_e32 v227, 16, v227
	s_waitcnt lgkmcnt(12)
	v_pk_fma_f32 v[250:251], v[206:207], v[14:15], v[250:251]
	v_pk_fma_f32 v[202:203], v[208:209], v[16:17], v[202:203]
	ds_read_b128 v[198:201], v57 offset:11472
	v_add_f32_e32 v246, v246, v248
	s_waitcnt lgkmcnt(12)
	v_pk_fma_f32 v[250:251], v[210:211], v[18:19], v[250:251]
	v_pk_fma_f32 v[202:203], v[212:213], v[20:21], v[202:203]
	ds_read_b128 v[206:209], v57 offset:11488
	v_fma_f32 v90, v226, v227, -v246
	s_waitcnt lgkmcnt(12)
	v_pk_fma_f32 v[250:251], v[214:215], v[22:23], v[250:251]
	v_pk_fma_f32 v[202:203], v[216:217], v[24:25], v[202:203]
	ds_read_b128 v[210:213], v57 offset:11504
	s_waitcnt lgkmcnt(12)
	v_pk_fma_f32 v[250:251], v[238:239], v[26:27], v[250:251]
	v_pk_fma_f32 v[202:203], v[240:241], v[28:29], v[202:203]
	ds_read_b128 v[214:217], v57 offset:11520
	s_waitcnt lgkmcnt(12)
	v_pk_fma_f32 v[250:251], v[242:243], v[30:31], v[250:251]
	v_pk_fma_f32 v[202:203], v[244:245], v[32:33], v[202:203]
	ds_read_b128 v[238:241], v57 offset:11536
	s_waitcnt lgkmcnt(12)
	v_pk_fma_f32 v[250:251], v[174:175], v[34:35], v[250:251]
	v_pk_fma_f32 v[202:203], v[176:177], v[36:37], v[202:203]
	ds_read_b128 v[242:245], v57 offset:11552
	s_waitcnt lgkmcnt(12)
	v_pk_fma_f32 v[250:251], v[178:179], v[86:87], v[250:251]
	v_pk_fma_f32 v[202:203], v[180:181], v[88:89], v[202:203]
	ds_read_b128 v[174:177], v57 offset:11568
	s_waitcnt lgkmcnt(12)
	v_pk_fma_f32 v[250:251], v[182:183], v[90:91], v[250:251]
	v_pk_fma_f32 v[202:203], v[184:185], v[92:93], v[202:203]
	ds_read_b128 v[178:181], v57 offset:11584
	s_waitcnt lgkmcnt(10)
	v_pk_fma_f32 v[246:247], v[186:187], v[2:3], 0 op_sel_hi:[1,1,0]
	v_pk_fma_f32 v[248:249], v[188:189], v[4:5], 0 op_sel_hi:[1,1,0]
	v_mad_u32_u24 v61, v55, 42, v51
	ds_read_u16 v221, v61
	ds_read_b32 v220, v53 offset:168
	ds_read_b128 v[182:185], v57 offset:11696
	v_add_f32_e32 v250, v250, v251
	s_waitcnt lgkmcnt(12)
	v_pk_fma_f32 v[246:247], v[190:191], v[6:7], v[246:247]
	v_pk_fma_f32 v[248:249], v[192:193], v[8:9], v[248:249]
	ds_read_b128 v[186:189], v57 offset:11712
	v_add_f32_e32 v202, v202, v203
	s_waitcnt lgkmcnt(12)
	v_pk_fma_f32 v[246:247], v[194:195], v[10:11], v[246:247]
	v_pk_fma_f32 v[248:249], v[196:197], v[12:13], v[248:249]
	ds_read_b128 v[190:193], v57 offset:11728
	v_lshlrev_b32_e32 v59, 16, v59
	s_waitcnt lgkmcnt(12)
	v_pk_fma_f32 v[246:247], v[198:199], v[14:15], v[246:247]
	v_pk_fma_f32 v[248:249], v[200:201], v[16:17], v[248:249]
	ds_read_b128 v[194:197], v57 offset:11744
	v_add_f32_e32 v250, v250, v202
	s_waitcnt lgkmcnt(12)
	v_pk_fma_f32 v[246:247], v[206:207], v[18:19], v[246:247]
	v_pk_fma_f32 v[248:249], v[208:209], v[20:21], v[248:249]
	ds_read_b128 v[198:201], v57 offset:11760
	v_fma_f32 v91, v204, v59, -v250
	s_waitcnt lgkmcnt(12)
	v_pk_fma_f32 v[246:247], v[210:211], v[22:23], v[246:247]
	v_pk_fma_f32 v[248:249], v[212:213], v[24:25], v[248:249]
	ds_read_b128 v[206:209], v57 offset:11776
	s_waitcnt lgkmcnt(12)
	v_pk_fma_f32 v[246:247], v[214:215], v[26:27], v[246:247]
	v_pk_fma_f32 v[248:249], v[216:217], v[28:29], v[248:249]
	ds_read_b128 v[210:213], v57 offset:11792
	s_waitcnt lgkmcnt(12)
	v_pk_fma_f32 v[246:247], v[238:239], v[30:31], v[246:247]
	v_pk_fma_f32 v[248:249], v[240:241], v[32:33], v[248:249]
	ds_read_b128 v[214:217], v57 offset:11808
	s_waitcnt lgkmcnt(12)
	v_pk_fma_f32 v[246:247], v[242:243], v[34:35], v[246:247]
	v_pk_fma_f32 v[248:249], v[244:245], v[36:37], v[248:249]
	ds_read_b128 v[238:241], v57 offset:11824
	s_waitcnt lgkmcnt(12)
	v_pk_fma_f32 v[246:247], v[174:175], v[86:87], v[246:247]
	v_pk_fma_f32 v[248:249], v[176:177], v[88:89], v[248:249]
	ds_read_b128 v[242:245], v57 offset:11840
	s_waitcnt lgkmcnt(12)
	v_pk_fma_f32 v[246:247], v[178:179], v[90:91], v[246:247]
	v_pk_fma_f32 v[248:249], v[180:181], v[92:93], v[248:249]
	ds_read_b128 v[174:177], v57 offset:11856
	s_waitcnt lgkmcnt(10)
	v_pk_fma_f32 v[250:251], v[182:183], v[2:3], 0 op_sel_hi:[1,1,0]
	v_pk_fma_f32 v[202:203], v[184:185], v[4:5], 0 op_sel_hi:[1,1,0]
	v_mad_u32_u24 v61, v55, 43, v51
	ds_read_u16 v227, v61
	ds_read_b32 v226, v53 offset:172
	ds_read_b128 v[178:181], v57 offset:11968
	v_add_f32_e32 v246, v246, v247
	s_waitcnt lgkmcnt(12)
	v_pk_fma_f32 v[250:251], v[186:187], v[6:7], v[250:251]
	v_pk_fma_f32 v[202:203], v[188:189], v[8:9], v[202:203]
	ds_read_b128 v[182:185], v57 offset:11984
	v_add_f32_e32 v248, v248, v249
	s_waitcnt lgkmcnt(12)
	v_pk_fma_f32 v[250:251], v[190:191], v[10:11], v[250:251]
	v_pk_fma_f32 v[202:203], v[192:193], v[12:13], v[202:203]
	ds_read_b128 v[186:189], v57 offset:12000
	v_lshlrev_b32_e32 v221, 16, v221
	s_waitcnt lgkmcnt(12)
	v_pk_fma_f32 v[250:251], v[194:195], v[14:15], v[250:251]
	v_pk_fma_f32 v[202:203], v[196:197], v[16:17], v[202:203]
	ds_read_b128 v[190:193], v57 offset:12016
	v_add_f32_e32 v246, v246, v248
	s_waitcnt lgkmcnt(12)
	v_pk_fma_f32 v[250:251], v[198:199], v[18:19], v[250:251]
	v_pk_fma_f32 v[202:203], v[200:201], v[20:21], v[202:203]
	ds_read_b128 v[194:197], v57 offset:12032
	v_fma_f32 v92, v220, v221, -v246
	s_waitcnt lgkmcnt(12)
	v_pk_fma_f32 v[250:251], v[206:207], v[22:23], v[250:251]
	v_pk_fma_f32 v[202:203], v[208:209], v[24:25], v[202:203]
	ds_read_b128 v[198:201], v57 offset:12048
	s_waitcnt lgkmcnt(12)
	v_pk_fma_f32 v[250:251], v[210:211], v[26:27], v[250:251]
	v_pk_fma_f32 v[202:203], v[212:213], v[28:29], v[202:203]
	ds_read_b128 v[206:209], v57 offset:12064
	s_waitcnt lgkmcnt(12)
	v_pk_fma_f32 v[250:251], v[214:215], v[30:31], v[250:251]
	v_pk_fma_f32 v[202:203], v[216:217], v[32:33], v[202:203]
	ds_read_b128 v[210:213], v57 offset:12080
	s_waitcnt lgkmcnt(12)
	v_pk_fma_f32 v[250:251], v[238:239], v[34:35], v[250:251]
	v_pk_fma_f32 v[202:203], v[240:241], v[36:37], v[202:203]
	ds_read_b128 v[214:217], v57 offset:12096
	s_waitcnt lgkmcnt(12)
	v_pk_fma_f32 v[250:251], v[242:243], v[86:87], v[250:251]
	v_pk_fma_f32 v[202:203], v[244:245], v[88:89], v[202:203]
	ds_read_b128 v[238:241], v57 offset:12112
	s_waitcnt lgkmcnt(12)
	v_pk_fma_f32 v[250:251], v[174:175], v[90:91], v[250:251]
	v_pk_fma_f32 v[202:203], v[176:177], v[92:93], v[202:203]
	ds_read_b128 v[242:245], v57 offset:12128
	s_waitcnt lgkmcnt(10)
	v_pk_fma_f32 v[246:247], v[178:179], v[2:3], 0 op_sel_hi:[1,1,0]
	v_pk_fma_f32 v[248:249], v[180:181], v[4:5], 0 op_sel_hi:[1,1,0]
	v_mad_u32_u24 v61, v55, 44, v51
	ds_read_u16 v59, v61
	ds_read_b32 v204, v53 offset:176
	ds_read_b128 v[174:177], v57 offset:12240
	v_add_f32_e32 v250, v250, v251
	s_waitcnt lgkmcnt(12)
	v_pk_fma_f32 v[246:247], v[182:183], v[6:7], v[246:247]
	v_pk_fma_f32 v[248:249], v[184:185], v[8:9], v[248:249]
	ds_read_b128 v[178:181], v57 offset:12256
	v_add_f32_e32 v202, v202, v203
	s_waitcnt lgkmcnt(12)
	v_pk_fma_f32 v[246:247], v[186:187], v[10:11], v[246:247]
	v_pk_fma_f32 v[248:249], v[188:189], v[12:13], v[248:249]
	ds_read_b128 v[182:185], v57 offset:12272
	v_lshlrev_b32_e32 v227, 16, v227
	s_waitcnt lgkmcnt(12)
	v_pk_fma_f32 v[246:247], v[190:191], v[14:15], v[246:247]
	v_pk_fma_f32 v[248:249], v[192:193], v[16:17], v[248:249]
	ds_read_b128 v[186:189], v57 offset:12288
	v_add_f32_e32 v250, v250, v202
	s_waitcnt lgkmcnt(12)
	v_pk_fma_f32 v[246:247], v[194:195], v[18:19], v[246:247]
	v_pk_fma_f32 v[248:249], v[196:197], v[20:21], v[248:249]
	ds_read_b128 v[190:193], v57 offset:12304
	v_fma_f32 v93, v226, v227, -v250
	s_waitcnt lgkmcnt(12)
	v_pk_fma_f32 v[246:247], v[198:199], v[22:23], v[246:247]
	v_pk_fma_f32 v[248:249], v[200:201], v[24:25], v[248:249]
	ds_read_b128 v[194:197], v57 offset:12320
	s_waitcnt lgkmcnt(12)
	v_pk_fma_f32 v[246:247], v[206:207], v[26:27], v[246:247]
	v_pk_fma_f32 v[248:249], v[208:209], v[28:29], v[248:249]
	ds_read_b128 v[198:201], v57 offset:12336
	s_waitcnt lgkmcnt(12)
	v_pk_fma_f32 v[246:247], v[210:211], v[30:31], v[246:247]
	v_pk_fma_f32 v[248:249], v[212:213], v[32:33], v[248:249]
	ds_read_b128 v[206:209], v57 offset:12352
	s_waitcnt lgkmcnt(12)
	v_pk_fma_f32 v[246:247], v[214:215], v[34:35], v[246:247]
	v_pk_fma_f32 v[248:249], v[216:217], v[36:37], v[248:249]
	ds_read_b128 v[210:213], v57 offset:12368
	s_waitcnt lgkmcnt(12)
	v_pk_fma_f32 v[246:247], v[238:239], v[86:87], v[246:247]
	v_pk_fma_f32 v[248:249], v[240:241], v[88:89], v[248:249]
	ds_read_b128 v[214:217], v57 offset:12384
	s_waitcnt lgkmcnt(12)
	v_pk_fma_f32 v[246:247], v[242:243], v[90:91], v[246:247]
	v_pk_fma_f32 v[248:249], v[244:245], v[92:93], v[248:249]
	ds_read_b128 v[238:241], v57 offset:12400
	s_waitcnt lgkmcnt(10)
	v_pk_fma_f32 v[250:251], v[174:175], v[2:3], 0 op_sel_hi:[1,1,0]
	v_pk_fma_f32 v[202:203], v[176:177], v[4:5], 0 op_sel_hi:[1,1,0]
	ds_read_b128 v[242:245], v57 offset:12416
	v_mad_u32_u24 v61, v55, 45, v51
	ds_read_u16 v221, v61
	ds_read_b32 v220, v53 offset:180
	v_add_f32_e32 v246, v246, v247
	s_waitcnt lgkmcnt(12)
	v_pk_fma_f32 v[250:251], v[178:179], v[6:7], v[250:251]
	v_pk_fma_f32 v[202:203], v[180:181], v[8:9], v[202:203]
	ds_read_b128 v[174:177], v57 offset:12512
	v_add_f32_e32 v248, v248, v249
	s_waitcnt lgkmcnt(12)
	v_pk_fma_f32 v[250:251], v[182:183], v[10:11], v[250:251]
	v_pk_fma_f32 v[202:203], v[184:185], v[12:13], v[202:203]
	ds_read_b128 v[178:181], v57 offset:12528
	v_lshlrev_b32_e32 v59, 16, v59
	s_waitcnt lgkmcnt(12)
	v_pk_fma_f32 v[250:251], v[186:187], v[14:15], v[250:251]
	v_pk_fma_f32 v[202:203], v[188:189], v[16:17], v[202:203]
	ds_read_b128 v[182:185], v57 offset:12544
	v_add_f32_e32 v246, v246, v248
	s_waitcnt lgkmcnt(12)
	v_pk_fma_f32 v[250:251], v[190:191], v[18:19], v[250:251]
	v_pk_fma_f32 v[202:203], v[192:193], v[20:21], v[202:203]
	ds_read_b128 v[186:189], v57 offset:12560
	v_fma_f32 v94, v204, v59, -v246
	s_waitcnt lgkmcnt(12)
	v_pk_fma_f32 v[250:251], v[194:195], v[22:23], v[250:251]
	v_pk_fma_f32 v[202:203], v[196:197], v[24:25], v[202:203]
	ds_read_b128 v[190:193], v57 offset:12576
	s_waitcnt lgkmcnt(12)
	v_pk_fma_f32 v[250:251], v[198:199], v[26:27], v[250:251]
	v_pk_fma_f32 v[202:203], v[200:201], v[28:29], v[202:203]
	ds_read_b128 v[194:197], v57 offset:12592
	s_waitcnt lgkmcnt(12)
	v_pk_fma_f32 v[250:251], v[206:207], v[30:31], v[250:251]
	v_pk_fma_f32 v[202:203], v[208:209], v[32:33], v[202:203]
	ds_read_b128 v[198:201], v57 offset:12608
	s_waitcnt lgkmcnt(12)
	v_pk_fma_f32 v[250:251], v[210:211], v[34:35], v[250:251]
	v_pk_fma_f32 v[202:203], v[212:213], v[36:37], v[202:203]
	ds_read_b128 v[206:209], v57 offset:12624
	s_waitcnt lgkmcnt(12)
	v_pk_fma_f32 v[250:251], v[214:215], v[86:87], v[250:251]
	v_pk_fma_f32 v[202:203], v[216:217], v[88:89], v[202:203]
	ds_read_b128 v[210:213], v57 offset:12640
	s_waitcnt lgkmcnt(12)
	v_pk_fma_f32 v[250:251], v[238:239], v[90:91], v[250:251]
	v_pk_fma_f32 v[202:203], v[240:241], v[92:93], v[202:203]
	ds_read_b128 v[214:217], v57 offset:12656
	s_waitcnt lgkmcnt(12)
	v_pk_fma_f32 v[250:251], v[242:243], v[94:95], v[250:251]
	v_pk_fma_f32 v[202:203], v[244:245], v[96:97], v[202:203]
	ds_read_b128 v[238:241], v57 offset:12672
	s_waitcnt lgkmcnt(10)
	v_pk_fma_f32 v[246:247], v[174:175], v[2:3], 0 op_sel_hi:[1,1,0]
	v_pk_fma_f32 v[248:249], v[176:177], v[4:5], 0 op_sel_hi:[1,1,0]
	ds_read_b128 v[242:245], v57 offset:12688
	v_mad_u32_u24 v61, v55, 46, v51
	ds_read_u16 v227, v61
	ds_read_b32 v226, v53 offset:184
	v_add_f32_e32 v250, v250, v251
	s_waitcnt lgkmcnt(12)
	v_pk_fma_f32 v[246:247], v[178:179], v[6:7], v[246:247]
	v_pk_fma_f32 v[248:249], v[180:181], v[8:9], v[248:249]
	ds_read_b128 v[174:177], v57 offset:12784
	v_add_f32_e32 v202, v202, v203
	s_waitcnt lgkmcnt(12)
	v_pk_fma_f32 v[246:247], v[182:183], v[10:11], v[246:247]
	v_pk_fma_f32 v[248:249], v[184:185], v[12:13], v[248:249]
	ds_read_b128 v[178:181], v57 offset:12800
	v_lshlrev_b32_e32 v221, 16, v221
	s_waitcnt lgkmcnt(12)
	v_pk_fma_f32 v[246:247], v[186:187], v[14:15], v[246:247]
	v_pk_fma_f32 v[248:249], v[188:189], v[16:17], v[248:249]
	ds_read_b128 v[182:185], v57 offset:12816
	v_add_f32_e32 v250, v250, v202
	s_waitcnt lgkmcnt(12)
	v_pk_fma_f32 v[246:247], v[190:191], v[18:19], v[246:247]
	v_pk_fma_f32 v[248:249], v[192:193], v[20:21], v[248:249]
	ds_read_b128 v[186:189], v57 offset:12832
	v_fma_f32 v95, v220, v221, -v250
	s_waitcnt lgkmcnt(12)
	v_pk_fma_f32 v[246:247], v[194:195], v[22:23], v[246:247]
	v_pk_fma_f32 v[248:249], v[196:197], v[24:25], v[248:249]
	ds_read_b128 v[190:193], v57 offset:12848
	s_waitcnt lgkmcnt(12)
	v_pk_fma_f32 v[246:247], v[198:199], v[26:27], v[246:247]
	v_pk_fma_f32 v[248:249], v[200:201], v[28:29], v[248:249]
	ds_read_b128 v[194:197], v57 offset:12864
	s_waitcnt lgkmcnt(12)
	v_pk_fma_f32 v[246:247], v[206:207], v[30:31], v[246:247]
	v_pk_fma_f32 v[248:249], v[208:209], v[32:33], v[248:249]
	ds_read_b128 v[198:201], v57 offset:12880
	s_waitcnt lgkmcnt(12)
	v_pk_fma_f32 v[246:247], v[210:211], v[34:35], v[246:247]
	v_pk_fma_f32 v[248:249], v[212:213], v[36:37], v[248:249]
	ds_read_b128 v[206:209], v57 offset:12896
	s_waitcnt lgkmcnt(12)
	v_pk_fma_f32 v[246:247], v[214:215], v[86:87], v[246:247]
	v_pk_fma_f32 v[248:249], v[216:217], v[88:89], v[248:249]
	ds_read_b128 v[210:213], v57 offset:12912
	s_waitcnt lgkmcnt(12)
	v_pk_fma_f32 v[246:247], v[238:239], v[90:91], v[246:247]
	v_pk_fma_f32 v[248:249], v[240:241], v[92:93], v[248:249]
	ds_read_b128 v[214:217], v57 offset:12928
	s_waitcnt lgkmcnt(12)
	v_pk_fma_f32 v[246:247], v[242:243], v[94:95], v[246:247]
	v_pk_fma_f32 v[248:249], v[244:245], v[96:97], v[248:249]
	ds_read_b128 v[238:241], v57 offset:12944
	s_waitcnt lgkmcnt(10)
	v_pk_fma_f32 v[250:251], v[174:175], v[2:3], 0 op_sel_hi:[1,1,0]
	v_pk_fma_f32 v[202:203], v[176:177], v[4:5], 0 op_sel_hi:[1,1,0]
	ds_read_b128 v[242:245], v57 offset:12960
	v_mad_u32_u24 v61, v55, 47, v51
	ds_read_u16 v59, v61
	ds_read_b32 v204, v53 offset:188
	v_add_f32_e32 v246, v246, v247
	s_waitcnt lgkmcnt(12)
	v_pk_fma_f32 v[250:251], v[178:179], v[6:7], v[250:251]
	v_pk_fma_f32 v[202:203], v[180:181], v[8:9], v[202:203]
	ds_read_b128 v[174:177], v57 offset:13056
	v_add_f32_e32 v248, v248, v249
	s_waitcnt lgkmcnt(12)
	v_pk_fma_f32 v[250:251], v[182:183], v[10:11], v[250:251]
	v_pk_fma_f32 v[202:203], v[184:185], v[12:13], v[202:203]
	ds_read_b128 v[178:181], v57 offset:13072
	v_lshlrev_b32_e32 v227, 16, v227
	s_waitcnt lgkmcnt(12)
	v_pk_fma_f32 v[250:251], v[186:187], v[14:15], v[250:251]
	v_pk_fma_f32 v[202:203], v[188:189], v[16:17], v[202:203]
	ds_read_b128 v[182:185], v57 offset:13088
	v_add_f32_e32 v246, v246, v248
	s_waitcnt lgkmcnt(12)
	v_pk_fma_f32 v[250:251], v[190:191], v[18:19], v[250:251]
	v_pk_fma_f32 v[202:203], v[192:193], v[20:21], v[202:203]
	ds_read_b128 v[186:189], v57 offset:13104
	v_fma_f32 v96, v226, v227, -v246
	s_waitcnt lgkmcnt(12)
	v_pk_fma_f32 v[250:251], v[194:195], v[22:23], v[250:251]
	v_pk_fma_f32 v[202:203], v[196:197], v[24:25], v[202:203]
	ds_read_b128 v[190:193], v57 offset:13120
	s_waitcnt lgkmcnt(12)
	v_pk_fma_f32 v[250:251], v[198:199], v[26:27], v[250:251]
	v_pk_fma_f32 v[202:203], v[200:201], v[28:29], v[202:203]
	ds_read_b128 v[194:197], v57 offset:13136
	s_waitcnt lgkmcnt(12)
	v_pk_fma_f32 v[250:251], v[206:207], v[30:31], v[250:251]
	v_pk_fma_f32 v[202:203], v[208:209], v[32:33], v[202:203]
	ds_read_b128 v[198:201], v57 offset:13152
	s_waitcnt lgkmcnt(12)
	v_pk_fma_f32 v[250:251], v[210:211], v[34:35], v[250:251]
	v_pk_fma_f32 v[202:203], v[212:213], v[36:37], v[202:203]
	ds_read_b128 v[206:209], v57 offset:13168
	s_waitcnt lgkmcnt(12)
	v_pk_fma_f32 v[250:251], v[214:215], v[86:87], v[250:251]
	v_pk_fma_f32 v[202:203], v[216:217], v[88:89], v[202:203]
	ds_read_b128 v[210:213], v57 offset:13184
	s_waitcnt lgkmcnt(12)
	v_pk_fma_f32 v[250:251], v[238:239], v[90:91], v[250:251]
	v_pk_fma_f32 v[202:203], v[240:241], v[92:93], v[202:203]
	ds_read_b128 v[214:217], v57 offset:13200
	s_waitcnt lgkmcnt(12)
	v_pk_fma_f32 v[250:251], v[242:243], v[94:95], v[250:251]
	v_pk_fma_f32 v[202:203], v[244:245], v[96:97], v[202:203]
	ds_read_b128 v[238:241], v57 offset:13216
	s_waitcnt lgkmcnt(10)
	v_pk_fma_f32 v[246:247], v[174:175], v[2:3], 0 op_sel_hi:[1,1,0]
	v_pk_fma_f32 v[248:249], v[176:177], v[4:5], 0 op_sel_hi:[1,1,0]
	ds_read_b128 v[242:245], v57 offset:13232
	v_mad_u32_u24 v61, v55, 48, v51
	ds_read_u16 v221, v61
	ds_read_b32 v220, v53 offset:192
	v_add_f32_e32 v250, v250, v251
	s_waitcnt lgkmcnt(12)
	v_pk_fma_f32 v[246:247], v[178:179], v[6:7], v[246:247]
	v_pk_fma_f32 v[248:249], v[180:181], v[8:9], v[248:249]
	ds_read_b128 v[174:177], v57 offset:13328
	v_add_f32_e32 v202, v202, v203
	s_waitcnt lgkmcnt(12)
	v_pk_fma_f32 v[246:247], v[182:183], v[10:11], v[246:247]
	v_pk_fma_f32 v[248:249], v[184:185], v[12:13], v[248:249]
	ds_read_b128 v[178:181], v57 offset:13344
	v_lshlrev_b32_e32 v59, 16, v59
	s_waitcnt lgkmcnt(12)
	v_pk_fma_f32 v[246:247], v[186:187], v[14:15], v[246:247]
	v_pk_fma_f32 v[248:249], v[188:189], v[16:17], v[248:249]
	ds_read_b128 v[182:185], v57 offset:13360
	v_add_f32_e32 v250, v250, v202
	s_waitcnt lgkmcnt(12)
	v_pk_fma_f32 v[246:247], v[190:191], v[18:19], v[246:247]
	v_pk_fma_f32 v[248:249], v[192:193], v[20:21], v[248:249]
	ds_read_b128 v[186:189], v57 offset:13376
	v_fma_f32 v97, v204, v59, -v250
	s_waitcnt lgkmcnt(12)
	v_pk_fma_f32 v[246:247], v[194:195], v[22:23], v[246:247]
	v_pk_fma_f32 v[248:249], v[196:197], v[24:25], v[248:249]
	ds_read_b128 v[190:193], v57 offset:13392
	s_waitcnt lgkmcnt(12)
	v_pk_fma_f32 v[246:247], v[198:199], v[26:27], v[246:247]
	v_pk_fma_f32 v[248:249], v[200:201], v[28:29], v[248:249]
	ds_read_b128 v[194:197], v57 offset:13408
	s_waitcnt lgkmcnt(12)
	v_pk_fma_f32 v[246:247], v[206:207], v[30:31], v[246:247]
	v_pk_fma_f32 v[248:249], v[208:209], v[32:33], v[248:249]
	ds_read_b128 v[198:201], v57 offset:13424
	s_waitcnt lgkmcnt(12)
	v_pk_fma_f32 v[246:247], v[210:211], v[34:35], v[246:247]
	v_pk_fma_f32 v[248:249], v[212:213], v[36:37], v[248:249]
	ds_read_b128 v[206:209], v57 offset:13440
	s_waitcnt lgkmcnt(12)
	v_pk_fma_f32 v[246:247], v[214:215], v[86:87], v[246:247]
	v_pk_fma_f32 v[248:249], v[216:217], v[88:89], v[248:249]
	ds_read_b128 v[210:213], v57 offset:13456
	s_waitcnt lgkmcnt(12)
	v_pk_fma_f32 v[246:247], v[238:239], v[90:91], v[246:247]
	v_pk_fma_f32 v[248:249], v[240:241], v[92:93], v[248:249]
	ds_read_b128 v[214:217], v57 offset:13472
	s_waitcnt lgkmcnt(12)
	v_pk_fma_f32 v[246:247], v[242:243], v[94:95], v[246:247]
	v_pk_fma_f32 v[248:249], v[244:245], v[96:97], v[248:249]
	ds_read_b128 v[238:241], v57 offset:13488
	s_waitcnt lgkmcnt(10)
	v_pk_fma_f32 v[250:251], v[174:175], v[2:3], 0 op_sel_hi:[1,1,0]
	v_pk_fma_f32 v[202:203], v[176:177], v[4:5], 0 op_sel_hi:[1,1,0]
	ds_read_b128 v[242:245], v57 offset:13504
	ds_read_b128 v[174:177], v57 offset:13520
	v_add_f32_e32 v246, v246, v247
	s_waitcnt lgkmcnt(11)
	v_pk_fma_f32 v[250:251], v[178:179], v[6:7], v[250:251]
	v_pk_fma_f32 v[202:203], v[180:181], v[8:9], v[202:203]
	v_mad_u32_u24 v61, v55, 49, v51
	ds_read_u16 v227, v61
	ds_read_b32 v226, v53 offset:196
	v_add_f32_e32 v248, v248, v249
	s_waitcnt lgkmcnt(12)
	v_pk_fma_f32 v[250:251], v[182:183], v[10:11], v[250:251]
	v_pk_fma_f32 v[202:203], v[184:185], v[12:13], v[202:203]
	ds_read_b128 v[178:181], v57 offset:13600
	v_lshlrev_b32_e32 v221, 16, v221
	s_waitcnt lgkmcnt(12)
	v_pk_fma_f32 v[250:251], v[186:187], v[14:15], v[250:251]
	v_pk_fma_f32 v[202:203], v[188:189], v[16:17], v[202:203]
	ds_read_b128 v[182:185], v57 offset:13616
	v_add_f32_e32 v246, v246, v248
	s_waitcnt lgkmcnt(12)
	v_pk_fma_f32 v[250:251], v[190:191], v[18:19], v[250:251]
	v_pk_fma_f32 v[202:203], v[192:193], v[20:21], v[202:203]
	ds_read_b128 v[186:189], v57 offset:13632
	v_fma_f32 v98, v220, v221, -v246
	s_waitcnt lgkmcnt(12)
	v_pk_fma_f32 v[250:251], v[194:195], v[22:23], v[250:251]
	v_pk_fma_f32 v[202:203], v[196:197], v[24:25], v[202:203]
	ds_read_b128 v[190:193], v57 offset:13648
	s_waitcnt lgkmcnt(12)
	v_pk_fma_f32 v[250:251], v[198:199], v[26:27], v[250:251]
	v_pk_fma_f32 v[202:203], v[200:201], v[28:29], v[202:203]
	ds_read_b128 v[194:197], v57 offset:13664
	s_waitcnt lgkmcnt(12)
	v_pk_fma_f32 v[250:251], v[206:207], v[30:31], v[250:251]
	v_pk_fma_f32 v[202:203], v[208:209], v[32:33], v[202:203]
	ds_read_b128 v[198:201], v57 offset:13680
	s_waitcnt lgkmcnt(12)
	v_pk_fma_f32 v[250:251], v[210:211], v[34:35], v[250:251]
	v_pk_fma_f32 v[202:203], v[212:213], v[36:37], v[202:203]
	ds_read_b128 v[206:209], v57 offset:13696
	s_waitcnt lgkmcnt(12)
	v_pk_fma_f32 v[250:251], v[214:215], v[86:87], v[250:251]
	v_pk_fma_f32 v[202:203], v[216:217], v[88:89], v[202:203]
	ds_read_b128 v[210:213], v57 offset:13712
	s_waitcnt lgkmcnt(12)
	v_pk_fma_f32 v[250:251], v[238:239], v[90:91], v[250:251]
	v_pk_fma_f32 v[202:203], v[240:241], v[92:93], v[202:203]
	ds_read_b128 v[214:217], v57 offset:13728
	s_waitcnt lgkmcnt(12)
	v_pk_fma_f32 v[250:251], v[242:243], v[94:95], v[250:251]
	v_pk_fma_f32 v[202:203], v[244:245], v[96:97], v[202:203]
	ds_read_b128 v[238:241], v57 offset:13744
	s_waitcnt lgkmcnt(12)
	v_pk_fma_f32 v[250:251], v[174:175], v[98:99], v[250:251]
	v_pk_fma_f32 v[202:203], v[176:177], v[100:101], v[202:203]
	ds_read_b128 v[242:245], v57 offset:13760
	s_waitcnt lgkmcnt(10)
	v_pk_fma_f32 v[246:247], v[178:179], v[2:3], 0 op_sel_hi:[1,1,0]
	v_pk_fma_f32 v[248:249], v[180:181], v[4:5], 0 op_sel_hi:[1,1,0]
	ds_read_b128 v[174:177], v57 offset:13776
	ds_read_b128 v[178:181], v57 offset:13792
	v_add_f32_e32 v250, v250, v251
	s_waitcnt lgkmcnt(11)
	v_pk_fma_f32 v[246:247], v[182:183], v[6:7], v[246:247]
	v_pk_fma_f32 v[248:249], v[184:185], v[8:9], v[248:249]
	v_mad_u32_u24 v61, v55, 50, v51
	ds_read_u16 v59, v61
	ds_read_b32 v204, v53 offset:200
	v_add_f32_e32 v202, v202, v203
	s_waitcnt lgkmcnt(12)
	v_pk_fma_f32 v[246:247], v[186:187], v[10:11], v[246:247]
	v_pk_fma_f32 v[248:249], v[188:189], v[12:13], v[248:249]
	ds_read_b128 v[182:185], v57 offset:13872
	v_lshlrev_b32_e32 v227, 16, v227
	s_waitcnt lgkmcnt(12)
	v_pk_fma_f32 v[246:247], v[190:191], v[14:15], v[246:247]
	v_pk_fma_f32 v[248:249], v[192:193], v[16:17], v[248:249]
	ds_read_b128 v[186:189], v57 offset:13888
	v_add_f32_e32 v250, v250, v202
	s_waitcnt lgkmcnt(12)
	v_pk_fma_f32 v[246:247], v[194:195], v[18:19], v[246:247]
	v_pk_fma_f32 v[248:249], v[196:197], v[20:21], v[248:249]
	ds_read_b128 v[190:193], v57 offset:13904
	v_fma_f32 v99, v226, v227, -v250
	s_waitcnt lgkmcnt(12)
	v_pk_fma_f32 v[246:247], v[198:199], v[22:23], v[246:247]
	v_pk_fma_f32 v[248:249], v[200:201], v[24:25], v[248:249]
	ds_read_b128 v[194:197], v57 offset:13920
	s_waitcnt lgkmcnt(12)
	v_pk_fma_f32 v[246:247], v[206:207], v[26:27], v[246:247]
	v_pk_fma_f32 v[248:249], v[208:209], v[28:29], v[248:249]
	ds_read_b128 v[198:201], v57 offset:13936
	s_waitcnt lgkmcnt(12)
	v_pk_fma_f32 v[246:247], v[210:211], v[30:31], v[246:247]
	v_pk_fma_f32 v[248:249], v[212:213], v[32:33], v[248:249]
	ds_read_b128 v[206:209], v57 offset:13952
	s_waitcnt lgkmcnt(12)
	v_pk_fma_f32 v[246:247], v[214:215], v[34:35], v[246:247]
	v_pk_fma_f32 v[248:249], v[216:217], v[36:37], v[248:249]
	ds_read_b128 v[210:213], v57 offset:13968
	s_waitcnt lgkmcnt(12)
	v_pk_fma_f32 v[246:247], v[238:239], v[86:87], v[246:247]
	v_pk_fma_f32 v[248:249], v[240:241], v[88:89], v[248:249]
	ds_read_b128 v[214:217], v57 offset:13984
	s_waitcnt lgkmcnt(12)
	v_pk_fma_f32 v[246:247], v[242:243], v[90:91], v[246:247]
	v_pk_fma_f32 v[248:249], v[244:245], v[92:93], v[248:249]
	ds_read_b128 v[238:241], v57 offset:14000
	s_waitcnt lgkmcnt(12)
	v_pk_fma_f32 v[246:247], v[174:175], v[94:95], v[246:247]
	v_pk_fma_f32 v[248:249], v[176:177], v[96:97], v[248:249]
	ds_read_b128 v[242:245], v57 offset:14016
	s_waitcnt lgkmcnt(12)
	v_pk_fma_f32 v[246:247], v[178:179], v[98:99], v[246:247]
	v_pk_fma_f32 v[248:249], v[180:181], v[100:101], v[248:249]
	ds_read_b128 v[174:177], v57 offset:14032
	s_waitcnt lgkmcnt(10)
	v_pk_fma_f32 v[250:251], v[182:183], v[2:3], 0 op_sel_hi:[1,1,0]
	v_pk_fma_f32 v[202:203], v[184:185], v[4:5], 0 op_sel_hi:[1,1,0]
	ds_read_b128 v[178:181], v57 offset:14048
	ds_read_b128 v[182:185], v57 offset:14064
	v_add_f32_e32 v246, v246, v247
	s_waitcnt lgkmcnt(11)
	v_pk_fma_f32 v[250:251], v[186:187], v[6:7], v[250:251]
	v_pk_fma_f32 v[202:203], v[188:189], v[8:9], v[202:203]
	v_mad_u32_u24 v61, v55, 51, v51
	ds_read_u16 v221, v61
	ds_read_b32 v220, v53 offset:204
	v_add_f32_e32 v248, v248, v249
	s_waitcnt lgkmcnt(12)
	v_pk_fma_f32 v[250:251], v[190:191], v[10:11], v[250:251]
	v_pk_fma_f32 v[202:203], v[192:193], v[12:13], v[202:203]
	ds_read_b128 v[186:189], v57 offset:14144
	v_lshlrev_b32_e32 v59, 16, v59
	s_waitcnt lgkmcnt(12)
	v_pk_fma_f32 v[250:251], v[194:195], v[14:15], v[250:251]
	v_pk_fma_f32 v[202:203], v[196:197], v[16:17], v[202:203]
	ds_read_b128 v[190:193], v57 offset:14160
	v_add_f32_e32 v246, v246, v248
	s_waitcnt lgkmcnt(12)
	v_pk_fma_f32 v[250:251], v[198:199], v[18:19], v[250:251]
	v_pk_fma_f32 v[202:203], v[200:201], v[20:21], v[202:203]
	ds_read_b128 v[194:197], v57 offset:14176
	v_fma_f32 v100, v204, v59, -v246
	s_waitcnt lgkmcnt(12)
	v_pk_fma_f32 v[250:251], v[206:207], v[22:23], v[250:251]
	v_pk_fma_f32 v[202:203], v[208:209], v[24:25], v[202:203]
	ds_read_b128 v[198:201], v57 offset:14192
	s_waitcnt lgkmcnt(12)
	v_pk_fma_f32 v[250:251], v[210:211], v[26:27], v[250:251]
	v_pk_fma_f32 v[202:203], v[212:213], v[28:29], v[202:203]
	ds_read_b128 v[206:209], v57 offset:14208
	s_waitcnt lgkmcnt(12)
	v_pk_fma_f32 v[250:251], v[214:215], v[30:31], v[250:251]
	v_pk_fma_f32 v[202:203], v[216:217], v[32:33], v[202:203]
	ds_read_b128 v[210:213], v57 offset:14224
	s_waitcnt lgkmcnt(12)
	v_pk_fma_f32 v[250:251], v[238:239], v[34:35], v[250:251]
	v_pk_fma_f32 v[202:203], v[240:241], v[36:37], v[202:203]
	ds_read_b128 v[214:217], v57 offset:14240
	s_waitcnt lgkmcnt(12)
	v_pk_fma_f32 v[250:251], v[242:243], v[86:87], v[250:251]
	v_pk_fma_f32 v[202:203], v[244:245], v[88:89], v[202:203]
	ds_read_b128 v[238:241], v57 offset:14256
	s_waitcnt lgkmcnt(12)
	v_pk_fma_f32 v[250:251], v[174:175], v[90:91], v[250:251]
	v_pk_fma_f32 v[202:203], v[176:177], v[92:93], v[202:203]
	ds_read_b128 v[242:245], v57 offset:14272
	s_waitcnt lgkmcnt(12)
	v_pk_fma_f32 v[250:251], v[178:179], v[94:95], v[250:251]
	v_pk_fma_f32 v[202:203], v[180:181], v[96:97], v[202:203]
	ds_read_b128 v[174:177], v57 offset:14288
	s_waitcnt lgkmcnt(12)
	v_pk_fma_f32 v[250:251], v[182:183], v[98:99], v[250:251]
	v_pk_fma_f32 v[202:203], v[184:185], v[100:101], v[202:203]
	ds_read_b128 v[178:181], v57 offset:14304
	s_waitcnt lgkmcnt(10)
	v_pk_fma_f32 v[246:247], v[186:187], v[2:3], 0 op_sel_hi:[1,1,0]
	v_pk_fma_f32 v[248:249], v[188:189], v[4:5], 0 op_sel_hi:[1,1,0]
	ds_read_b128 v[182:185], v57 offset:14320
	ds_read_b128 v[186:189], v57 offset:14336
	v_add_f32_e32 v250, v250, v251
	s_waitcnt lgkmcnt(11)
	v_pk_fma_f32 v[246:247], v[190:191], v[6:7], v[246:247]
	v_pk_fma_f32 v[248:249], v[192:193], v[8:9], v[248:249]
	v_mad_u32_u24 v61, v55, 52, v51
	ds_read_u16 v227, v61
	ds_read_b32 v226, v53 offset:208
	v_add_f32_e32 v202, v202, v203
	s_waitcnt lgkmcnt(12)
	v_pk_fma_f32 v[246:247], v[194:195], v[10:11], v[246:247]
	v_pk_fma_f32 v[248:249], v[196:197], v[12:13], v[248:249]
	ds_read_b128 v[190:193], v57 offset:14416
	v_lshlrev_b32_e32 v221, 16, v221
	s_waitcnt lgkmcnt(12)
	v_pk_fma_f32 v[246:247], v[198:199], v[14:15], v[246:247]
	v_pk_fma_f32 v[248:249], v[200:201], v[16:17], v[248:249]
	ds_read_b128 v[194:197], v57 offset:14432
	v_add_f32_e32 v250, v250, v202
	s_waitcnt lgkmcnt(12)
	v_pk_fma_f32 v[246:247], v[206:207], v[18:19], v[246:247]
	v_pk_fma_f32 v[248:249], v[208:209], v[20:21], v[248:249]
	ds_read_b128 v[198:201], v57 offset:14448
	v_fma_f32 v101, v220, v221, -v250
	s_waitcnt lgkmcnt(12)
	v_pk_fma_f32 v[246:247], v[210:211], v[22:23], v[246:247]
	v_pk_fma_f32 v[248:249], v[212:213], v[24:25], v[248:249]
	ds_read_b128 v[206:209], v57 offset:14464
	s_waitcnt lgkmcnt(12)
	v_pk_fma_f32 v[246:247], v[214:215], v[26:27], v[246:247]
	v_pk_fma_f32 v[248:249], v[216:217], v[28:29], v[248:249]
	ds_read_b128 v[210:213], v57 offset:14480
	s_waitcnt lgkmcnt(12)
	v_pk_fma_f32 v[246:247], v[238:239], v[30:31], v[246:247]
	v_pk_fma_f32 v[248:249], v[240:241], v[32:33], v[248:249]
	ds_read_b128 v[214:217], v57 offset:14496
	s_waitcnt lgkmcnt(12)
	v_pk_fma_f32 v[246:247], v[242:243], v[34:35], v[246:247]
	v_pk_fma_f32 v[248:249], v[244:245], v[36:37], v[248:249]
	ds_read_b128 v[238:241], v57 offset:14512
	s_waitcnt lgkmcnt(12)
	v_pk_fma_f32 v[246:247], v[174:175], v[86:87], v[246:247]
	v_pk_fma_f32 v[248:249], v[176:177], v[88:89], v[248:249]
	ds_read_b128 v[242:245], v57 offset:14528
	s_waitcnt lgkmcnt(12)
	v_pk_fma_f32 v[246:247], v[178:179], v[90:91], v[246:247]
	v_pk_fma_f32 v[248:249], v[180:181], v[92:93], v[248:249]
	ds_read_b128 v[174:177], v57 offset:14544
	s_waitcnt lgkmcnt(12)
	v_pk_fma_f32 v[246:247], v[182:183], v[94:95], v[246:247]
	v_pk_fma_f32 v[248:249], v[184:185], v[96:97], v[248:249]
	ds_read_b128 v[178:181], v57 offset:14560
	s_waitcnt lgkmcnt(12)
	v_pk_fma_f32 v[246:247], v[186:187], v[98:99], v[246:247]
	v_pk_fma_f32 v[248:249], v[188:189], v[100:101], v[248:249]
	ds_read_b128 v[182:185], v57 offset:14576
	s_waitcnt lgkmcnt(10)
	v_pk_fma_f32 v[250:251], v[190:191], v[2:3], 0 op_sel_hi:[1,1,0]
	v_pk_fma_f32 v[202:203], v[192:193], v[4:5], 0 op_sel_hi:[1,1,0]
	ds_read_b128 v[186:189], v57 offset:14592
	ds_read_b128 v[190:193], v57 offset:14608
	v_add_f32_e32 v246, v246, v247
	s_waitcnt lgkmcnt(11)
	v_pk_fma_f32 v[250:251], v[194:195], v[6:7], v[250:251]
	v_pk_fma_f32 v[202:203], v[196:197], v[8:9], v[202:203]
	ds_read_b128 v[194:197], v57 offset:14624
	v_add_f32_e32 v248, v248, v249
	s_waitcnt lgkmcnt(11)
	v_pk_fma_f32 v[250:251], v[198:199], v[10:11], v[250:251]
	v_pk_fma_f32 v[202:203], v[200:201], v[12:13], v[202:203]
	v_mad_u32_u24 v61, v55, 53, v51
	ds_read_u16 v59, v61
	ds_read_b32 v204, v53 offset:212
	v_lshlrev_b32_e32 v227, 16, v227
	s_waitcnt lgkmcnt(12)
	v_pk_fma_f32 v[250:251], v[206:207], v[14:15], v[250:251]
	v_pk_fma_f32 v[202:203], v[208:209], v[16:17], v[202:203]
	ds_read_b128 v[198:201], v57 offset:14688
	v_add_f32_e32 v246, v246, v248
	s_waitcnt lgkmcnt(12)
	v_pk_fma_f32 v[250:251], v[210:211], v[18:19], v[250:251]
	v_pk_fma_f32 v[202:203], v[212:213], v[20:21], v[202:203]
	ds_read_b128 v[206:209], v57 offset:14704
	v_fma_f32 v102, v226, v227, -v246
	s_waitcnt lgkmcnt(12)
	v_pk_fma_f32 v[250:251], v[214:215], v[22:23], v[250:251]
	v_pk_fma_f32 v[202:203], v[216:217], v[24:25], v[202:203]
	ds_read_b128 v[210:213], v57 offset:14720
	s_waitcnt lgkmcnt(12)
	v_pk_fma_f32 v[250:251], v[238:239], v[26:27], v[250:251]
	v_pk_fma_f32 v[202:203], v[240:241], v[28:29], v[202:203]
	ds_read_b128 v[214:217], v57 offset:14736
	s_waitcnt lgkmcnt(12)
	v_pk_fma_f32 v[250:251], v[242:243], v[30:31], v[250:251]
	v_pk_fma_f32 v[202:203], v[244:245], v[32:33], v[202:203]
	ds_read_b128 v[238:241], v57 offset:14752
	s_waitcnt lgkmcnt(12)
	v_pk_fma_f32 v[250:251], v[174:175], v[34:35], v[250:251]
	v_pk_fma_f32 v[202:203], v[176:177], v[36:37], v[202:203]
	ds_read_b128 v[242:245], v57 offset:14768
	s_waitcnt lgkmcnt(12)
	v_pk_fma_f32 v[250:251], v[178:179], v[86:87], v[250:251]
	v_pk_fma_f32 v[202:203], v[180:181], v[88:89], v[202:203]
	ds_read_b128 v[174:177], v57 offset:14784
	s_waitcnt lgkmcnt(12)
	v_pk_fma_f32 v[250:251], v[182:183], v[90:91], v[250:251]
	v_pk_fma_f32 v[202:203], v[184:185], v[92:93], v[202:203]
	ds_read_b128 v[178:181], v57 offset:14800
	s_waitcnt lgkmcnt(12)
	v_pk_fma_f32 v[250:251], v[186:187], v[94:95], v[250:251]
	v_pk_fma_f32 v[202:203], v[188:189], v[96:97], v[202:203]
	ds_read_b128 v[182:185], v57 offset:14816
	s_waitcnt lgkmcnt(12)
	v_pk_fma_f32 v[250:251], v[190:191], v[98:99], v[250:251]
	v_pk_fma_f32 v[202:203], v[192:193], v[100:101], v[202:203]
	ds_read_b128 v[186:189], v57 offset:14832
	s_waitcnt lgkmcnt(12)
	v_pk_fma_f32 v[250:251], v[194:195], v[102:103], v[250:251]
	v_pk_fma_f32 v[202:203], v[196:197], v[104:105], v[202:203]
	ds_read_b128 v[190:193], v57 offset:14848
	s_waitcnt lgkmcnt(10)
	v_pk_fma_f32 v[246:247], v[198:199], v[2:3], 0 op_sel_hi:[1,1,0]
	v_pk_fma_f32 v[248:249], v[200:201], v[4:5], 0 op_sel_hi:[1,1,0]
	ds_read_b128 v[194:197], v57 offset:14864
	ds_read_b128 v[198:201], v57 offset:14880
	v_add_f32_e32 v250, v250, v251
	s_waitcnt lgkmcnt(11)
	v_pk_fma_f32 v[246:247], v[206:207], v[6:7], v[246:247]
	v_pk_fma_f32 v[248:249], v[208:209], v[8:9], v[248:249]
	ds_read_b128 v[206:209], v57 offset:14896
	v_add_f32_e32 v202, v202, v203
	s_waitcnt lgkmcnt(11)
	v_pk_fma_f32 v[246:247], v[210:211], v[10:11], v[246:247]
	v_pk_fma_f32 v[248:249], v[212:213], v[12:13], v[248:249]
	v_mad_u32_u24 v61, v55, 54, v51
	ds_read_u16 v221, v61
	ds_read_b32 v220, v53 offset:216
	v_lshlrev_b32_e32 v59, 16, v59
	s_waitcnt lgkmcnt(12)
	v_pk_fma_f32 v[246:247], v[214:215], v[14:15], v[246:247]
	v_pk_fma_f32 v[248:249], v[216:217], v[16:17], v[248:249]
	ds_read_b128 v[210:213], v57 offset:14960
	v_add_f32_e32 v250, v250, v202
	s_waitcnt lgkmcnt(12)
	v_pk_fma_f32 v[246:247], v[238:239], v[18:19], v[246:247]
	v_pk_fma_f32 v[248:249], v[240:241], v[20:21], v[248:249]
	ds_read_b128 v[214:217], v57 offset:14976
	v_fma_f32 v103, v204, v59, -v250
	s_waitcnt lgkmcnt(12)
	v_pk_fma_f32 v[246:247], v[242:243], v[22:23], v[246:247]
	v_pk_fma_f32 v[248:249], v[244:245], v[24:25], v[248:249]
	ds_read_b128 v[238:241], v57 offset:14992
	s_waitcnt lgkmcnt(12)
	v_pk_fma_f32 v[246:247], v[174:175], v[26:27], v[246:247]
	v_pk_fma_f32 v[248:249], v[176:177], v[28:29], v[248:249]
	ds_read_b128 v[242:245], v57 offset:15008
	s_waitcnt lgkmcnt(12)
	v_pk_fma_f32 v[246:247], v[178:179], v[30:31], v[246:247]
	v_pk_fma_f32 v[248:249], v[180:181], v[32:33], v[248:249]
	ds_read_b128 v[174:177], v57 offset:15024
	s_waitcnt lgkmcnt(12)
	v_pk_fma_f32 v[246:247], v[182:183], v[34:35], v[246:247]
	v_pk_fma_f32 v[248:249], v[184:185], v[36:37], v[248:249]
	ds_read_b128 v[178:181], v57 offset:15040
	s_waitcnt lgkmcnt(12)
	v_pk_fma_f32 v[246:247], v[186:187], v[86:87], v[246:247]
	v_pk_fma_f32 v[248:249], v[188:189], v[88:89], v[248:249]
	ds_read_b128 v[182:185], v57 offset:15056
	s_waitcnt lgkmcnt(12)
	v_pk_fma_f32 v[246:247], v[190:191], v[90:91], v[246:247]
	v_pk_fma_f32 v[248:249], v[192:193], v[92:93], v[248:249]
	ds_read_b128 v[186:189], v57 offset:15072
	s_waitcnt lgkmcnt(12)
	v_pk_fma_f32 v[246:247], v[194:195], v[94:95], v[246:247]
	v_pk_fma_f32 v[248:249], v[196:197], v[96:97], v[248:249]
	ds_read_b128 v[190:193], v57 offset:15088
	s_waitcnt lgkmcnt(12)
	v_pk_fma_f32 v[246:247], v[198:199], v[98:99], v[246:247]
	v_pk_fma_f32 v[248:249], v[200:201], v[100:101], v[248:249]
	ds_read_b128 v[194:197], v57 offset:15104
	s_waitcnt lgkmcnt(12)
	v_pk_fma_f32 v[246:247], v[206:207], v[102:103], v[246:247]
	v_pk_fma_f32 v[248:249], v[208:209], v[104:105], v[248:249]
	ds_read_b128 v[198:201], v57 offset:15120
	s_waitcnt lgkmcnt(10)
	v_pk_fma_f32 v[250:251], v[210:211], v[2:3], 0 op_sel_hi:[1,1,0]
	v_pk_fma_f32 v[202:203], v[212:213], v[4:5], 0 op_sel_hi:[1,1,0]
	ds_read_b128 v[206:209], v57 offset:15136
	ds_read_b128 v[210:213], v57 offset:15152
	v_add_f32_e32 v246, v246, v247
	s_waitcnt lgkmcnt(11)
	v_pk_fma_f32 v[250:251], v[214:215], v[6:7], v[250:251]
	v_pk_fma_f32 v[202:203], v[216:217], v[8:9], v[202:203]
	ds_read_b128 v[214:217], v57 offset:15168
	v_add_f32_e32 v248, v248, v249
	s_waitcnt lgkmcnt(11)
	v_pk_fma_f32 v[250:251], v[238:239], v[10:11], v[250:251]
	v_pk_fma_f32 v[202:203], v[240:241], v[12:13], v[202:203]
	v_mad_u32_u24 v61, v55, 55, v51
	ds_read_u16 v227, v61
	ds_read_b32 v226, v53 offset:220
	v_lshlrev_b32_e32 v221, 16, v221
	s_waitcnt lgkmcnt(12)
	v_pk_fma_f32 v[250:251], v[242:243], v[14:15], v[250:251]
	v_pk_fma_f32 v[202:203], v[244:245], v[16:17], v[202:203]
	ds_read_b128 v[238:241], v57 offset:15232
	v_add_f32_e32 v246, v246, v248
	s_waitcnt lgkmcnt(12)
	v_pk_fma_f32 v[250:251], v[174:175], v[18:19], v[250:251]
	v_pk_fma_f32 v[202:203], v[176:177], v[20:21], v[202:203]
	ds_read_b128 v[242:245], v57 offset:15248
	v_fma_f32 v104, v220, v221, -v246
	s_waitcnt lgkmcnt(12)
	v_pk_fma_f32 v[250:251], v[178:179], v[22:23], v[250:251]
	v_pk_fma_f32 v[202:203], v[180:181], v[24:25], v[202:203]
	ds_read_b128 v[174:177], v57 offset:15264
	s_waitcnt lgkmcnt(12)
	v_pk_fma_f32 v[250:251], v[182:183], v[26:27], v[250:251]
	v_pk_fma_f32 v[202:203], v[184:185], v[28:29], v[202:203]
	ds_read_b128 v[178:181], v57 offset:15280
	s_waitcnt lgkmcnt(12)
	v_pk_fma_f32 v[250:251], v[186:187], v[30:31], v[250:251]
	v_pk_fma_f32 v[202:203], v[188:189], v[32:33], v[202:203]
	ds_read_b128 v[182:185], v57 offset:15296
	s_waitcnt lgkmcnt(12)
	v_pk_fma_f32 v[250:251], v[190:191], v[34:35], v[250:251]
	v_pk_fma_f32 v[202:203], v[192:193], v[36:37], v[202:203]
	ds_read_b128 v[186:189], v57 offset:15312
	s_waitcnt lgkmcnt(12)
	v_pk_fma_f32 v[250:251], v[194:195], v[86:87], v[250:251]
	v_pk_fma_f32 v[202:203], v[196:197], v[88:89], v[202:203]
	ds_read_b128 v[190:193], v57 offset:15328
	s_waitcnt lgkmcnt(12)
	v_pk_fma_f32 v[250:251], v[198:199], v[90:91], v[250:251]
	v_pk_fma_f32 v[202:203], v[200:201], v[92:93], v[202:203]
	ds_read_b128 v[194:197], v57 offset:15344
	s_waitcnt lgkmcnt(12)
	v_pk_fma_f32 v[250:251], v[206:207], v[94:95], v[250:251]
	v_pk_fma_f32 v[202:203], v[208:209], v[96:97], v[202:203]
	ds_read_b128 v[198:201], v57 offset:15360
	s_waitcnt lgkmcnt(12)
	v_pk_fma_f32 v[250:251], v[210:211], v[98:99], v[250:251]
	v_pk_fma_f32 v[202:203], v[212:213], v[100:101], v[202:203]
	ds_read_b128 v[206:209], v57 offset:15376
	s_waitcnt lgkmcnt(12)
	v_pk_fma_f32 v[250:251], v[214:215], v[102:103], v[250:251]
	v_pk_fma_f32 v[202:203], v[216:217], v[104:105], v[202:203]
	ds_read_b128 v[210:213], v57 offset:15392
	s_waitcnt lgkmcnt(10)
	v_pk_fma_f32 v[246:247], v[238:239], v[2:3], 0 op_sel_hi:[1,1,0]
	v_pk_fma_f32 v[248:249], v[240:241], v[4:5], 0 op_sel_hi:[1,1,0]
	ds_read_b128 v[214:217], v57 offset:15408
	ds_read_b128 v[238:241], v57 offset:15424
	v_add_f32_e32 v250, v250, v251
	s_waitcnt lgkmcnt(11)
	v_pk_fma_f32 v[246:247], v[242:243], v[6:7], v[246:247]
	v_pk_fma_f32 v[248:249], v[244:245], v[8:9], v[248:249]
	ds_read_b128 v[242:245], v57 offset:15440
	v_add_f32_e32 v202, v202, v203
	s_waitcnt lgkmcnt(11)
	v_pk_fma_f32 v[246:247], v[174:175], v[10:11], v[246:247]
	v_pk_fma_f32 v[248:249], v[176:177], v[12:13], v[248:249]
	v_mad_u32_u24 v61, v55, 56, v51
	ds_read_u16 v59, v61
	ds_read_b32 v204, v53 offset:224
	v_lshlrev_b32_e32 v227, 16, v227
	s_waitcnt lgkmcnt(12)
	v_pk_fma_f32 v[246:247], v[178:179], v[14:15], v[246:247]
	v_pk_fma_f32 v[248:249], v[180:181], v[16:17], v[248:249]
	ds_read_b128 v[174:177], v57 offset:15504
	v_add_f32_e32 v250, v250, v202
	s_waitcnt lgkmcnt(12)
	v_pk_fma_f32 v[246:247], v[182:183], v[18:19], v[246:247]
	v_pk_fma_f32 v[248:249], v[184:185], v[20:21], v[248:249]
	ds_read_b128 v[178:181], v57 offset:15520
	v_fma_f32 v105, v226, v227, -v250
	s_waitcnt lgkmcnt(12)
	v_pk_fma_f32 v[246:247], v[186:187], v[22:23], v[246:247]
	v_pk_fma_f32 v[248:249], v[188:189], v[24:25], v[248:249]
	ds_read_b128 v[182:185], v57 offset:15536
	s_waitcnt lgkmcnt(12)
	v_pk_fma_f32 v[246:247], v[190:191], v[26:27], v[246:247]
	v_pk_fma_f32 v[248:249], v[192:193], v[28:29], v[248:249]
	ds_read_b128 v[186:189], v57 offset:15552
	s_waitcnt lgkmcnt(12)
	v_pk_fma_f32 v[246:247], v[194:195], v[30:31], v[246:247]
	v_pk_fma_f32 v[248:249], v[196:197], v[32:33], v[248:249]
	ds_read_b128 v[190:193], v57 offset:15568
	s_waitcnt lgkmcnt(12)
	v_pk_fma_f32 v[246:247], v[198:199], v[34:35], v[246:247]
	v_pk_fma_f32 v[248:249], v[200:201], v[36:37], v[248:249]
	ds_read_b128 v[194:197], v57 offset:15584
	s_waitcnt lgkmcnt(12)
	v_pk_fma_f32 v[246:247], v[206:207], v[86:87], v[246:247]
	v_pk_fma_f32 v[248:249], v[208:209], v[88:89], v[248:249]
	ds_read_b128 v[198:201], v57 offset:15600
	s_waitcnt lgkmcnt(12)
	v_pk_fma_f32 v[246:247], v[210:211], v[90:91], v[246:247]
	v_pk_fma_f32 v[248:249], v[212:213], v[92:93], v[248:249]
	ds_read_b128 v[206:209], v57 offset:15616
	s_waitcnt lgkmcnt(12)
	v_pk_fma_f32 v[246:247], v[214:215], v[94:95], v[246:247]
	v_pk_fma_f32 v[248:249], v[216:217], v[96:97], v[248:249]
	ds_read_b128 v[210:213], v57 offset:15632
	s_waitcnt lgkmcnt(12)
	v_pk_fma_f32 v[246:247], v[238:239], v[98:99], v[246:247]
	v_pk_fma_f32 v[248:249], v[240:241], v[100:101], v[248:249]
	ds_read_b128 v[214:217], v57 offset:15648
	s_waitcnt lgkmcnt(12)
	v_pk_fma_f32 v[246:247], v[242:243], v[102:103], v[246:247]
	v_pk_fma_f32 v[248:249], v[244:245], v[104:105], v[248:249]
	ds_read_b128 v[238:241], v57 offset:15664
	s_waitcnt lgkmcnt(10)
	v_pk_fma_f32 v[250:251], v[174:175], v[2:3], 0 op_sel_hi:[1,1,0]
	v_pk_fma_f32 v[202:203], v[176:177], v[4:5], 0 op_sel_hi:[1,1,0]
	ds_read_b128 v[242:245], v57 offset:15680
	ds_read_b128 v[174:177], v57 offset:15696
	v_add_f32_e32 v246, v246, v247
	s_waitcnt lgkmcnt(11)
	v_pk_fma_f32 v[250:251], v[178:179], v[6:7], v[250:251]
	v_pk_fma_f32 v[202:203], v[180:181], v[8:9], v[202:203]
	ds_read_b128 v[178:181], v57 offset:15712
	v_add_f32_e32 v248, v248, v249
	s_waitcnt lgkmcnt(11)
	v_pk_fma_f32 v[250:251], v[182:183], v[10:11], v[250:251]
	v_pk_fma_f32 v[202:203], v[184:185], v[12:13], v[202:203]
	ds_read_b128 v[182:185], v57 offset:15728
	v_lshlrev_b32_e32 v59, 16, v59
	s_waitcnt lgkmcnt(11)
	v_pk_fma_f32 v[250:251], v[186:187], v[14:15], v[250:251]
	v_pk_fma_f32 v[202:203], v[188:189], v[16:17], v[202:203]
	v_mad_u32_u24 v61, v55, 57, v51
	ds_read_u16 v221, v61
	ds_read_b32 v220, v53 offset:228
	v_add_f32_e32 v246, v246, v248
	s_waitcnt lgkmcnt(12)
	v_pk_fma_f32 v[250:251], v[190:191], v[18:19], v[250:251]
	v_pk_fma_f32 v[202:203], v[192:193], v[20:21], v[202:203]
	ds_read_b128 v[186:189], v57 offset:15776
	v_fma_f32 v106, v204, v59, -v246
	s_waitcnt lgkmcnt(12)
	v_pk_fma_f32 v[250:251], v[194:195], v[22:23], v[250:251]
	v_pk_fma_f32 v[202:203], v[196:197], v[24:25], v[202:203]
	ds_read_b128 v[190:193], v57 offset:15792
	s_waitcnt lgkmcnt(12)
	v_pk_fma_f32 v[250:251], v[198:199], v[26:27], v[250:251]
	v_pk_fma_f32 v[202:203], v[200:201], v[28:29], v[202:203]
	ds_read_b128 v[194:197], v57 offset:15808
	s_waitcnt lgkmcnt(12)
	v_pk_fma_f32 v[250:251], v[206:207], v[30:31], v[250:251]
	v_pk_fma_f32 v[202:203], v[208:209], v[32:33], v[202:203]
	ds_read_b128 v[198:201], v57 offset:15824
	s_waitcnt lgkmcnt(12)
	v_pk_fma_f32 v[250:251], v[210:211], v[34:35], v[250:251]
	v_pk_fma_f32 v[202:203], v[212:213], v[36:37], v[202:203]
	ds_read_b128 v[206:209], v57 offset:15840
	s_waitcnt lgkmcnt(12)
	v_pk_fma_f32 v[250:251], v[214:215], v[86:87], v[250:251]
	v_pk_fma_f32 v[202:203], v[216:217], v[88:89], v[202:203]
	ds_read_b128 v[210:213], v57 offset:15856
	s_waitcnt lgkmcnt(12)
	v_pk_fma_f32 v[250:251], v[238:239], v[90:91], v[250:251]
	v_pk_fma_f32 v[202:203], v[240:241], v[92:93], v[202:203]
	ds_read_b128 v[214:217], v57 offset:15872
	s_waitcnt lgkmcnt(12)
	v_pk_fma_f32 v[250:251], v[242:243], v[94:95], v[250:251]
	v_pk_fma_f32 v[202:203], v[244:245], v[96:97], v[202:203]
	ds_read_b128 v[238:241], v57 offset:15888
	s_waitcnt lgkmcnt(12)
	v_pk_fma_f32 v[250:251], v[174:175], v[98:99], v[250:251]
	v_pk_fma_f32 v[202:203], v[176:177], v[100:101], v[202:203]
	ds_read_b128 v[242:245], v57 offset:15904
	s_waitcnt lgkmcnt(12)
	v_pk_fma_f32 v[250:251], v[178:179], v[102:103], v[250:251]
	v_pk_fma_f32 v[202:203], v[180:181], v[104:105], v[202:203]
	ds_read_b128 v[174:177], v57 offset:15920
	s_waitcnt lgkmcnt(12)
	v_pk_fma_f32 v[250:251], v[182:183], v[106:107], v[250:251]
	v_pk_fma_f32 v[202:203], v[184:185], v[108:109], v[202:203]
	ds_read_b128 v[178:181], v57 offset:15936
	s_waitcnt lgkmcnt(10)
	v_pk_fma_f32 v[246:247], v[186:187], v[2:3], 0 op_sel_hi:[1,1,0]
	v_pk_fma_f32 v[248:249], v[188:189], v[4:5], 0 op_sel_hi:[1,1,0]
	ds_read_b128 v[182:185], v57 offset:15952
	ds_read_b128 v[186:189], v57 offset:15968
	v_add_f32_e32 v250, v250, v251
	s_waitcnt lgkmcnt(11)
	v_pk_fma_f32 v[246:247], v[190:191], v[6:7], v[246:247]
	v_pk_fma_f32 v[248:249], v[192:193], v[8:9], v[248:249]
	ds_read_b128 v[190:193], v57 offset:15984
	v_add_f32_e32 v202, v202, v203
	s_waitcnt lgkmcnt(11)
	v_pk_fma_f32 v[246:247], v[194:195], v[10:11], v[246:247]
	v_pk_fma_f32 v[248:249], v[196:197], v[12:13], v[248:249]
	ds_read_b128 v[194:197], v57 offset:16000
	v_lshlrev_b32_e32 v221, 16, v221
	s_waitcnt lgkmcnt(11)
	v_pk_fma_f32 v[246:247], v[198:199], v[14:15], v[246:247]
	v_pk_fma_f32 v[248:249], v[200:201], v[16:17], v[248:249]
	v_mad_u32_u24 v61, v55, 58, v51
	ds_read_u16 v227, v61
	ds_read_b32 v226, v53 offset:232
	v_add_f32_e32 v250, v250, v202
	s_waitcnt lgkmcnt(12)
	v_pk_fma_f32 v[246:247], v[206:207], v[18:19], v[246:247]
	v_pk_fma_f32 v[248:249], v[208:209], v[20:21], v[248:249]
	ds_read_b128 v[198:201], v57 offset:16048
	v_fma_f32 v107, v220, v221, -v250
	s_waitcnt lgkmcnt(12)
	v_pk_fma_f32 v[246:247], v[210:211], v[22:23], v[246:247]
	v_pk_fma_f32 v[248:249], v[212:213], v[24:25], v[248:249]
	ds_read_b128 v[206:209], v57 offset:16064
	s_waitcnt lgkmcnt(12)
	v_pk_fma_f32 v[246:247], v[214:215], v[26:27], v[246:247]
	v_pk_fma_f32 v[248:249], v[216:217], v[28:29], v[248:249]
	ds_read_b128 v[210:213], v57 offset:16080
	s_waitcnt lgkmcnt(12)
	v_pk_fma_f32 v[246:247], v[238:239], v[30:31], v[246:247]
	v_pk_fma_f32 v[248:249], v[240:241], v[32:33], v[248:249]
	ds_read_b128 v[214:217], v57 offset:16096
	s_waitcnt lgkmcnt(12)
	v_pk_fma_f32 v[246:247], v[242:243], v[34:35], v[246:247]
	v_pk_fma_f32 v[248:249], v[244:245], v[36:37], v[248:249]
	ds_read_b128 v[238:241], v57 offset:16112
	s_waitcnt lgkmcnt(12)
	v_pk_fma_f32 v[246:247], v[174:175], v[86:87], v[246:247]
	v_pk_fma_f32 v[248:249], v[176:177], v[88:89], v[248:249]
	ds_read_b128 v[242:245], v57 offset:16128
	s_waitcnt lgkmcnt(12)
	v_pk_fma_f32 v[246:247], v[178:179], v[90:91], v[246:247]
	v_pk_fma_f32 v[248:249], v[180:181], v[92:93], v[248:249]
	ds_read_b128 v[174:177], v57 offset:16144
	s_waitcnt lgkmcnt(12)
	v_pk_fma_f32 v[246:247], v[182:183], v[94:95], v[246:247]
	v_pk_fma_f32 v[248:249], v[184:185], v[96:97], v[248:249]
	ds_read_b128 v[178:181], v57 offset:16160
	s_waitcnt lgkmcnt(12)
	v_pk_fma_f32 v[246:247], v[186:187], v[98:99], v[246:247]
	v_pk_fma_f32 v[248:249], v[188:189], v[100:101], v[248:249]
	ds_read_b128 v[182:185], v57 offset:16176
	s_waitcnt lgkmcnt(12)
	v_pk_fma_f32 v[246:247], v[190:191], v[102:103], v[246:247]
	v_pk_fma_f32 v[248:249], v[192:193], v[104:105], v[248:249]
	ds_read_b128 v[186:189], v57 offset:16192
	s_waitcnt lgkmcnt(12)
	v_pk_fma_f32 v[246:247], v[194:195], v[106:107], v[246:247]
	v_pk_fma_f32 v[248:249], v[196:197], v[108:109], v[248:249]
	ds_read_b128 v[190:193], v57 offset:16208
	s_waitcnt lgkmcnt(10)
	v_pk_fma_f32 v[250:251], v[198:199], v[2:3], 0 op_sel_hi:[1,1,0]
	v_pk_fma_f32 v[202:203], v[200:201], v[4:5], 0 op_sel_hi:[1,1,0]
	ds_read_b128 v[194:197], v57 offset:16224
	ds_read_b128 v[198:201], v57 offset:16240
	v_add_f32_e32 v246, v246, v247
	s_waitcnt lgkmcnt(11)
	v_pk_fma_f32 v[250:251], v[206:207], v[6:7], v[250:251]
	v_pk_fma_f32 v[202:203], v[208:209], v[8:9], v[202:203]
	ds_read_b128 v[206:209], v57 offset:16256
	v_add_f32_e32 v248, v248, v249
	s_waitcnt lgkmcnt(11)
	v_pk_fma_f32 v[250:251], v[210:211], v[10:11], v[250:251]
	v_pk_fma_f32 v[202:203], v[212:213], v[12:13], v[202:203]
	ds_read_b128 v[210:213], v57 offset:16272
	v_lshlrev_b32_e32 v227, 16, v227
	s_waitcnt lgkmcnt(11)
	v_pk_fma_f32 v[250:251], v[214:215], v[14:15], v[250:251]
	v_pk_fma_f32 v[202:203], v[216:217], v[16:17], v[202:203]
	v_mad_u32_u24 v61, v55, 59, v51
	ds_read_u16 v59, v61
	ds_read_b32 v204, v53 offset:236
	v_add_f32_e32 v246, v246, v248
	s_waitcnt lgkmcnt(12)
	v_pk_fma_f32 v[250:251], v[238:239], v[18:19], v[250:251]
	v_pk_fma_f32 v[202:203], v[240:241], v[20:21], v[202:203]
	ds_read_b128 v[214:217], v57 offset:16320
	v_fma_f32 v108, v226, v227, -v246
	s_waitcnt lgkmcnt(12)
	v_pk_fma_f32 v[250:251], v[242:243], v[22:23], v[250:251]
	v_pk_fma_f32 v[202:203], v[244:245], v[24:25], v[202:203]
	ds_read_b128 v[238:241], v57 offset:16336
	s_waitcnt lgkmcnt(12)
	v_pk_fma_f32 v[250:251], v[174:175], v[26:27], v[250:251]
	v_pk_fma_f32 v[202:203], v[176:177], v[28:29], v[202:203]
	ds_read_b128 v[242:245], v57 offset:16352
	s_waitcnt lgkmcnt(12)
	v_pk_fma_f32 v[250:251], v[178:179], v[30:31], v[250:251]
	v_pk_fma_f32 v[202:203], v[180:181], v[32:33], v[202:203]
	ds_read_b128 v[174:177], v57 offset:16368
	s_waitcnt lgkmcnt(12)
	v_pk_fma_f32 v[250:251], v[182:183], v[34:35], v[250:251]
	v_pk_fma_f32 v[202:203], v[184:185], v[36:37], v[202:203]
	ds_read_b128 v[178:181], v57 offset:16384
	s_waitcnt lgkmcnt(12)
	v_pk_fma_f32 v[250:251], v[186:187], v[86:87], v[250:251]
	v_pk_fma_f32 v[202:203], v[188:189], v[88:89], v[202:203]
	ds_read_b128 v[182:185], v57 offset:16400
	s_waitcnt lgkmcnt(12)
	v_pk_fma_f32 v[250:251], v[190:191], v[90:91], v[250:251]
	v_pk_fma_f32 v[202:203], v[192:193], v[92:93], v[202:203]
	ds_read_b128 v[186:189], v57 offset:16416
	s_waitcnt lgkmcnt(12)
	v_pk_fma_f32 v[250:251], v[194:195], v[94:95], v[250:251]
	v_pk_fma_f32 v[202:203], v[196:197], v[96:97], v[202:203]
	ds_read_b128 v[190:193], v57 offset:16432
	s_waitcnt lgkmcnt(12)
	v_pk_fma_f32 v[250:251], v[198:199], v[98:99], v[250:251]
	v_pk_fma_f32 v[202:203], v[200:201], v[100:101], v[202:203]
	ds_read_b128 v[194:197], v57 offset:16448
	s_waitcnt lgkmcnt(12)
	v_pk_fma_f32 v[250:251], v[206:207], v[102:103], v[250:251]
	v_pk_fma_f32 v[202:203], v[208:209], v[104:105], v[202:203]
	ds_read_b128 v[198:201], v57 offset:16464
	s_waitcnt lgkmcnt(12)
	v_pk_fma_f32 v[250:251], v[210:211], v[106:107], v[250:251]
	v_pk_fma_f32 v[202:203], v[212:213], v[108:109], v[202:203]
	ds_read_b128 v[206:209], v57 offset:16480
	s_waitcnt lgkmcnt(10)
	v_pk_fma_f32 v[246:247], v[214:215], v[2:3], 0 op_sel_hi:[1,1,0]
	v_pk_fma_f32 v[248:249], v[216:217], v[4:5], 0 op_sel_hi:[1,1,0]
	ds_read_b128 v[210:213], v57 offset:16496
	ds_read_b128 v[214:217], v57 offset:16512
	v_add_f32_e32 v250, v250, v251
	s_waitcnt lgkmcnt(11)
	v_pk_fma_f32 v[246:247], v[238:239], v[6:7], v[246:247]
	v_pk_fma_f32 v[248:249], v[240:241], v[8:9], v[248:249]
	ds_read_b128 v[238:241], v57 offset:16528
	v_add_f32_e32 v202, v202, v203
	s_waitcnt lgkmcnt(11)
	v_pk_fma_f32 v[246:247], v[242:243], v[10:11], v[246:247]
	v_pk_fma_f32 v[248:249], v[244:245], v[12:13], v[248:249]
	ds_read_b128 v[242:245], v57 offset:16544
	v_lshlrev_b32_e32 v59, 16, v59
	s_waitcnt lgkmcnt(11)
	v_pk_fma_f32 v[246:247], v[174:175], v[14:15], v[246:247]
	v_pk_fma_f32 v[248:249], v[176:177], v[16:17], v[248:249]
	v_mad_u32_u24 v61, v55, 60, v51
	ds_read_u16 v221, v61
	ds_read_b32 v220, v53 offset:240
	v_add_f32_e32 v250, v250, v202
	s_waitcnt lgkmcnt(12)
	v_pk_fma_f32 v[246:247], v[178:179], v[18:19], v[246:247]
	v_pk_fma_f32 v[248:249], v[180:181], v[20:21], v[248:249]
	ds_read_b128 v[174:177], v57 offset:16592
	v_fma_f32 v109, v204, v59, -v250
	s_waitcnt lgkmcnt(12)
	v_pk_fma_f32 v[246:247], v[182:183], v[22:23], v[246:247]
	v_pk_fma_f32 v[248:249], v[184:185], v[24:25], v[248:249]
	ds_read_b128 v[178:181], v57 offset:16608
	s_waitcnt lgkmcnt(12)
	v_pk_fma_f32 v[246:247], v[186:187], v[26:27], v[246:247]
	v_pk_fma_f32 v[248:249], v[188:189], v[28:29], v[248:249]
	ds_read_b128 v[182:185], v57 offset:16624
	s_waitcnt lgkmcnt(12)
	v_pk_fma_f32 v[246:247], v[190:191], v[30:31], v[246:247]
	v_pk_fma_f32 v[248:249], v[192:193], v[32:33], v[248:249]
	ds_read_b128 v[186:189], v57 offset:16640
	s_waitcnt lgkmcnt(12)
	v_pk_fma_f32 v[246:247], v[194:195], v[34:35], v[246:247]
	v_pk_fma_f32 v[248:249], v[196:197], v[36:37], v[248:249]
	ds_read_b128 v[190:193], v57 offset:16656
	s_waitcnt lgkmcnt(12)
	v_pk_fma_f32 v[246:247], v[198:199], v[86:87], v[246:247]
	v_pk_fma_f32 v[248:249], v[200:201], v[88:89], v[248:249]
	ds_read_b128 v[194:197], v57 offset:16672
	s_waitcnt lgkmcnt(12)
	v_pk_fma_f32 v[246:247], v[206:207], v[90:91], v[246:247]
	v_pk_fma_f32 v[248:249], v[208:209], v[92:93], v[248:249]
	ds_read_b128 v[198:201], v57 offset:16688
	s_waitcnt lgkmcnt(12)
	v_pk_fma_f32 v[246:247], v[210:211], v[94:95], v[246:247]
	v_pk_fma_f32 v[248:249], v[212:213], v[96:97], v[248:249]
	ds_read_b128 v[206:209], v57 offset:16704
	s_waitcnt lgkmcnt(12)
	v_pk_fma_f32 v[246:247], v[214:215], v[98:99], v[246:247]
	v_pk_fma_f32 v[248:249], v[216:217], v[100:101], v[248:249]
	ds_read_b128 v[210:213], v57 offset:16720
	s_waitcnt lgkmcnt(12)
	v_pk_fma_f32 v[246:247], v[238:239], v[102:103], v[246:247]
	v_pk_fma_f32 v[248:249], v[240:241], v[104:105], v[248:249]
	ds_read_b128 v[214:217], v57 offset:16736
	s_waitcnt lgkmcnt(12)
	v_pk_fma_f32 v[246:247], v[242:243], v[106:107], v[246:247]
	v_pk_fma_f32 v[248:249], v[244:245], v[108:109], v[248:249]
	ds_read_b128 v[238:241], v57 offset:16752
	s_waitcnt lgkmcnt(10)
	v_pk_fma_f32 v[250:251], v[174:175], v[2:3], 0 op_sel_hi:[1,1,0]
	v_pk_fma_f32 v[202:203], v[176:177], v[4:5], 0 op_sel_hi:[1,1,0]
	ds_read_b128 v[242:245], v57 offset:16768
	ds_read_b128 v[174:177], v57 offset:16784
	v_add_f32_e32 v246, v246, v247
	s_waitcnt lgkmcnt(11)
	v_pk_fma_f32 v[250:251], v[178:179], v[6:7], v[250:251]
	v_pk_fma_f32 v[202:203], v[180:181], v[8:9], v[202:203]
	ds_read_b128 v[178:181], v57 offset:16800
	v_add_f32_e32 v248, v248, v249
	s_waitcnt lgkmcnt(11)
	v_pk_fma_f32 v[250:251], v[182:183], v[10:11], v[250:251]
	v_pk_fma_f32 v[202:203], v[184:185], v[12:13], v[202:203]
	ds_read_b128 v[182:185], v57 offset:16816
	v_lshlrev_b32_e32 v221, 16, v221
	s_waitcnt lgkmcnt(11)
	v_pk_fma_f32 v[250:251], v[186:187], v[14:15], v[250:251]
	v_pk_fma_f32 v[202:203], v[188:189], v[16:17], v[202:203]
	ds_read_b128 v[186:189], v57 offset:16832
	v_add_f32_e32 v246, v246, v248
	s_waitcnt lgkmcnt(11)
	v_pk_fma_f32 v[250:251], v[190:191], v[18:19], v[250:251]
	v_pk_fma_f32 v[202:203], v[192:193], v[20:21], v[202:203]
	v_mad_u32_u24 v61, v55, 61, v51
	ds_read_u16 v227, v61
	ds_read_b32 v226, v53 offset:244
	v_fma_f32 v110, v220, v221, -v246
	s_waitcnt lgkmcnt(12)
	v_pk_fma_f32 v[250:251], v[194:195], v[22:23], v[250:251]
	v_pk_fma_f32 v[202:203], v[196:197], v[24:25], v[202:203]
	ds_read_b128 v[190:193], v57 offset:16864
	s_waitcnt lgkmcnt(12)
	v_pk_fma_f32 v[250:251], v[198:199], v[26:27], v[250:251]
	v_pk_fma_f32 v[202:203], v[200:201], v[28:29], v[202:203]
	ds_read_b128 v[194:197], v57 offset:16880
	s_waitcnt lgkmcnt(12)
	v_pk_fma_f32 v[250:251], v[206:207], v[30:31], v[250:251]
	v_pk_fma_f32 v[202:203], v[208:209], v[32:33], v[202:203]
	ds_read_b128 v[198:201], v57 offset:16896
	s_waitcnt lgkmcnt(12)
	v_pk_fma_f32 v[250:251], v[210:211], v[34:35], v[250:251]
	v_pk_fma_f32 v[202:203], v[212:213], v[36:37], v[202:203]
	ds_read_b128 v[206:209], v57 offset:16912
	s_waitcnt lgkmcnt(12)
	v_pk_fma_f32 v[250:251], v[214:215], v[86:87], v[250:251]
	v_pk_fma_f32 v[202:203], v[216:217], v[88:89], v[202:203]
	ds_read_b128 v[210:213], v57 offset:16928
	s_waitcnt lgkmcnt(12)
	v_pk_fma_f32 v[250:251], v[238:239], v[90:91], v[250:251]
	v_pk_fma_f32 v[202:203], v[240:241], v[92:93], v[202:203]
	ds_read_b128 v[214:217], v57 offset:16944
	s_waitcnt lgkmcnt(12)
	v_pk_fma_f32 v[250:251], v[242:243], v[94:95], v[250:251]
	v_pk_fma_f32 v[202:203], v[244:245], v[96:97], v[202:203]
	ds_read_b128 v[238:241], v57 offset:16960
	s_waitcnt lgkmcnt(12)
	v_pk_fma_f32 v[250:251], v[174:175], v[98:99], v[250:251]
	v_pk_fma_f32 v[202:203], v[176:177], v[100:101], v[202:203]
	ds_read_b128 v[242:245], v57 offset:16976
	s_waitcnt lgkmcnt(12)
	v_pk_fma_f32 v[250:251], v[178:179], v[102:103], v[250:251]
	v_pk_fma_f32 v[202:203], v[180:181], v[104:105], v[202:203]
	ds_read_b128 v[174:177], v57 offset:16992
	s_waitcnt lgkmcnt(12)
	v_pk_fma_f32 v[250:251], v[182:183], v[106:107], v[250:251]
	v_pk_fma_f32 v[202:203], v[184:185], v[108:109], v[202:203]
	ds_read_b128 v[178:181], v57 offset:17008
	s_waitcnt lgkmcnt(12)
	v_pk_fma_f32 v[250:251], v[186:187], v[110:111], v[250:251]
	v_pk_fma_f32 v[202:203], v[188:189], v[112:113], v[202:203]
	ds_read_b128 v[182:185], v57 offset:17024
	s_waitcnt lgkmcnt(10)
	v_pk_fma_f32 v[246:247], v[190:191], v[2:3], 0 op_sel_hi:[1,1,0]
	v_pk_fma_f32 v[248:249], v[192:193], v[4:5], 0 op_sel_hi:[1,1,0]
	ds_read_b128 v[186:189], v57 offset:17040
	ds_read_b128 v[190:193], v57 offset:17056
	v_add_f32_e32 v250, v250, v251
	s_waitcnt lgkmcnt(11)
	v_pk_fma_f32 v[246:247], v[194:195], v[6:7], v[246:247]
	v_pk_fma_f32 v[248:249], v[196:197], v[8:9], v[248:249]
	ds_read_b128 v[194:197], v57 offset:17072
	v_add_f32_e32 v202, v202, v203
	s_waitcnt lgkmcnt(11)
	v_pk_fma_f32 v[246:247], v[198:199], v[10:11], v[246:247]
	v_pk_fma_f32 v[248:249], v[200:201], v[12:13], v[248:249]
	ds_read_b128 v[198:201], v57 offset:17088
	v_lshlrev_b32_e32 v227, 16, v227
	s_waitcnt lgkmcnt(11)
	v_pk_fma_f32 v[246:247], v[206:207], v[14:15], v[246:247]
	v_pk_fma_f32 v[248:249], v[208:209], v[16:17], v[248:249]
	ds_read_b128 v[206:209], v57 offset:17104
	v_add_f32_e32 v250, v250, v202
	s_waitcnt lgkmcnt(11)
	v_pk_fma_f32 v[246:247], v[210:211], v[18:19], v[246:247]
	v_pk_fma_f32 v[248:249], v[212:213], v[20:21], v[248:249]
	v_mad_u32_u24 v61, v55, 62, v51
	ds_read_u16 v59, v61
	ds_read_b32 v204, v53 offset:248
	v_fma_f32 v111, v226, v227, -v250
	s_waitcnt lgkmcnt(12)
	v_pk_fma_f32 v[246:247], v[214:215], v[22:23], v[246:247]
	v_pk_fma_f32 v[248:249], v[216:217], v[24:25], v[248:249]
	ds_read_b128 v[210:213], v57 offset:17136
	s_waitcnt lgkmcnt(12)
	v_pk_fma_f32 v[246:247], v[238:239], v[26:27], v[246:247]
	v_pk_fma_f32 v[248:249], v[240:241], v[28:29], v[248:249]
	ds_read_b128 v[214:217], v57 offset:17152
	s_waitcnt lgkmcnt(12)
	v_pk_fma_f32 v[246:247], v[242:243], v[30:31], v[246:247]
	v_pk_fma_f32 v[248:249], v[244:245], v[32:33], v[248:249]
	ds_read_b128 v[238:241], v57 offset:17168
	s_waitcnt lgkmcnt(12)
	v_pk_fma_f32 v[246:247], v[174:175], v[34:35], v[246:247]
	v_pk_fma_f32 v[248:249], v[176:177], v[36:37], v[248:249]
	ds_read_b128 v[242:245], v57 offset:17184
	s_waitcnt lgkmcnt(12)
	v_pk_fma_f32 v[246:247], v[178:179], v[86:87], v[246:247]
	v_pk_fma_f32 v[248:249], v[180:181], v[88:89], v[248:249]
	ds_read_b128 v[174:177], v57 offset:17200
	s_waitcnt lgkmcnt(12)
	v_pk_fma_f32 v[246:247], v[182:183], v[90:91], v[246:247]
	v_pk_fma_f32 v[248:249], v[184:185], v[92:93], v[248:249]
	ds_read_b128 v[178:181], v57 offset:17216
	s_waitcnt lgkmcnt(12)
	v_pk_fma_f32 v[246:247], v[186:187], v[94:95], v[246:247]
	v_pk_fma_f32 v[248:249], v[188:189], v[96:97], v[248:249]
	ds_read_b128 v[182:185], v57 offset:17232
	s_waitcnt lgkmcnt(12)
	v_pk_fma_f32 v[246:247], v[190:191], v[98:99], v[246:247]
	v_pk_fma_f32 v[248:249], v[192:193], v[100:101], v[248:249]
	ds_read_b128 v[186:189], v57 offset:17248
	s_waitcnt lgkmcnt(12)
	v_pk_fma_f32 v[246:247], v[194:195], v[102:103], v[246:247]
	v_pk_fma_f32 v[248:249], v[196:197], v[104:105], v[248:249]
	ds_read_b128 v[190:193], v57 offset:17264
	s_waitcnt lgkmcnt(12)
	v_pk_fma_f32 v[246:247], v[198:199], v[106:107], v[246:247]
	v_pk_fma_f32 v[248:249], v[200:201], v[108:109], v[248:249]
	ds_read_b128 v[194:197], v57 offset:17280
	s_waitcnt lgkmcnt(12)
	v_pk_fma_f32 v[246:247], v[206:207], v[110:111], v[246:247]
	v_pk_fma_f32 v[248:249], v[208:209], v[112:113], v[248:249]
	ds_read_b128 v[198:201], v57 offset:17296
	s_waitcnt lgkmcnt(10)
	v_pk_fma_f32 v[250:251], v[210:211], v[2:3], 0 op_sel_hi:[1,1,0]
	v_pk_fma_f32 v[202:203], v[212:213], v[4:5], 0 op_sel_hi:[1,1,0]
	ds_read_b128 v[206:209], v57 offset:17312
	ds_read_b128 v[210:213], v57 offset:17328
	v_add_f32_e32 v246, v246, v247
	s_waitcnt lgkmcnt(11)
	v_pk_fma_f32 v[250:251], v[214:215], v[6:7], v[250:251]
	v_pk_fma_f32 v[202:203], v[216:217], v[8:9], v[202:203]
	ds_read_b128 v[214:217], v57 offset:17344
	v_add_f32_e32 v248, v248, v249
	s_waitcnt lgkmcnt(11)
	v_pk_fma_f32 v[250:251], v[238:239], v[10:11], v[250:251]
	v_pk_fma_f32 v[202:203], v[240:241], v[12:13], v[202:203]
	ds_read_b128 v[238:241], v57 offset:17360
	v_lshlrev_b32_e32 v59, 16, v59
	s_waitcnt lgkmcnt(11)
	v_pk_fma_f32 v[250:251], v[242:243], v[14:15], v[250:251]
	v_pk_fma_f32 v[202:203], v[244:245], v[16:17], v[202:203]
	ds_read_b128 v[242:245], v57 offset:17376
	v_add_f32_e32 v246, v246, v248
	s_waitcnt lgkmcnt(11)
	v_pk_fma_f32 v[250:251], v[174:175], v[18:19], v[250:251]
	v_pk_fma_f32 v[202:203], v[176:177], v[20:21], v[202:203]
	v_mad_u32_u24 v61, v55, 63, v51
	ds_read_u16 v221, v61
	ds_read_b32 v220, v53 offset:252
	v_fma_f32 v112, v204, v59, -v246
	s_waitcnt lgkmcnt(12)
	v_pk_fma_f32 v[250:251], v[178:179], v[22:23], v[250:251]
	v_pk_fma_f32 v[202:203], v[180:181], v[24:25], v[202:203]
	s_waitcnt lgkmcnt(11)
	v_pk_fma_f32 v[250:251], v[182:183], v[26:27], v[250:251]
	v_pk_fma_f32 v[202:203], v[184:185], v[28:29], v[202:203]
	s_waitcnt lgkmcnt(10)
	v_pk_fma_f32 v[250:251], v[186:187], v[30:31], v[250:251]
	v_pk_fma_f32 v[202:203], v[188:189], v[32:33], v[202:203]
	s_waitcnt lgkmcnt(9)
	v_pk_fma_f32 v[250:251], v[190:191], v[34:35], v[250:251]
	v_pk_fma_f32 v[202:203], v[192:193], v[36:37], v[202:203]
	s_waitcnt lgkmcnt(8)
	v_pk_fma_f32 v[250:251], v[194:195], v[86:87], v[250:251]
	v_pk_fma_f32 v[202:203], v[196:197], v[88:89], v[202:203]
	s_waitcnt lgkmcnt(7)
	v_pk_fma_f32 v[250:251], v[198:199], v[90:91], v[250:251]
	v_pk_fma_f32 v[202:203], v[200:201], v[92:93], v[202:203]
	s_waitcnt lgkmcnt(6)
	v_pk_fma_f32 v[250:251], v[206:207], v[94:95], v[250:251]
	v_pk_fma_f32 v[202:203], v[208:209], v[96:97], v[202:203]
	s_waitcnt lgkmcnt(5)
	v_pk_fma_f32 v[250:251], v[210:211], v[98:99], v[250:251]
	v_pk_fma_f32 v[202:203], v[212:213], v[100:101], v[202:203]
	s_waitcnt lgkmcnt(4)
	v_pk_fma_f32 v[250:251], v[214:215], v[102:103], v[250:251]
	v_pk_fma_f32 v[202:203], v[216:217], v[104:105], v[202:203]
	s_waitcnt lgkmcnt(3)
	v_pk_fma_f32 v[250:251], v[238:239], v[106:107], v[250:251]
	v_pk_fma_f32 v[202:203], v[240:241], v[108:109], v[202:203]
	s_waitcnt lgkmcnt(2)
	v_pk_fma_f32 v[250:251], v[242:243], v[110:111], v[250:251]
	v_pk_fma_f32 v[202:203], v[244:245], v[112:113], v[202:203]
	v_add_f32_e32 v250, v250, v251
	v_add_f32_e32 v202, v202, v203
	s_waitcnt lgkmcnt(0)
	v_lshlrev_b32_e32 v221, 16, v221
	v_add_f32_e32 v250, v250, v202
	v_fma_f32 v2, v220, v221, -v250
	s_and_saveexec_b64 s[0:1], vcc
	s_xor_b64 s[0:1], exec, s[0:1]
	s_cbranch_execz .LBB0_194
	v_lshl_add_u32 v47, v47, 1, 0
	v_bfe_u32 v49, v0, 16, 1
	v_add_u32_e32 v47, 0x1d900, v47
	v_add3_u32 v0, v0, v49, s33
	ds_write_b16_d16_hi v47, v0
	v_bfe_u32 v0, v3, 16, 1
	v_add3_u32 v0, v3, v0, s33
	ds_write_b16_d16_hi v47, v0 offset:256
	v_bfe_u32 v0, v4, 16, 1
	v_add3_u32 v0, v4, v0, s33
	ds_write_b16_d16_hi v47, v0 offset:512
	v_bfe_u32 v0, v5, 16, 1
	v_add3_u32 v0, v5, v0, s33
	ds_write_b16_d16_hi v47, v0 offset:768
	v_bfe_u32 v0, v6, 16, 1
	v_add3_u32 v0, v6, v0, s33
	ds_write_b16_d16_hi v47, v0 offset:1024
	v_bfe_u32 v0, v7, 16, 1
	v_add3_u32 v0, v7, v0, s33
	ds_write_b16_d16_hi v47, v0 offset:1280
	v_bfe_u32 v0, v8, 16, 1
	v_add3_u32 v0, v8, v0, s33
	ds_write_b16_d16_hi v47, v0 offset:1536
	v_bfe_u32 v0, v9, 16, 1
	v_add3_u32 v0, v9, v0, s33
	ds_write_b16_d16_hi v47, v0 offset:1792
	v_bfe_u32 v0, v10, 16, 1
	v_add3_u32 v0, v10, v0, s33
	ds_write_b16_d16_hi v47, v0 offset:2048
	v_bfe_u32 v0, v11, 16, 1
	v_add3_u32 v0, v11, v0, s33
	ds_write_b16_d16_hi v47, v0 offset:2304
	v_bfe_u32 v0, v12, 16, 1
	v_add3_u32 v0, v12, v0, s33
	ds_write_b16_d16_hi v47, v0 offset:2560
	v_bfe_u32 v0, v13, 16, 1
	v_add3_u32 v0, v13, v0, s33
	ds_write_b16_d16_hi v47, v0 offset:2816
	v_bfe_u32 v0, v14, 16, 1
	v_add3_u32 v0, v14, v0, s33
	ds_write_b16_d16_hi v47, v0 offset:3072
	v_bfe_u32 v0, v15, 16, 1
	v_add3_u32 v0, v15, v0, s33
	ds_write_b16_d16_hi v47, v0 offset:3328
	v_bfe_u32 v0, v16, 16, 1
	v_add3_u32 v0, v16, v0, s33
	ds_write_b16_d16_hi v47, v0 offset:3584
	v_bfe_u32 v0, v17, 16, 1
	v_add3_u32 v0, v17, v0, s33
	ds_write_b16_d16_hi v47, v0 offset:3840
	v_bfe_u32 v0, v18, 16, 1
	v_add3_u32 v0, v18, v0, s33
	ds_write_b16_d16_hi v47, v0 offset:4096
	v_bfe_u32 v0, v19, 16, 1
	v_add3_u32 v0, v19, v0, s33
	ds_write_b16_d16_hi v47, v0 offset:4352
	v_bfe_u32 v0, v20, 16, 1
	v_add3_u32 v0, v20, v0, s33
	ds_write_b16_d16_hi v47, v0 offset:4608
	v_bfe_u32 v0, v21, 16, 1
	v_add3_u32 v0, v21, v0, s33
	ds_write_b16_d16_hi v47, v0 offset:4864
	v_bfe_u32 v0, v22, 16, 1
	v_add3_u32 v0, v22, v0, s33
	ds_write_b16_d16_hi v47, v0 offset:5120
	v_bfe_u32 v0, v23, 16, 1
	v_add3_u32 v0, v23, v0, s33
	ds_write_b16_d16_hi v47, v0 offset:5376
	v_bfe_u32 v0, v24, 16, 1
	v_add3_u32 v0, v24, v0, s33
	ds_write_b16_d16_hi v47, v0 offset:5632
	v_bfe_u32 v0, v25, 16, 1
	v_add3_u32 v0, v25, v0, s33
	ds_write_b16_d16_hi v47, v0 offset:5888
	v_bfe_u32 v0, v26, 16, 1
	v_add3_u32 v0, v26, v0, s33
	ds_write_b16_d16_hi v47, v0 offset:6144
	v_bfe_u32 v0, v27, 16, 1
	v_add3_u32 v0, v27, v0, s33
	ds_write_b16_d16_hi v47, v0 offset:6400
	v_bfe_u32 v0, v28, 16, 1
	v_add3_u32 v0, v28, v0, s33
	ds_write_b16_d16_hi v47, v0 offset:6656
	v_bfe_u32 v0, v29, 16, 1
	v_add3_u32 v0, v29, v0, s33
	ds_write_b16_d16_hi v47, v0 offset:6912
	v_bfe_u32 v0, v30, 16, 1
	v_add3_u32 v0, v30, v0, s33
	ds_write_b16_d16_hi v47, v0 offset:7168
	v_bfe_u32 v0, v31, 16, 1
	v_add3_u32 v0, v31, v0, s33
	ds_write_b16_d16_hi v47, v0 offset:7424
	v_bfe_u32 v0, v32, 16, 1
	v_add3_u32 v0, v32, v0, s33
	ds_write_b16_d16_hi v47, v0 offset:7680
	v_bfe_u32 v0, v33, 16, 1
	v_add3_u32 v0, v33, v0, s33
	ds_write_b16_d16_hi v47, v0 offset:7936
	v_bfe_u32 v0, v34, 16, 1
	v_add3_u32 v0, v34, v0, s33
	ds_write_b16_d16_hi v47, v0 offset:8192
	v_bfe_u32 v0, v35, 16, 1
	v_add3_u32 v0, v35, v0, s33
	ds_write_b16_d16_hi v47, v0 offset:8448
	v_bfe_u32 v0, v36, 16, 1
	v_add3_u32 v0, v36, v0, s33
	ds_write_b16_d16_hi v47, v0 offset:8704
	v_bfe_u32 v0, v37, 16, 1
	v_add3_u32 v0, v37, v0, s33
	ds_write_b16_d16_hi v47, v0 offset:8960
	v_bfe_u32 v0, v86, 16, 1
	v_add3_u32 v0, v86, v0, s33
	ds_write_b16_d16_hi v47, v0 offset:9216
	v_bfe_u32 v0, v87, 16, 1
	v_add3_u32 v0, v87, v0, s33
	ds_write_b16_d16_hi v47, v0 offset:9472
	v_bfe_u32 v0, v88, 16, 1
	v_add3_u32 v0, v88, v0, s33
	ds_write_b16_d16_hi v47, v0 offset:9728
	v_bfe_u32 v0, v89, 16, 1
	v_add3_u32 v0, v89, v0, s33
	ds_write_b16_d16_hi v47, v0 offset:9984
	v_bfe_u32 v0, v90, 16, 1
	v_add3_u32 v0, v90, v0, s33
	ds_write_b16_d16_hi v47, v0 offset:10240
	v_bfe_u32 v0, v91, 16, 1
	v_add3_u32 v0, v91, v0, s33
	ds_write_b16_d16_hi v47, v0 offset:10496
	v_bfe_u32 v0, v92, 16, 1
	v_add3_u32 v0, v92, v0, s33
	ds_write_b16_d16_hi v47, v0 offset:10752
	v_bfe_u32 v0, v93, 16, 1
	v_add3_u32 v0, v93, v0, s33
	ds_write_b16_d16_hi v47, v0 offset:11008
	v_bfe_u32 v0, v94, 16, 1
	v_add3_u32 v0, v94, v0, s33
	ds_write_b16_d16_hi v47, v0 offset:11264
	v_bfe_u32 v0, v95, 16, 1
	v_add3_u32 v0, v95, v0, s33
	ds_write_b16_d16_hi v47, v0 offset:11520
	v_bfe_u32 v0, v96, 16, 1
	v_add3_u32 v0, v96, v0, s33
	ds_write_b16_d16_hi v47, v0 offset:11776
	v_bfe_u32 v0, v97, 16, 1
	v_add3_u32 v0, v97, v0, s33
	ds_write_b16_d16_hi v47, v0 offset:12032
	v_bfe_u32 v0, v98, 16, 1
	v_add3_u32 v0, v98, v0, s33
	ds_write_b16_d16_hi v47, v0 offset:12288
	v_bfe_u32 v0, v99, 16, 1
	v_add3_u32 v0, v99, v0, s33
	ds_write_b16_d16_hi v47, v0 offset:12544
	v_bfe_u32 v0, v100, 16, 1
	v_add3_u32 v0, v100, v0, s33
	ds_write_b16_d16_hi v47, v0 offset:12800
	v_bfe_u32 v0, v101, 16, 1
	v_add3_u32 v0, v101, v0, s33
	ds_write_b16_d16_hi v47, v0 offset:13056
	v_bfe_u32 v0, v102, 16, 1
	v_add3_u32 v0, v102, v0, s33
	ds_write_b16_d16_hi v47, v0 offset:13312
	v_bfe_u32 v0, v103, 16, 1
	v_add3_u32 v0, v103, v0, s33
	ds_write_b16_d16_hi v47, v0 offset:13568
	v_bfe_u32 v0, v104, 16, 1
	v_add3_u32 v0, v104, v0, s33
	ds_write_b16_d16_hi v47, v0 offset:13824
	v_bfe_u32 v0, v105, 16, 1
	v_add3_u32 v0, v105, v0, s33
	ds_write_b16_d16_hi v47, v0 offset:14080
	v_bfe_u32 v0, v106, 16, 1
	v_add3_u32 v0, v106, v0, s33
	ds_write_b16_d16_hi v47, v0 offset:14336
	v_bfe_u32 v0, v107, 16, 1
	v_add3_u32 v0, v107, v0, s33
	ds_write_b16_d16_hi v47, v0 offset:14592
	v_bfe_u32 v0, v108, 16, 1
	v_add3_u32 v0, v108, v0, s33
	ds_write_b16_d16_hi v47, v0 offset:14848
	v_bfe_u32 v0, v109, 16, 1
	v_add3_u32 v0, v109, v0, s33
	ds_write_b16_d16_hi v47, v0 offset:15104
	v_bfe_u32 v0, v110, 16, 1
	v_add3_u32 v0, v110, v0, s33
	ds_write_b16_d16_hi v47, v0 offset:15360
	v_bfe_u32 v0, v111, 16, 1
	v_add3_u32 v0, v111, v0, s33
	ds_write_b16_d16_hi v47, v0 offset:15616
	v_bfe_u32 v0, v112, 16, 1
	v_add3_u32 v0, v112, v0, s33
	ds_write_b16_d16_hi v47, v0 offset:15872
	v_bfe_u32 v0, v2, 16, 1
	v_add3_u32 v0, v2, v0, s33
	ds_write_b16_d16_hi v47, v0 offset:16128
